# GEMM k-loop head: LDS read addresses and m0 set before the barrier, first A/B fragments read first with per-MFMA counted waits
# speedup vs baseline: 1.0163x; 1.0047x over previous
; template <int OFF> DEVI bf16x8 ldsr(unsigned a) { bf16x8 v; asm volatile("ds_read_b128 %0, %1 offset:%2" : "=v"(v) : "v"(a), "n"(OFF)); return v; }
; template <int EPI, int NB>
; DEVI void gemm_tile(const GemmJob& J, int m0, int n0, unsigned char* smem) {
;     ...
; #pragma clang loop unroll(disable)
;   for (int kt = 0; kt < nk; ++kt) {
;     if (nk - 1 - kt >= S - 2) {
;       if constexpr (NB == 8) asm volatile("s_waitcnt vmcnt(6)" ::: "memory");
;       else                   asm volatile("s_waitcnt vmcnt(8)" ::: "memory");
;     } else {
;       asm volatile("s_waitcnt vmcnt(0)" ::: "memory");
;     }
;     RAW_BARRIER();
;     if (kt + S - 1 < nk) GEMM_ISSUE(kt + S - 1, is);
;     is = (is + 1 == S) ? 0 : is + 1;
;     const unsigned cur = lbase + cs * STG;
;     cs = (cs + 1 == S) ? 0 : cs + 1;
;     bf16x8 af[4], bfr[NB];
;     const unsigned aa = cur + aofs, ba = cur + bofs;
;     af[0] = ldsr<0>(aa); af[1] = ldsr<1024>(aa); af[2] = ldsr<2048>(aa); af[3] = ldsr<3072>(aa);
;     bfr[0] = ldsr<0>(ba); bfr[1] = ldsr<1024>(ba); bfr[2] = ldsr<2048>(ba); bfr[3] = ldsr<3072>(ba);
;     __builtin_amdgcn_s_setprio(1);
; #pragma unroll
;     for (int nb = 0; nb < NB; ++nb) {
;       if (nb == 0) asm volatile("s_waitcnt lgkmcnt(3)" : "+v"(af[0]), "+v"(af[1]), "+v"(af[2]), "+v"(af[3]), "+v"(bfr[0]) :: "memory");
;       else if (nb <= NB - 4) asm volatile("s_waitcnt lgkmcnt(3)" : "+v"(bfr[nb]) :: "memory");
;       else if (nb == NB - 3) asm volatile("s_waitcnt lgkmcnt(2)" : "+v"(bfr[nb]) :: "memory");
;       else if (nb == NB - 2) asm volatile("s_waitcnt lgkmcnt(1)" : "+v"(bfr[nb]) :: "memory");
;       else asm volatile("s_waitcnt lgkmcnt(0)" : "+v"(bfr[nb]) :: "memory");
;       __builtin_amdgcn_sched_barrier(0);
; #pragma unroll
;       for (int mb = 0; mb < 4; ++mb) {
;         if constexpr (SWAP) acc[mb][nb] = __builtin_amdgcn_mfma_f32_16x16x32_bf16(bfr[nb], af[mb], acc[mb][nb], 0, 0, 0);
;         else                acc[mb][nb] = __builtin_amdgcn_mfma_f32_16x16x32_bf16(af[mb], bfr[nb], acc[mb][nb], 0, 0, 0);
;       }
;       if constexpr (NB == 8) {
;         __builtin_amdgcn_sched_barrier(0);
;         if (nb == 0) bfr[4] = ldsr<4096>(ba);
;         if (nb == 1) bfr[5] = ldsr<5120>(ba);
;         if (nb == 2) bfr[6] = ldsr<6144>(ba);
;         if (nb == 3) bfr[7] = ldsr<7168>(ba);
;       }
;     }
;     __builtin_amdgcn_s_setprio(0);
;   }
.LBB0_154:
	s_mul_i32 s1, s43, 0x6000
	v_add_u32_e32 v213, s1, v210
	v_add_u32_e32 v246, s1, v212
	s_mul_i32 m0, s42, 0x6000
	s_add_u32 m0, m0, s0
	s_cmp_gt_u32 s20, 30
	s_cbranch_scc1 .Lgk0_w0
	s_waitcnt vmcnt(6)
.Lgk0_bar:
	s_waitcnt lgkmcnt(0)
	s_barrier
	s_setprio 1
	ds_read_b128 v[214:217], v213 offset:0
	ds_read_b128 v[230:233], v246 offset:0
	ds_read_b128 v[218:221], v213 offset:0x400
	ds_read_b128 v[222:225], v213 offset:0x800
	ds_read_b128 v[226:229], v213 offset:0xc00
	ds_read_b128 v[234:237], v246 offset:0x400
	ds_read_b128 v[238:241], v246 offset:0x800
	ds_read_b128 v[242:245], v246 offset:0xc00
	s_cmp_gt_u32 s20, 29
	s_cbranch_scc1 .Lgk0_tail
	s_waitcnt lgkmcnt(6)
	v_mfma_f32_16x16x32_bf16 v[122:125], v[230:233], v[214:217], v[122:125]
	s_waitcnt lgkmcnt(5)
	v_mfma_f32_16x16x32_bf16 v[90:93], v[230:233], v[218:221], v[90:93]
	s_waitcnt lgkmcnt(4)
	v_mfma_f32_16x16x32_bf16 v[58:61], v[230:233], v[222:225], v[58:61]
	s_waitcnt lgkmcnt(3)
	v_mfma_f32_16x16x32_bf16 v[26:29], v[230:233], v[226:229], v[26:29]
	ds_read_b128 v[230:233], v246 offset:0x1000
	global_load_lds_dwordx4 v184, s[100:101]
	s_add_u32 m0, m0, 0x1000
	s_waitcnt lgkmcnt(3)
	v_mfma_f32_16x16x32_bf16 v[114:117], v[234:237], v[214:217], v[114:117]
	v_mfma_f32_16x16x32_bf16 v[82:85], v[234:237], v[218:221], v[82:85]
	v_mfma_f32_16x16x32_bf16 v[50:53], v[234:237], v[222:225], v[50:53]
	v_mfma_f32_16x16x32_bf16 v[18:21], v[234:237], v[226:229], v[18:21]
	ds_read_b128 v[234:237], v246 offset:0x1400
	global_load_lds_dwordx4 v185, s[100:101]
	s_add_u32 m0, m0, 0x1000
	s_waitcnt lgkmcnt(3)
	v_mfma_f32_16x16x32_bf16 v[126:129], v[238:241], v[214:217], v[126:129]
	v_mfma_f32_16x16x32_bf16 v[94:97], v[238:241], v[218:221], v[94:97]
	v_mfma_f32_16x16x32_bf16 v[62:65], v[238:241], v[222:225], v[62:65]
	v_mfma_f32_16x16x32_bf16 v[30:33], v[238:241], v[226:229], v[30:33]
	ds_read_b128 v[238:241], v246 offset:0x1800
	global_load_lds_dwordx4 v182, vcc
	s_add_u32 m0, m0, 0x1000
	s_waitcnt lgkmcnt(3)
	v_mfma_f32_16x16x32_bf16 v[118:121], v[242:245], v[214:217], v[118:121]
	v_mfma_f32_16x16x32_bf16 v[86:89], v[242:245], v[218:221], v[86:89]
	v_mfma_f32_16x16x32_bf16 v[54:57], v[242:245], v[222:225], v[54:57]
	v_mfma_f32_16x16x32_bf16 v[22:25], v[242:245], v[226:229], v[22:25]
	ds_read_b128 v[242:245], v246 offset:0x1c00
	global_load_lds_dwordx4 v183, vcc
	s_add_u32 m0, m0, 0x1000
	s_waitcnt lgkmcnt(3)
	v_mfma_f32_16x16x32_bf16 v[106:109], v[230:233], v[214:217], v[106:109]
	v_mfma_f32_16x16x32_bf16 v[74:77], v[230:233], v[218:221], v[74:77]
	v_mfma_f32_16x16x32_bf16 v[42:45], v[230:233], v[222:225], v[42:45]
	v_mfma_f32_16x16x32_bf16 v[10:13], v[230:233], v[226:229], v[10:13]
	global_load_lds_dwordx4 v253, vcc
	s_add_u32 m0, m0, 0x1000
	s_waitcnt lgkmcnt(2)
	v_mfma_f32_16x16x32_bf16 v[98:101], v[234:237], v[214:217], v[98:101]
	v_mfma_f32_16x16x32_bf16 v[66:69], v[234:237], v[218:221], v[66:69]
	v_mfma_f32_16x16x32_bf16 v[34:37], v[234:237], v[222:225], v[34:37]
	v_mfma_f32_16x16x32_bf16 v[2:5], v[234:237], v[226:229], v[2:5]
	global_load_lds_dwordx4 v254, vcc
	s_waitcnt lgkmcnt(1)
	v_mfma_f32_16x16x32_bf16 v[110:113], v[238:241], v[214:217], v[110:113]
	v_mfma_f32_16x16x32_bf16 v[78:81], v[238:241], v[218:221], v[78:81]
	v_mfma_f32_16x16x32_bf16 v[46:49], v[238:241], v[222:225], v[46:49]
	v_mfma_f32_16x16x32_bf16 v[14:17], v[238:241], v[226:229], v[14:17]
	s_waitcnt lgkmcnt(0)
	v_mfma_f32_16x16x32_bf16 v[102:105], v[242:245], v[214:217], v[102:105]
	v_mfma_f32_16x16x32_bf16 v[70:73], v[242:245], v[218:221], v[70:73]
	v_mfma_f32_16x16x32_bf16 v[38:41], v[242:245], v[222:225], v[38:41]
	v_mfma_f32_16x16x32_bf16 v[6:9], v[242:245], v[226:229], v[6:9]
	s_add_u32 s100, s100, s94
	s_addc_u32 s101, s101, s95
	s_add_u32 vcc_lo, vcc_lo, s50
	s_addc_u32 vcc_hi, vcc_hi, s51
	s_add_i32 s42, s42, 1
	s_cmp_lg_u32 s42, 3
	s_cselect_b32 s42, s42, 0
	s_add_i32 s43, s43, 1
	s_cmp_lg_u32 s43, 3
	s_cselect_b32 s43, s43, 0
	s_setprio 0
	s_add_i32 s20, s20, 1
	s_branch .LBB0_154
.Lgk0_tail:
	s_waitcnt lgkmcnt(6)
	v_mfma_f32_16x16x32_bf16 v[122:125], v[230:233], v[214:217], v[122:125]
	s_waitcnt lgkmcnt(5)
	v_mfma_f32_16x16x32_bf16 v[90:93], v[230:233], v[218:221], v[90:93]
	s_waitcnt lgkmcnt(4)
	v_mfma_f32_16x16x32_bf16 v[58:61], v[230:233], v[222:225], v[58:61]
	s_waitcnt lgkmcnt(3)
	v_mfma_f32_16x16x32_bf16 v[26:29], v[230:233], v[226:229], v[26:29]
	ds_read_b128 v[230:233], v246 offset:0x1000
	s_waitcnt lgkmcnt(3)
	v_mfma_f32_16x16x32_bf16 v[114:117], v[234:237], v[214:217], v[114:117]
	v_mfma_f32_16x16x32_bf16 v[82:85], v[234:237], v[218:221], v[82:85]
	v_mfma_f32_16x16x32_bf16 v[50:53], v[234:237], v[222:225], v[50:53]
	v_mfma_f32_16x16x32_bf16 v[18:21], v[234:237], v[226:229], v[18:21]
	ds_read_b128 v[234:237], v246 offset:0x1400
	s_waitcnt lgkmcnt(3)
	v_mfma_f32_16x16x32_bf16 v[126:129], v[238:241], v[214:217], v[126:129]
	v_mfma_f32_16x16x32_bf16 v[94:97], v[238:241], v[218:221], v[94:97]
	v_mfma_f32_16x16x32_bf16 v[62:65], v[238:241], v[222:225], v[62:65]
	v_mfma_f32_16x16x32_bf16 v[30:33], v[238:241], v[226:229], v[30:33]
	ds_read_b128 v[238:241], v246 offset:0x1800
	s_waitcnt lgkmcnt(3)
	v_mfma_f32_16x16x32_bf16 v[118:121], v[242:245], v[214:217], v[118:121]
	v_mfma_f32_16x16x32_bf16 v[86:89], v[242:245], v[218:221], v[86:89]
	v_mfma_f32_16x16x32_bf16 v[54:57], v[242:245], v[222:225], v[54:57]
	v_mfma_f32_16x16x32_bf16 v[22:25], v[242:245], v[226:229], v[22:25]
	ds_read_b128 v[242:245], v246 offset:0x1c00
	s_waitcnt lgkmcnt(3)
	v_mfma_f32_16x16x32_bf16 v[106:109], v[230:233], v[214:217], v[106:109]
	v_mfma_f32_16x16x32_bf16 v[74:77], v[230:233], v[218:221], v[74:77]
	v_mfma_f32_16x16x32_bf16 v[42:45], v[230:233], v[222:225], v[42:45]
	v_mfma_f32_16x16x32_bf16 v[10:13], v[230:233], v[226:229], v[10:13]
	s_waitcnt lgkmcnt(2)
	v_mfma_f32_16x16x32_bf16 v[98:101], v[234:237], v[214:217], v[98:101]
	v_mfma_f32_16x16x32_bf16 v[66:69], v[234:237], v[218:221], v[66:69]
	v_mfma_f32_16x16x32_bf16 v[34:37], v[234:237], v[222:225], v[34:37]
	v_mfma_f32_16x16x32_bf16 v[2:5], v[234:237], v[226:229], v[2:5]
	s_waitcnt lgkmcnt(1)
	v_mfma_f32_16x16x32_bf16 v[110:113], v[238:241], v[214:217], v[110:113]
	v_mfma_f32_16x16x32_bf16 v[78:81], v[238:241], v[218:221], v[78:81]
	v_mfma_f32_16x16x32_bf16 v[46:49], v[238:241], v[222:225], v[46:49]
	v_mfma_f32_16x16x32_bf16 v[14:17], v[238:241], v[226:229], v[14:17]
	s_waitcnt lgkmcnt(0)
	v_mfma_f32_16x16x32_bf16 v[102:105], v[242:245], v[214:217], v[102:105]
	v_mfma_f32_16x16x32_bf16 v[70:73], v[242:245], v[218:221], v[70:73]
	v_mfma_f32_16x16x32_bf16 v[38:41], v[242:245], v[222:225], v[38:41]
	v_mfma_f32_16x16x32_bf16 v[6:9], v[242:245], v[226:229], v[6:9]
	s_add_i32 s42, s42, 1
	s_cmp_lg_u32 s42, 3
	s_cselect_b32 s42, s42, 0
	s_add_i32 s43, s43, 1
	s_cmp_lg_u32 s43, 3
	s_cselect_b32 s43, s43, 0
	s_setprio 0
	s_add_i32 s20, s20, 1
	s_cmp_lg_u32 s20, 32
	s_cbranch_scc1 .LBB0_154
	s_branch .LBB0_151

; template <int OFF> DEVI bf16x8 ldsr(unsigned a) { bf16x8 v; asm volatile("ds_read_b128 %0, %1 offset:%2" : "=v"(v) : "v"(a), "n"(OFF)); return v; }
; template <int EPI, int NB>
; DEVI void gemm_tile(const GemmJob& J, int m0, int n0, unsigned char* smem) {
;     ...
; #pragma clang loop unroll(disable)
;   for (int kt = 0; kt < nk; ++kt) {
;     if (nk - 1 - kt >= S - 2) {
;       if constexpr (NB == 8) asm volatile("s_waitcnt vmcnt(6)" ::: "memory");
;       else                   asm volatile("s_waitcnt vmcnt(8)" ::: "memory");
;     } else {
;       asm volatile("s_waitcnt vmcnt(0)" ::: "memory");
;     }
;     RAW_BARRIER();
;     if (kt + S - 1 < nk) GEMM_ISSUE(kt + S - 1, is);
;     is = (is + 1 == S) ? 0 : is + 1;
;     const unsigned cur = lbase + cs * STG;
;     cs = (cs + 1 == S) ? 0 : cs + 1;
;     bf16x8 af[4], bfr[NB];
;     const unsigned aa = cur + aofs, ba = cur + bofs;
;     af[0] = ldsr<0>(aa); af[1] = ldsr<1024>(aa); af[2] = ldsr<2048>(aa); af[3] = ldsr<3072>(aa);
;     bfr[0] = ldsr<0>(ba); bfr[1] = ldsr<1024>(ba); bfr[2] = ldsr<2048>(ba); bfr[3] = ldsr<3072>(ba);
;     __builtin_amdgcn_s_setprio(1);
; #pragma unroll
;     for (int nb = 0; nb < NB; ++nb) {
;       if (nb == 0) asm volatile("s_waitcnt lgkmcnt(3)" : "+v"(af[0]), "+v"(af[1]), "+v"(af[2]), "+v"(af[3]), "+v"(bfr[0]) :: "memory");
;       else if (nb <= NB - 4) asm volatile("s_waitcnt lgkmcnt(3)" : "+v"(bfr[nb]) :: "memory");
;       else if (nb == NB - 3) asm volatile("s_waitcnt lgkmcnt(2)" : "+v"(bfr[nb]) :: "memory");
;       else if (nb == NB - 2) asm volatile("s_waitcnt lgkmcnt(1)" : "+v"(bfr[nb]) :: "memory");
;       else asm volatile("s_waitcnt lgkmcnt(0)" : "+v"(bfr[nb]) :: "memory");
;       __builtin_amdgcn_sched_barrier(0);
; #pragma unroll
;       for (int mb = 0; mb < 4; ++mb) {
;         if constexpr (SWAP) acc[mb][nb] = __builtin_amdgcn_mfma_f32_16x16x32_bf16(bfr[nb], af[mb], acc[mb][nb], 0, 0, 0);
;         else                acc[mb][nb] = __builtin_amdgcn_mfma_f32_16x16x32_bf16(af[mb], bfr[nb], acc[mb][nb], 0, 0, 0);
;       }
;       if constexpr (NB == 8) {
;         __builtin_amdgcn_sched_barrier(0);
;         if (nb == 0) bfr[4] = ldsr<4096>(ba);
;         if (nb == 1) bfr[5] = ldsr<5120>(ba);
;         if (nb == 2) bfr[6] = ldsr<6144>(ba);
;         if (nb == 3) bfr[7] = ldsr<7168>(ba);
;       }
;     }
;     __builtin_amdgcn_s_setprio(0);
;   }
.LBB0_167:
	s_mul_i32 s1, s43, 0x6000
	v_add_u32_e32 v213, s1, v210
	v_add_u32_e32 v246, s1, v212
	s_mul_i32 m0, s42, 0x6000
	s_add_u32 m0, m0, s0
	s_cmp_gt_u32 s8, 30
	s_cbranch_scc1 .Lgk1_w0
	s_waitcnt vmcnt(6)
.Lgk1_bar:
	s_waitcnt lgkmcnt(0)
	s_barrier
	s_setprio 1
	ds_read_b128 v[214:217], v213 offset:0
	ds_read_b128 v[230:233], v246 offset:0
	ds_read_b128 v[218:221], v213 offset:0x400
	ds_read_b128 v[222:225], v213 offset:0x800
	ds_read_b128 v[226:229], v213 offset:0xc00
	ds_read_b128 v[234:237], v246 offset:0x400
	ds_read_b128 v[238:241], v246 offset:0x800
	ds_read_b128 v[242:245], v246 offset:0xc00
	s_cmp_gt_u32 s8, 29
	s_cbranch_scc1 .Lgk1_tail
	s_waitcnt lgkmcnt(6)
	v_mfma_f32_16x16x32_bf16 v[122:125], v[230:233], v[214:217], v[122:125]
	s_waitcnt lgkmcnt(5)
	v_mfma_f32_16x16x32_bf16 v[90:93], v[230:233], v[218:221], v[90:93]
	s_waitcnt lgkmcnt(4)
	v_mfma_f32_16x16x32_bf16 v[58:61], v[230:233], v[222:225], v[58:61]
	s_waitcnt lgkmcnt(3)
	v_mfma_f32_16x16x32_bf16 v[26:29], v[230:233], v[226:229], v[26:29]
	ds_read_b128 v[230:233], v246 offset:0x1000
	global_load_lds_dwordx4 v184, s[100:101]
	s_add_u32 m0, m0, 0x1000
	s_waitcnt lgkmcnt(3)
	v_mfma_f32_16x16x32_bf16 v[114:117], v[234:237], v[214:217], v[114:117]
	v_mfma_f32_16x16x32_bf16 v[82:85], v[234:237], v[218:221], v[82:85]
	v_mfma_f32_16x16x32_bf16 v[50:53], v[234:237], v[222:225], v[50:53]
	v_mfma_f32_16x16x32_bf16 v[18:21], v[234:237], v[226:229], v[18:21]
	ds_read_b128 v[234:237], v246 offset:0x1400
	global_load_lds_dwordx4 v185, s[100:101]
	s_add_u32 m0, m0, 0x1000
	s_waitcnt lgkmcnt(3)
	v_mfma_f32_16x16x32_bf16 v[126:129], v[238:241], v[214:217], v[126:129]
	v_mfma_f32_16x16x32_bf16 v[94:97], v[238:241], v[218:221], v[94:97]
	v_mfma_f32_16x16x32_bf16 v[62:65], v[238:241], v[222:225], v[62:65]
	v_mfma_f32_16x16x32_bf16 v[30:33], v[238:241], v[226:229], v[30:33]
	ds_read_b128 v[238:241], v246 offset:0x1800
	global_load_lds_dwordx4 v182, vcc
	s_add_u32 m0, m0, 0x1000
	s_waitcnt lgkmcnt(3)
	v_mfma_f32_16x16x32_bf16 v[118:121], v[242:245], v[214:217], v[118:121]
	v_mfma_f32_16x16x32_bf16 v[86:89], v[242:245], v[218:221], v[86:89]
	v_mfma_f32_16x16x32_bf16 v[54:57], v[242:245], v[222:225], v[54:57]
	v_mfma_f32_16x16x32_bf16 v[22:25], v[242:245], v[226:229], v[22:25]
	ds_read_b128 v[242:245], v246 offset:0x1c00
	global_load_lds_dwordx4 v183, vcc
	s_add_u32 m0, m0, 0x1000
	s_waitcnt lgkmcnt(3)
	v_mfma_f32_16x16x32_bf16 v[106:109], v[230:233], v[214:217], v[106:109]
	v_mfma_f32_16x16x32_bf16 v[74:77], v[230:233], v[218:221], v[74:77]
	v_mfma_f32_16x16x32_bf16 v[42:45], v[230:233], v[222:225], v[42:45]
	v_mfma_f32_16x16x32_bf16 v[10:13], v[230:233], v[226:229], v[10:13]
	global_load_lds_dwordx4 v253, vcc
	s_add_u32 m0, m0, 0x1000
	s_waitcnt lgkmcnt(2)
	v_mfma_f32_16x16x32_bf16 v[98:101], v[234:237], v[214:217], v[98:101]
	v_mfma_f32_16x16x32_bf16 v[66:69], v[234:237], v[218:221], v[66:69]
	v_mfma_f32_16x16x32_bf16 v[34:37], v[234:237], v[222:225], v[34:37]
	v_mfma_f32_16x16x32_bf16 v[2:5], v[234:237], v[226:229], v[2:5]
	global_load_lds_dwordx4 v254, vcc
	s_waitcnt lgkmcnt(1)
	v_mfma_f32_16x16x32_bf16 v[110:113], v[238:241], v[214:217], v[110:113]
	v_mfma_f32_16x16x32_bf16 v[78:81], v[238:241], v[218:221], v[78:81]
	v_mfma_f32_16x16x32_bf16 v[46:49], v[238:241], v[222:225], v[46:49]
	v_mfma_f32_16x16x32_bf16 v[14:17], v[238:241], v[226:229], v[14:17]
	s_waitcnt lgkmcnt(0)
	v_mfma_f32_16x16x32_bf16 v[102:105], v[242:245], v[214:217], v[102:105]
	v_mfma_f32_16x16x32_bf16 v[70:73], v[242:245], v[218:221], v[70:73]
	v_mfma_f32_16x16x32_bf16 v[38:41], v[242:245], v[222:225], v[38:41]
	v_mfma_f32_16x16x32_bf16 v[6:9], v[242:245], v[226:229], v[6:9]
	s_add_u32 s100, s100, s94
	s_addc_u32 s101, s101, s95
	s_add_u32 vcc_lo, vcc_lo, s50
	s_addc_u32 vcc_hi, vcc_hi, s51
	s_add_i32 s42, s42, 1
	s_cmp_lg_u32 s42, 3
	s_cselect_b32 s42, s42, 0
	s_add_i32 s43, s43, 1
	s_cmp_lg_u32 s43, 3
	s_cselect_b32 s43, s43, 0
	s_setprio 0
	s_add_i32 s8, s8, 1
	s_branch .LBB0_167
.Lgk1_tail:
	s_waitcnt lgkmcnt(6)
	v_mfma_f32_16x16x32_bf16 v[122:125], v[230:233], v[214:217], v[122:125]
	s_waitcnt lgkmcnt(5)
	v_mfma_f32_16x16x32_bf16 v[90:93], v[230:233], v[218:221], v[90:93]
	s_waitcnt lgkmcnt(4)
	v_mfma_f32_16x16x32_bf16 v[58:61], v[230:233], v[222:225], v[58:61]
	s_waitcnt lgkmcnt(3)
	v_mfma_f32_16x16x32_bf16 v[26:29], v[230:233], v[226:229], v[26:29]
	ds_read_b128 v[230:233], v246 offset:0x1000
	s_waitcnt lgkmcnt(3)
	v_mfma_f32_16x16x32_bf16 v[114:117], v[234:237], v[214:217], v[114:117]
	v_mfma_f32_16x16x32_bf16 v[82:85], v[234:237], v[218:221], v[82:85]
	v_mfma_f32_16x16x32_bf16 v[50:53], v[234:237], v[222:225], v[50:53]
	v_mfma_f32_16x16x32_bf16 v[18:21], v[234:237], v[226:229], v[18:21]
	ds_read_b128 v[234:237], v246 offset:0x1400
	s_waitcnt lgkmcnt(3)
	v_mfma_f32_16x16x32_bf16 v[126:129], v[238:241], v[214:217], v[126:129]
	v_mfma_f32_16x16x32_bf16 v[94:97], v[238:241], v[218:221], v[94:97]
	v_mfma_f32_16x16x32_bf16 v[62:65], v[238:241], v[222:225], v[62:65]
	v_mfma_f32_16x16x32_bf16 v[30:33], v[238:241], v[226:229], v[30:33]
	ds_read_b128 v[238:241], v246 offset:0x1800
	s_waitcnt lgkmcnt(3)
	v_mfma_f32_16x16x32_bf16 v[118:121], v[242:245], v[214:217], v[118:121]
	v_mfma_f32_16x16x32_bf16 v[86:89], v[242:245], v[218:221], v[86:89]
	v_mfma_f32_16x16x32_bf16 v[54:57], v[242:245], v[222:225], v[54:57]
	v_mfma_f32_16x16x32_bf16 v[22:25], v[242:245], v[226:229], v[22:25]
	ds_read_b128 v[242:245], v246 offset:0x1c00
	s_waitcnt lgkmcnt(3)
	v_mfma_f32_16x16x32_bf16 v[106:109], v[230:233], v[214:217], v[106:109]
	v_mfma_f32_16x16x32_bf16 v[74:77], v[230:233], v[218:221], v[74:77]
	v_mfma_f32_16x16x32_bf16 v[42:45], v[230:233], v[222:225], v[42:45]
	v_mfma_f32_16x16x32_bf16 v[10:13], v[230:233], v[226:229], v[10:13]
	s_waitcnt lgkmcnt(2)
	v_mfma_f32_16x16x32_bf16 v[98:101], v[234:237], v[214:217], v[98:101]
	v_mfma_f32_16x16x32_bf16 v[66:69], v[234:237], v[218:221], v[66:69]
	v_mfma_f32_16x16x32_bf16 v[34:37], v[234:237], v[222:225], v[34:37]
	v_mfma_f32_16x16x32_bf16 v[2:5], v[234:237], v[226:229], v[2:5]
	s_waitcnt lgkmcnt(1)
	v_mfma_f32_16x16x32_bf16 v[110:113], v[238:241], v[214:217], v[110:113]
	v_mfma_f32_16x16x32_bf16 v[78:81], v[238:241], v[218:221], v[78:81]
	v_mfma_f32_16x16x32_bf16 v[46:49], v[238:241], v[222:225], v[46:49]
	v_mfma_f32_16x16x32_bf16 v[14:17], v[238:241], v[226:229], v[14:17]
	s_waitcnt lgkmcnt(0)
	v_mfma_f32_16x16x32_bf16 v[102:105], v[242:245], v[214:217], v[102:105]
	v_mfma_f32_16x16x32_bf16 v[70:73], v[242:245], v[218:221], v[70:73]
	v_mfma_f32_16x16x32_bf16 v[38:41], v[242:245], v[222:225], v[38:41]
	v_mfma_f32_16x16x32_bf16 v[6:9], v[242:245], v[226:229], v[6:9]
	s_add_i32 s42, s42, 1
	s_cmp_lg_u32 s42, 3
	s_cselect_b32 s42, s42, 0
	s_add_i32 s43, s43, 1
	s_cmp_lg_u32 s43, 3
	s_cselect_b32 s43, s43, 0
	s_setprio 0
	s_add_i32 s8, s8, 1
	s_cmp_lg_u32 s8, 32
	s_cbranch_scc1 .LBB0_167
	s_branch .LBB0_164

; template <int OFF> DEVI bf16x8 ldsr(unsigned a) { bf16x8 v; asm volatile("ds_read_b128 %0, %1 offset:%2" : "=v"(v) : "v"(a), "n"(OFF)); return v; }
; #define RAW_BARRIER() do { asm volatile("s_waitcnt lgkmcnt(0)" ::: "memory"); __builtin_amdgcn_s_barrier(); } while (0)
; template <int EPI, int NB>
; DEVI void gemm_tile(const GemmJob& J, int m0, int n0, unsigned char* smem) {
;     ...
;   for (int kt = 0; kt < nk; ++kt) {
;     if (nk - 1 - kt >= S - 2) {
;       if constexpr (NB == 8) asm volatile("s_waitcnt vmcnt(6)" ::: "memory");
;       else                   asm volatile("s_waitcnt vmcnt(8)" ::: "memory");
;     } else {
;       asm volatile("s_waitcnt vmcnt(0)" ::: "memory");
;     }
;     RAW_BARRIER();
;     if (kt + S - 1 < nk) GEMM_ISSUE(kt + S - 1, is);
;     is = (is + 1 == S) ? 0 : is + 1;
;     const unsigned cur = lbase + cs * STG;
;     cs = (cs + 1 == S) ? 0 : cs + 1;
;     bf16x8 af[4], bfr[NB];
;     const unsigned aa = cur + aofs, ba = cur + bofs;
;     af[0] = ldsr<0>(aa); af[1] = ldsr<1024>(aa); af[2] = ldsr<2048>(aa); af[3] = ldsr<3072>(aa);
;     bfr[0] = ldsr<0>(ba); bfr[1] = ldsr<1024>(ba); bfr[2] = ldsr<2048>(ba); bfr[3] = ldsr<3072>(ba);
;     __builtin_amdgcn_s_setprio(1);
; #pragma unroll
;     for (int nb = 0; nb < NB; ++nb) {
;       if (nb == 0) asm volatile("s_waitcnt lgkmcnt(3)" : "+v"(af[0]), "+v"(af[1]), "+v"(af[2]), "+v"(af[3]), "+v"(bfr[0]) :: "memory");
;       else if (nb <= NB - 4) asm volatile("s_waitcnt lgkmcnt(3)" : "+v"(bfr[nb]) :: "memory");
;       else if (nb == NB - 3) asm volatile("s_waitcnt lgkmcnt(2)" : "+v"(bfr[nb]) :: "memory");
;       else if (nb == NB - 2) asm volatile("s_waitcnt lgkmcnt(1)" : "+v"(bfr[nb]) :: "memory");
;       else asm volatile("s_waitcnt lgkmcnt(0)" : "+v"(bfr[nb]) :: "memory");
;       __builtin_amdgcn_sched_barrier(0);
; #pragma unroll
;       for (int mb = 0; mb < 4; ++mb) {
;         if constexpr (SWAP) acc[mb][nb] = __builtin_amdgcn_mfma_f32_16x16x32_bf16(bfr[nb], af[mb], acc[mb][nb], 0, 0, 0);
;         else                acc[mb][nb] = __builtin_amdgcn_mfma_f32_16x16x32_bf16(af[mb], bfr[nb], acc[mb][nb], 0, 0, 0);
;       }
.LBB0_231:
	s_mul_i32 s1, s43, 0x6000
	v_add_u32_e32 v215, s1, v213
	v_add_u32_e32 v248, s1, v214
	s_mul_i32 m0, s42, 0x6000
	s_add_u32 m0, m0, s0
	s_cmp_gt_u32 s20, 86
	s_cbranch_scc1 .Lgk2_w0
	s_waitcnt vmcnt(6)
.Lgk2_bar:
	s_waitcnt lgkmcnt(0)
	s_barrier
	s_setprio 1
	ds_read_b128 v[216:219], v215 offset:0
	ds_read_b128 v[232:235], v248 offset:0
	ds_read_b128 v[220:223], v215 offset:0x400
	ds_read_b128 v[224:227], v215 offset:0x800
	ds_read_b128 v[228:231], v215 offset:0xc00
	ds_read_b128 v[236:239], v248 offset:0x400
	ds_read_b128 v[240:243], v248 offset:0x800
	ds_read_b128 v[244:247], v248 offset:0xc00
	s_cmp_gt_u32 s20, 85
	s_cbranch_scc1 .Lgk2_tail
	s_waitcnt lgkmcnt(6)
	v_mfma_f32_16x16x32_bf16 v[126:129], v[232:235], v[216:219], v[126:129]
	s_waitcnt lgkmcnt(5)
	v_mfma_f32_16x16x32_bf16 v[94:97], v[232:235], v[220:223], v[94:97]
	s_waitcnt lgkmcnt(4)
	v_mfma_f32_16x16x32_bf16 v[62:65], v[232:235], v[224:227], v[62:65]
	s_waitcnt lgkmcnt(3)
	v_mfma_f32_16x16x32_bf16 v[30:33], v[232:235], v[228:231], v[30:33]
	ds_read_b128 v[232:235], v248 offset:0x1000
	global_load_lds_dwordx4 v186, s[100:101]
	s_add_u32 m0, m0, 0x1000
	s_waitcnt lgkmcnt(3)
	v_mfma_f32_16x16x32_bf16 v[122:125], v[236:239], v[216:219], v[122:125]
	v_mfma_f32_16x16x32_bf16 v[90:93], v[236:239], v[220:223], v[90:93]
	v_mfma_f32_16x16x32_bf16 v[58:61], v[236:239], v[224:227], v[58:61]
	v_mfma_f32_16x16x32_bf16 v[26:29], v[236:239], v[228:231], v[26:29]
	ds_read_b128 v[236:239], v248 offset:0x1400
	global_load_lds_dwordx4 v187, s[100:101]
	s_add_u32 m0, m0, 0x1000
	s_waitcnt lgkmcnt(3)
	v_mfma_f32_16x16x32_bf16 v[118:121], v[240:243], v[216:219], v[118:121]
	v_mfma_f32_16x16x32_bf16 v[86:89], v[240:243], v[220:223], v[86:89]
	v_mfma_f32_16x16x32_bf16 v[54:57], v[240:243], v[224:227], v[54:57]
	v_mfma_f32_16x16x32_bf16 v[22:25], v[240:243], v[228:231], v[22:25]
	ds_read_b128 v[240:243], v248 offset:0x1800
	global_load_lds_dwordx4 v184, vcc
	s_add_u32 m0, m0, 0x1000
	s_waitcnt lgkmcnt(3)
	v_mfma_f32_16x16x32_bf16 v[114:117], v[244:247], v[216:219], v[114:117]
	v_mfma_f32_16x16x32_bf16 v[82:85], v[244:247], v[220:223], v[82:85]
	v_mfma_f32_16x16x32_bf16 v[50:53], v[244:247], v[224:227], v[50:53]
	v_mfma_f32_16x16x32_bf16 v[18:21], v[244:247], v[228:231], v[18:21]
	ds_read_b128 v[244:247], v248 offset:0x1c00
	global_load_lds_dwordx4 v185, vcc
	s_add_u32 m0, m0, 0x1000
	s_waitcnt lgkmcnt(3)
	v_mfma_f32_16x16x32_bf16 v[110:113], v[232:235], v[216:219], v[110:113]
	v_mfma_f32_16x16x32_bf16 v[78:81], v[232:235], v[220:223], v[78:81]
	v_mfma_f32_16x16x32_bf16 v[46:49], v[232:235], v[224:227], v[46:49]
	v_mfma_f32_16x16x32_bf16 v[14:17], v[232:235], v[228:231], v[14:17]
	global_load_lds_dwordx4 v253, vcc
	s_add_u32 m0, m0, 0x1000
	s_waitcnt lgkmcnt(2)
	v_mfma_f32_16x16x32_bf16 v[106:109], v[236:239], v[216:219], v[106:109]
	v_mfma_f32_16x16x32_bf16 v[74:77], v[236:239], v[220:223], v[74:77]
	v_mfma_f32_16x16x32_bf16 v[42:45], v[236:239], v[224:227], v[42:45]
	v_mfma_f32_16x16x32_bf16 v[10:13], v[236:239], v[228:231], v[10:13]
	global_load_lds_dwordx4 v254, vcc
	s_waitcnt lgkmcnt(1)
	v_mfma_f32_16x16x32_bf16 v[102:105], v[240:243], v[216:219], v[102:105]
	v_mfma_f32_16x16x32_bf16 v[70:73], v[240:243], v[220:223], v[70:73]
	v_mfma_f32_16x16x32_bf16 v[38:41], v[240:243], v[224:227], v[38:41]
	v_mfma_f32_16x16x32_bf16 v[6:9], v[240:243], v[228:231], v[6:9]
	s_waitcnt lgkmcnt(0)
	v_mfma_f32_16x16x32_bf16 v[98:101], v[244:247], v[216:219], v[98:101]
	v_mfma_f32_16x16x32_bf16 v[66:69], v[244:247], v[220:223], v[66:69]
	v_mfma_f32_16x16x32_bf16 v[34:37], v[244:247], v[224:227], v[34:37]
	v_mfma_f32_16x16x32_bf16 v[2:5], v[244:247], v[228:231], v[2:5]
	s_add_u32 s100, s100, s94
	s_addc_u32 s101, s101, s95
	s_add_u32 vcc_lo, vcc_lo, s22
	s_addc_u32 vcc_hi, vcc_hi, s23
	s_add_i32 s42, s42, 1
	s_cmp_lg_u32 s42, 3
	s_cselect_b32 s42, s42, 0
	s_add_i32 s43, s43, 1
	s_cmp_lg_u32 s43, 3
	s_cselect_b32 s43, s43, 0
	s_setprio 0
	s_add_i32 s20, s20, 1
	s_branch .LBB0_231
.Lgk2_tail:
	s_waitcnt lgkmcnt(6)
	v_mfma_f32_16x16x32_bf16 v[126:129], v[232:235], v[216:219], v[126:129]
	s_waitcnt lgkmcnt(5)
	v_mfma_f32_16x16x32_bf16 v[94:97], v[232:235], v[220:223], v[94:97]
	s_waitcnt lgkmcnt(4)
	v_mfma_f32_16x16x32_bf16 v[62:65], v[232:235], v[224:227], v[62:65]
	s_waitcnt lgkmcnt(3)
	v_mfma_f32_16x16x32_bf16 v[30:33], v[232:235], v[228:231], v[30:33]
	ds_read_b128 v[232:235], v248 offset:0x1000
	s_waitcnt lgkmcnt(3)
	v_mfma_f32_16x16x32_bf16 v[122:125], v[236:239], v[216:219], v[122:125]
	v_mfma_f32_16x16x32_bf16 v[90:93], v[236:239], v[220:223], v[90:93]
	v_mfma_f32_16x16x32_bf16 v[58:61], v[236:239], v[224:227], v[58:61]
	v_mfma_f32_16x16x32_bf16 v[26:29], v[236:239], v[228:231], v[26:29]
	ds_read_b128 v[236:239], v248 offset:0x1400
	s_waitcnt lgkmcnt(3)
	v_mfma_f32_16x16x32_bf16 v[118:121], v[240:243], v[216:219], v[118:121]
	v_mfma_f32_16x16x32_bf16 v[86:89], v[240:243], v[220:223], v[86:89]
	v_mfma_f32_16x16x32_bf16 v[54:57], v[240:243], v[224:227], v[54:57]
	v_mfma_f32_16x16x32_bf16 v[22:25], v[240:243], v[228:231], v[22:25]
	ds_read_b128 v[240:243], v248 offset:0x1800
	s_waitcnt lgkmcnt(3)
	v_mfma_f32_16x16x32_bf16 v[114:117], v[244:247], v[216:219], v[114:117]
	v_mfma_f32_16x16x32_bf16 v[82:85], v[244:247], v[220:223], v[82:85]
	v_mfma_f32_16x16x32_bf16 v[50:53], v[244:247], v[224:227], v[50:53]
	v_mfma_f32_16x16x32_bf16 v[18:21], v[244:247], v[228:231], v[18:21]
	ds_read_b128 v[244:247], v248 offset:0x1c00
	s_waitcnt lgkmcnt(3)
	v_mfma_f32_16x16x32_bf16 v[110:113], v[232:235], v[216:219], v[110:113]
	v_mfma_f32_16x16x32_bf16 v[78:81], v[232:235], v[220:223], v[78:81]
	v_mfma_f32_16x16x32_bf16 v[46:49], v[232:235], v[224:227], v[46:49]
	v_mfma_f32_16x16x32_bf16 v[14:17], v[232:235], v[228:231], v[14:17]
	s_waitcnt lgkmcnt(2)
	v_mfma_f32_16x16x32_bf16 v[106:109], v[236:239], v[216:219], v[106:109]
	v_mfma_f32_16x16x32_bf16 v[74:77], v[236:239], v[220:223], v[74:77]
	v_mfma_f32_16x16x32_bf16 v[42:45], v[236:239], v[224:227], v[42:45]
	v_mfma_f32_16x16x32_bf16 v[10:13], v[236:239], v[228:231], v[10:13]
	s_waitcnt lgkmcnt(1)
	v_mfma_f32_16x16x32_bf16 v[102:105], v[240:243], v[216:219], v[102:105]
	v_mfma_f32_16x16x32_bf16 v[70:73], v[240:243], v[220:223], v[70:73]
	v_mfma_f32_16x16x32_bf16 v[38:41], v[240:243], v[224:227], v[38:41]
	v_mfma_f32_16x16x32_bf16 v[6:9], v[240:243], v[228:231], v[6:9]
	s_waitcnt lgkmcnt(0)
	v_mfma_f32_16x16x32_bf16 v[98:101], v[244:247], v[216:219], v[98:101]
	v_mfma_f32_16x16x32_bf16 v[66:69], v[244:247], v[220:223], v[66:69]
	v_mfma_f32_16x16x32_bf16 v[34:37], v[244:247], v[224:227], v[34:37]
	v_mfma_f32_16x16x32_bf16 v[2:5], v[244:247], v[228:231], v[2:5]
	s_add_i32 s42, s42, 1
	s_cmp_lg_u32 s42, 3
	s_cselect_b32 s42, s42, 0
	s_add_i32 s43, s43, 1
	s_cmp_lg_u32 s43, 3
	s_cselect_b32 s43, s43, 0
	s_setprio 0
	s_add_i32 s20, s20, 1
	s_cmp_lg_u32 s20, 88
	s_cbranch_scc1 .LBB0_231
	s_branch .LBB0_237

; template <int OFF> DEVI bf16x8 ldsr(unsigned a) { bf16x8 v; asm volatile("ds_read_b128 %0, %1 offset:%2" : "=v"(v) : "v"(a), "n"(OFF)); return v; }
; #define RAW_BARRIER() do { asm volatile("s_waitcnt lgkmcnt(0)" ::: "memory"); __builtin_amdgcn_s_barrier(); } while (0)
; template <int EPI, int NB>
; DEVI void gemm_tile(const GemmJob& J, int m0, int n0, unsigned char* smem) {
;     ...
;   for (int kt = 0; kt < nk; ++kt) {
;     if (nk - 1 - kt >= S - 2) {
;       if constexpr (NB == 8) asm volatile("s_waitcnt vmcnt(6)" ::: "memory");
;       else                   asm volatile("s_waitcnt vmcnt(8)" ::: "memory");
;     } else {
;       asm volatile("s_waitcnt vmcnt(0)" ::: "memory");
;     }
;     RAW_BARRIER();
;     if (kt + S - 1 < nk) GEMM_ISSUE(kt + S - 1, is);
;     is = (is + 1 == S) ? 0 : is + 1;
;     const unsigned cur = lbase + cs * STG;
;     cs = (cs + 1 == S) ? 0 : cs + 1;
;     bf16x8 af[4], bfr[NB];
;     const unsigned aa = cur + aofs, ba = cur + bofs;
;     af[0] = ldsr<0>(aa); af[1] = ldsr<1024>(aa); af[2] = ldsr<2048>(aa); af[3] = ldsr<3072>(aa);
;     bfr[0] = ldsr<0>(ba); bfr[1] = ldsr<1024>(ba); bfr[2] = ldsr<2048>(ba); bfr[3] = ldsr<3072>(ba);
;     __builtin_amdgcn_s_setprio(1);
; #pragma unroll
;     for (int nb = 0; nb < NB; ++nb) {
;       if (nb == 0) asm volatile("s_waitcnt lgkmcnt(3)" : "+v"(af[0]), "+v"(af[1]), "+v"(af[2]), "+v"(af[3]), "+v"(bfr[0]) :: "memory");
;       else if (nb <= NB - 4) asm volatile("s_waitcnt lgkmcnt(3)" : "+v"(bfr[nb]) :: "memory");
;       else if (nb == NB - 3) asm volatile("s_waitcnt lgkmcnt(2)" : "+v"(bfr[nb]) :: "memory");
;       else if (nb == NB - 2) asm volatile("s_waitcnt lgkmcnt(1)" : "+v"(bfr[nb]) :: "memory");
;       else asm volatile("s_waitcnt lgkmcnt(0)" : "+v"(bfr[nb]) :: "memory");
;       __builtin_amdgcn_sched_barrier(0);
; #pragma unroll
;       for (int mb = 0; mb < 4; ++mb) {
;         if constexpr (SWAP) acc[mb][nb] = __builtin_amdgcn_mfma_f32_16x16x32_bf16(bfr[nb], af[mb], acc[mb][nb], 0, 0, 0);
;         else                acc[mb][nb] = __builtin_amdgcn_mfma_f32_16x16x32_bf16(af[mb], bfr[nb], acc[mb][nb], 0, 0, 0);
;       }
.LBB0_309:
	s_mul_i32 s1, s43, 0x6000
	v_add_u32_e32 v215, s1, v213
	v_add_u32_e32 v248, s1, v214
	s_mul_i32 m0, s42, 0x6000
	s_add_u32 m0, m0, s0
	s_cmp_gt_u32 s2, 86
	s_cbranch_scc1 .Lgk3_w0
	s_waitcnt vmcnt(6)
.Lgk3_bar:
	s_waitcnt lgkmcnt(0)
	s_barrier
	s_setprio 1
	ds_read_b128 v[216:219], v215 offset:0
	ds_read_b128 v[232:235], v248 offset:0
	ds_read_b128 v[220:223], v215 offset:0x400
	ds_read_b128 v[224:227], v215 offset:0x800
	ds_read_b128 v[228:231], v215 offset:0xc00
	ds_read_b128 v[236:239], v248 offset:0x400
	ds_read_b128 v[240:243], v248 offset:0x800
	ds_read_b128 v[244:247], v248 offset:0xc00
	s_cmp_gt_u32 s2, 85
	s_cbranch_scc1 .Lgk3_tail
	s_waitcnt lgkmcnt(6)
	v_mfma_f32_16x16x32_bf16 v[126:129], v[232:235], v[216:219], v[126:129]
	s_waitcnt lgkmcnt(5)
	v_mfma_f32_16x16x32_bf16 v[94:97], v[232:235], v[220:223], v[94:97]
	s_waitcnt lgkmcnt(4)
	v_mfma_f32_16x16x32_bf16 v[62:65], v[232:235], v[224:227], v[62:65]
	s_waitcnt lgkmcnt(3)
	v_mfma_f32_16x16x32_bf16 v[30:33], v[232:235], v[228:231], v[30:33]
	ds_read_b128 v[232:235], v248 offset:0x1000
	global_load_lds_dwordx4 v186, s[100:101]
	s_add_u32 m0, m0, 0x1000
	s_waitcnt lgkmcnt(3)
	v_mfma_f32_16x16x32_bf16 v[122:125], v[236:239], v[216:219], v[122:125]
	v_mfma_f32_16x16x32_bf16 v[90:93], v[236:239], v[220:223], v[90:93]
	v_mfma_f32_16x16x32_bf16 v[58:61], v[236:239], v[224:227], v[58:61]
	v_mfma_f32_16x16x32_bf16 v[26:29], v[236:239], v[228:231], v[26:29]
	ds_read_b128 v[236:239], v248 offset:0x1400
	global_load_lds_dwordx4 v187, s[100:101]
	s_add_u32 m0, m0, 0x1000
	s_waitcnt lgkmcnt(3)
	v_mfma_f32_16x16x32_bf16 v[118:121], v[240:243], v[216:219], v[118:121]
	v_mfma_f32_16x16x32_bf16 v[86:89], v[240:243], v[220:223], v[86:89]
	v_mfma_f32_16x16x32_bf16 v[54:57], v[240:243], v[224:227], v[54:57]
	v_mfma_f32_16x16x32_bf16 v[22:25], v[240:243], v[228:231], v[22:25]
	ds_read_b128 v[240:243], v248 offset:0x1800
	global_load_lds_dwordx4 v184, vcc
	s_add_u32 m0, m0, 0x1000
	s_waitcnt lgkmcnt(3)
	v_mfma_f32_16x16x32_bf16 v[114:117], v[244:247], v[216:219], v[114:117]
	v_mfma_f32_16x16x32_bf16 v[82:85], v[244:247], v[220:223], v[82:85]
	v_mfma_f32_16x16x32_bf16 v[50:53], v[244:247], v[224:227], v[50:53]
	v_mfma_f32_16x16x32_bf16 v[18:21], v[244:247], v[228:231], v[18:21]
	ds_read_b128 v[244:247], v248 offset:0x1c00
	global_load_lds_dwordx4 v185, vcc
	s_add_u32 m0, m0, 0x1000
	s_waitcnt lgkmcnt(3)
	v_mfma_f32_16x16x32_bf16 v[110:113], v[232:235], v[216:219], v[110:113]
	v_mfma_f32_16x16x32_bf16 v[78:81], v[232:235], v[220:223], v[78:81]
	v_mfma_f32_16x16x32_bf16 v[46:49], v[232:235], v[224:227], v[46:49]
	v_mfma_f32_16x16x32_bf16 v[14:17], v[232:235], v[228:231], v[14:17]
	global_load_lds_dwordx4 v253, vcc
	s_add_u32 m0, m0, 0x1000
	s_waitcnt lgkmcnt(2)
	v_mfma_f32_16x16x32_bf16 v[106:109], v[236:239], v[216:219], v[106:109]
	v_mfma_f32_16x16x32_bf16 v[74:77], v[236:239], v[220:223], v[74:77]
	v_mfma_f32_16x16x32_bf16 v[42:45], v[236:239], v[224:227], v[42:45]
	v_mfma_f32_16x16x32_bf16 v[10:13], v[236:239], v[228:231], v[10:13]
	global_load_lds_dwordx4 v254, vcc
	s_waitcnt lgkmcnt(1)
	v_mfma_f32_16x16x32_bf16 v[102:105], v[240:243], v[216:219], v[102:105]
	v_mfma_f32_16x16x32_bf16 v[70:73], v[240:243], v[220:223], v[70:73]
	v_mfma_f32_16x16x32_bf16 v[38:41], v[240:243], v[224:227], v[38:41]
	v_mfma_f32_16x16x32_bf16 v[6:9], v[240:243], v[228:231], v[6:9]
	s_waitcnt lgkmcnt(0)
	v_mfma_f32_16x16x32_bf16 v[98:101], v[244:247], v[216:219], v[98:101]
	v_mfma_f32_16x16x32_bf16 v[66:69], v[244:247], v[220:223], v[66:69]
	v_mfma_f32_16x16x32_bf16 v[34:37], v[244:247], v[224:227], v[34:37]
	v_mfma_f32_16x16x32_bf16 v[2:5], v[244:247], v[228:231], v[2:5]
	s_add_u32 s100, s100, s94
	s_addc_u32 s101, s101, s95
	s_add_u32 vcc_lo, vcc_lo, s22
	s_addc_u32 vcc_hi, vcc_hi, s23
	s_add_i32 s42, s42, 1
	s_cmp_lg_u32 s42, 3
	s_cselect_b32 s42, s42, 0
	s_add_i32 s43, s43, 1
	s_cmp_lg_u32 s43, 3
	s_cselect_b32 s43, s43, 0
	s_setprio 0
	s_add_i32 s2, s2, 1
	s_branch .LBB0_309
.Lgk3_tail:
	s_waitcnt lgkmcnt(6)
	v_mfma_f32_16x16x32_bf16 v[126:129], v[232:235], v[216:219], v[126:129]
	s_waitcnt lgkmcnt(5)
	v_mfma_f32_16x16x32_bf16 v[94:97], v[232:235], v[220:223], v[94:97]
	s_waitcnt lgkmcnt(4)
	v_mfma_f32_16x16x32_bf16 v[62:65], v[232:235], v[224:227], v[62:65]
	s_waitcnt lgkmcnt(3)
	v_mfma_f32_16x16x32_bf16 v[30:33], v[232:235], v[228:231], v[30:33]
	ds_read_b128 v[232:235], v248 offset:0x1000
	s_waitcnt lgkmcnt(3)
	v_mfma_f32_16x16x32_bf16 v[122:125], v[236:239], v[216:219], v[122:125]
	v_mfma_f32_16x16x32_bf16 v[90:93], v[236:239], v[220:223], v[90:93]
	v_mfma_f32_16x16x32_bf16 v[58:61], v[236:239], v[224:227], v[58:61]
	v_mfma_f32_16x16x32_bf16 v[26:29], v[236:239], v[228:231], v[26:29]
	ds_read_b128 v[236:239], v248 offset:0x1400
	s_waitcnt lgkmcnt(3)
	v_mfma_f32_16x16x32_bf16 v[118:121], v[240:243], v[216:219], v[118:121]
	v_mfma_f32_16x16x32_bf16 v[86:89], v[240:243], v[220:223], v[86:89]
	v_mfma_f32_16x16x32_bf16 v[54:57], v[240:243], v[224:227], v[54:57]
	v_mfma_f32_16x16x32_bf16 v[22:25], v[240:243], v[228:231], v[22:25]
	ds_read_b128 v[240:243], v248 offset:0x1800
	s_waitcnt lgkmcnt(3)
	v_mfma_f32_16x16x32_bf16 v[114:117], v[244:247], v[216:219], v[114:117]
	v_mfma_f32_16x16x32_bf16 v[82:85], v[244:247], v[220:223], v[82:85]
	v_mfma_f32_16x16x32_bf16 v[50:53], v[244:247], v[224:227], v[50:53]
	v_mfma_f32_16x16x32_bf16 v[18:21], v[244:247], v[228:231], v[18:21]
	ds_read_b128 v[244:247], v248 offset:0x1c00
	s_waitcnt lgkmcnt(3)
	v_mfma_f32_16x16x32_bf16 v[110:113], v[232:235], v[216:219], v[110:113]
	v_mfma_f32_16x16x32_bf16 v[78:81], v[232:235], v[220:223], v[78:81]
	v_mfma_f32_16x16x32_bf16 v[46:49], v[232:235], v[224:227], v[46:49]
	v_mfma_f32_16x16x32_bf16 v[14:17], v[232:235], v[228:231], v[14:17]
	s_waitcnt lgkmcnt(2)
	v_mfma_f32_16x16x32_bf16 v[106:109], v[236:239], v[216:219], v[106:109]
	v_mfma_f32_16x16x32_bf16 v[74:77], v[236:239], v[220:223], v[74:77]
	v_mfma_f32_16x16x32_bf16 v[42:45], v[236:239], v[224:227], v[42:45]
	v_mfma_f32_16x16x32_bf16 v[10:13], v[236:239], v[228:231], v[10:13]
	s_waitcnt lgkmcnt(1)
	v_mfma_f32_16x16x32_bf16 v[102:105], v[240:243], v[216:219], v[102:105]
	v_mfma_f32_16x16x32_bf16 v[70:73], v[240:243], v[220:223], v[70:73]
	v_mfma_f32_16x16x32_bf16 v[38:41], v[240:243], v[224:227], v[38:41]
	v_mfma_f32_16x16x32_bf16 v[6:9], v[240:243], v[228:231], v[6:9]
	s_waitcnt lgkmcnt(0)
	v_mfma_f32_16x16x32_bf16 v[98:101], v[244:247], v[216:219], v[98:101]
	v_mfma_f32_16x16x32_bf16 v[66:69], v[244:247], v[220:223], v[66:69]
	v_mfma_f32_16x16x32_bf16 v[34:37], v[244:247], v[224:227], v[34:37]
	v_mfma_f32_16x16x32_bf16 v[2:5], v[244:247], v[228:231], v[2:5]
	s_add_i32 s42, s42, 1
	s_cmp_lg_u32 s42, 3
	s_cselect_b32 s42, s42, 0
	s_add_i32 s43, s43, 1
	s_cmp_lg_u32 s43, 3
	s_cselect_b32 s43, s43, 0
	s_setprio 0
	s_add_i32 s2, s2, 1
	s_cmp_lg_u32 s2, 88
	s_cbranch_scc1 .LBB0_309
	s_branch .LBB0_315

; template <int OFF> DEVI bf16x8 ldsr(unsigned a) { bf16x8 v; asm volatile("ds_read_b128 %0, %1 offset:%2" : "=v"(v) : "v"(a), "n"(OFF)); return v; }
; #define RAW_BARRIER() do { asm volatile("s_waitcnt lgkmcnt(0)" ::: "memory"); __builtin_amdgcn_s_barrier(); } while (0)
; template <int EPI, int NB>
; DEVI void gemm_tile(const GemmJob& J, int m0, int n0, unsigned char* smem) {
;     ...
;   for (int kt = 0; kt < nk; ++kt) {
;     if (nk - 1 - kt >= S - 2) {
;       if constexpr (NB == 8) asm volatile("s_waitcnt vmcnt(6)" ::: "memory");
;       else                   asm volatile("s_waitcnt vmcnt(8)" ::: "memory");
;     } else {
;       asm volatile("s_waitcnt vmcnt(0)" ::: "memory");
;     }
;     RAW_BARRIER();
;     if (kt + S - 1 < nk) GEMM_ISSUE(kt + S - 1, is);
;     is = (is + 1 == S) ? 0 : is + 1;
;     const unsigned cur = lbase + cs * STG;
;     cs = (cs + 1 == S) ? 0 : cs + 1;
;     bf16x8 af[4], bfr[NB];
;     const unsigned aa = cur + aofs, ba = cur + bofs;
;     af[0] = ldsr<0>(aa); af[1] = ldsr<1024>(aa); af[2] = ldsr<2048>(aa); af[3] = ldsr<3072>(aa);
;     bfr[0] = ldsr<0>(ba); bfr[1] = ldsr<1024>(ba); bfr[2] = ldsr<2048>(ba); bfr[3] = ldsr<3072>(ba);
;     __builtin_amdgcn_s_setprio(1);
; #pragma unroll
;     for (int nb = 0; nb < NB; ++nb) {
;       if (nb == 0) asm volatile("s_waitcnt lgkmcnt(3)" : "+v"(af[0]), "+v"(af[1]), "+v"(af[2]), "+v"(af[3]), "+v"(bfr[0]) :: "memory");
;       else if (nb <= NB - 4) asm volatile("s_waitcnt lgkmcnt(3)" : "+v"(bfr[nb]) :: "memory");
;       else if (nb == NB - 3) asm volatile("s_waitcnt lgkmcnt(2)" : "+v"(bfr[nb]) :: "memory");
;       else if (nb == NB - 2) asm volatile("s_waitcnt lgkmcnt(1)" : "+v"(bfr[nb]) :: "memory");
;       else asm volatile("s_waitcnt lgkmcnt(0)" : "+v"(bfr[nb]) :: "memory");
;       __builtin_amdgcn_sched_barrier(0);
; #pragma unroll
;       for (int mb = 0; mb < 4; ++mb) {
;         if constexpr (SWAP) acc[mb][nb] = __builtin_amdgcn_mfma_f32_16x16x32_bf16(bfr[nb], af[mb], acc[mb][nb], 0, 0, 0);
;         else                acc[mb][nb] = __builtin_amdgcn_mfma_f32_16x16x32_bf16(af[mb], bfr[nb], acc[mb][nb], 0, 0, 0);
;       }
.LBB0_529:
	s_mul_i32 s1, s43, 0x6000
	v_add_u32_e32 v211, s1, v209
	v_add_u32_e32 v244, s1, v210
	s_mul_i32 m0, s42, 0x6000
	s_add_u32 m0, m0, s0
	s_cmp_gt_u32 s20, 30
	s_cbranch_scc1 .Lgk4_w0
	s_waitcnt vmcnt(6)
.Lgk4_bar:
	s_waitcnt lgkmcnt(0)
	s_barrier
	s_setprio 1
	ds_read_b128 v[212:215], v211 offset:0
	ds_read_b128 v[228:231], v244 offset:0
	ds_read_b128 v[216:219], v211 offset:0x400
	ds_read_b128 v[220:223], v211 offset:0x800
	ds_read_b128 v[224:227], v211 offset:0xc00
	ds_read_b128 v[232:235], v244 offset:0x400
	ds_read_b128 v[236:239], v244 offset:0x800
	ds_read_b128 v[240:243], v244 offset:0xc00
	s_cmp_gt_u32 s20, 29
	s_cbranch_scc1 .Lgk4_tail
	s_waitcnt lgkmcnt(6)
	v_mfma_f32_16x16x32_bf16 v[126:129], v[228:231], v[212:215], v[126:129]
	s_waitcnt lgkmcnt(5)
	v_mfma_f32_16x16x32_bf16 v[94:97], v[228:231], v[216:219], v[94:97]
	s_waitcnt lgkmcnt(4)
	v_mfma_f32_16x16x32_bf16 v[62:65], v[228:231], v[220:223], v[62:65]
	s_waitcnt lgkmcnt(3)
	v_mfma_f32_16x16x32_bf16 v[30:33], v[228:231], v[224:227], v[30:33]
	ds_read_b128 v[228:231], v244 offset:0x1000
	global_load_lds_dwordx4 v182, s[100:101]
	s_add_u32 m0, m0, 0x1000
	s_waitcnt lgkmcnt(3)
	v_mfma_f32_16x16x32_bf16 v[122:125], v[232:235], v[212:215], v[122:125]
	v_mfma_f32_16x16x32_bf16 v[90:93], v[232:235], v[216:219], v[90:93]
	v_mfma_f32_16x16x32_bf16 v[58:61], v[232:235], v[220:223], v[58:61]
	v_mfma_f32_16x16x32_bf16 v[26:29], v[232:235], v[224:227], v[26:29]
	ds_read_b128 v[232:235], v244 offset:0x1400
	global_load_lds_dwordx4 v183, s[100:101]
	s_add_u32 m0, m0, 0x1000
	s_waitcnt lgkmcnt(3)
	v_mfma_f32_16x16x32_bf16 v[118:121], v[236:239], v[212:215], v[118:121]
	v_mfma_f32_16x16x32_bf16 v[86:89], v[236:239], v[216:219], v[86:89]
	v_mfma_f32_16x16x32_bf16 v[54:57], v[236:239], v[220:223], v[54:57]
	v_mfma_f32_16x16x32_bf16 v[22:25], v[236:239], v[224:227], v[22:25]
	ds_read_b128 v[236:239], v244 offset:0x1800
	global_load_lds_dwordx4 v180, vcc
	s_add_u32 m0, m0, 0x1000
	s_waitcnt lgkmcnt(3)
	v_mfma_f32_16x16x32_bf16 v[114:117], v[240:243], v[212:215], v[114:117]
	v_mfma_f32_16x16x32_bf16 v[82:85], v[240:243], v[216:219], v[82:85]
	v_mfma_f32_16x16x32_bf16 v[50:53], v[240:243], v[220:223], v[50:53]
	v_mfma_f32_16x16x32_bf16 v[18:21], v[240:243], v[224:227], v[18:21]
	ds_read_b128 v[240:243], v244 offset:0x1c00
	global_load_lds_dwordx4 v181, vcc
	s_add_u32 m0, m0, 0x1000
	s_waitcnt lgkmcnt(3)
	v_mfma_f32_16x16x32_bf16 v[110:113], v[228:231], v[212:215], v[110:113]
	v_mfma_f32_16x16x32_bf16 v[78:81], v[228:231], v[216:219], v[78:81]
	v_mfma_f32_16x16x32_bf16 v[46:49], v[228:231], v[220:223], v[46:49]
	v_mfma_f32_16x16x32_bf16 v[14:17], v[228:231], v[224:227], v[14:17]
	global_load_lds_dwordx4 v253, vcc
	s_add_u32 m0, m0, 0x1000
	s_waitcnt lgkmcnt(2)
	v_mfma_f32_16x16x32_bf16 v[106:109], v[232:235], v[212:215], v[106:109]
	v_mfma_f32_16x16x32_bf16 v[74:77], v[232:235], v[216:219], v[74:77]
	v_mfma_f32_16x16x32_bf16 v[42:45], v[232:235], v[220:223], v[42:45]
	v_mfma_f32_16x16x32_bf16 v[10:13], v[232:235], v[224:227], v[10:13]
	global_load_lds_dwordx4 v254, vcc
	s_waitcnt lgkmcnt(1)
	v_mfma_f32_16x16x32_bf16 v[102:105], v[236:239], v[212:215], v[102:105]
	v_mfma_f32_16x16x32_bf16 v[70:73], v[236:239], v[216:219], v[70:73]
	v_mfma_f32_16x16x32_bf16 v[38:41], v[236:239], v[220:223], v[38:41]
	v_mfma_f32_16x16x32_bf16 v[6:9], v[236:239], v[224:227], v[6:9]
	s_waitcnt lgkmcnt(0)
	v_mfma_f32_16x16x32_bf16 v[98:101], v[240:243], v[212:215], v[98:101]
	v_mfma_f32_16x16x32_bf16 v[66:69], v[240:243], v[216:219], v[66:69]
	v_mfma_f32_16x16x32_bf16 v[34:37], v[240:243], v[220:223], v[34:37]
	v_mfma_f32_16x16x32_bf16 v[2:5], v[240:243], v[224:227], v[2:5]
	s_add_u32 s100, s100, s94
	s_addc_u32 s101, s101, s95
	s_add_u32 vcc_lo, vcc_lo, s4
	s_addc_u32 vcc_hi, vcc_hi, s5
	s_add_i32 s42, s42, 1
	s_cmp_lg_u32 s42, 3
	s_cselect_b32 s42, s42, 0
	s_add_i32 s43, s43, 1
	s_cmp_lg_u32 s43, 3
	s_cselect_b32 s43, s43, 0
	s_setprio 0
	s_add_i32 s20, s20, 1
	s_branch .LBB0_529
.Lgk4_tail:
	s_waitcnt lgkmcnt(6)
	v_mfma_f32_16x16x32_bf16 v[126:129], v[228:231], v[212:215], v[126:129]
	s_waitcnt lgkmcnt(5)
	v_mfma_f32_16x16x32_bf16 v[94:97], v[228:231], v[216:219], v[94:97]
	s_waitcnt lgkmcnt(4)
	v_mfma_f32_16x16x32_bf16 v[62:65], v[228:231], v[220:223], v[62:65]
	s_waitcnt lgkmcnt(3)
	v_mfma_f32_16x16x32_bf16 v[30:33], v[228:231], v[224:227], v[30:33]
	ds_read_b128 v[228:231], v244 offset:0x1000
	s_waitcnt lgkmcnt(3)
	v_mfma_f32_16x16x32_bf16 v[122:125], v[232:235], v[212:215], v[122:125]
	v_mfma_f32_16x16x32_bf16 v[90:93], v[232:235], v[216:219], v[90:93]
	v_mfma_f32_16x16x32_bf16 v[58:61], v[232:235], v[220:223], v[58:61]
	v_mfma_f32_16x16x32_bf16 v[26:29], v[232:235], v[224:227], v[26:29]
	ds_read_b128 v[232:235], v244 offset:0x1400
	s_waitcnt lgkmcnt(3)
	v_mfma_f32_16x16x32_bf16 v[118:121], v[236:239], v[212:215], v[118:121]
	v_mfma_f32_16x16x32_bf16 v[86:89], v[236:239], v[216:219], v[86:89]
	v_mfma_f32_16x16x32_bf16 v[54:57], v[236:239], v[220:223], v[54:57]
	v_mfma_f32_16x16x32_bf16 v[22:25], v[236:239], v[224:227], v[22:25]
	ds_read_b128 v[236:239], v244 offset:0x1800
	s_waitcnt lgkmcnt(3)
	v_mfma_f32_16x16x32_bf16 v[114:117], v[240:243], v[212:215], v[114:117]
	v_mfma_f32_16x16x32_bf16 v[82:85], v[240:243], v[216:219], v[82:85]
	v_mfma_f32_16x16x32_bf16 v[50:53], v[240:243], v[220:223], v[50:53]
	v_mfma_f32_16x16x32_bf16 v[18:21], v[240:243], v[224:227], v[18:21]
	ds_read_b128 v[240:243], v244 offset:0x1c00
	s_waitcnt lgkmcnt(3)
	v_mfma_f32_16x16x32_bf16 v[110:113], v[228:231], v[212:215], v[110:113]
	v_mfma_f32_16x16x32_bf16 v[78:81], v[228:231], v[216:219], v[78:81]
	v_mfma_f32_16x16x32_bf16 v[46:49], v[228:231], v[220:223], v[46:49]
	v_mfma_f32_16x16x32_bf16 v[14:17], v[228:231], v[224:227], v[14:17]
	s_waitcnt lgkmcnt(2)
	v_mfma_f32_16x16x32_bf16 v[106:109], v[232:235], v[212:215], v[106:109]
	v_mfma_f32_16x16x32_bf16 v[74:77], v[232:235], v[216:219], v[74:77]
	v_mfma_f32_16x16x32_bf16 v[42:45], v[232:235], v[220:223], v[42:45]
	v_mfma_f32_16x16x32_bf16 v[10:13], v[232:235], v[224:227], v[10:13]
	s_waitcnt lgkmcnt(1)
	v_mfma_f32_16x16x32_bf16 v[102:105], v[236:239], v[212:215], v[102:105]
	v_mfma_f32_16x16x32_bf16 v[70:73], v[236:239], v[216:219], v[70:73]
	v_mfma_f32_16x16x32_bf16 v[38:41], v[236:239], v[220:223], v[38:41]
	v_mfma_f32_16x16x32_bf16 v[6:9], v[236:239], v[224:227], v[6:9]
	s_waitcnt lgkmcnt(0)
	v_mfma_f32_16x16x32_bf16 v[98:101], v[240:243], v[212:215], v[98:101]
	v_mfma_f32_16x16x32_bf16 v[66:69], v[240:243], v[216:219], v[66:69]
	v_mfma_f32_16x16x32_bf16 v[34:37], v[240:243], v[220:223], v[34:37]
	v_mfma_f32_16x16x32_bf16 v[2:5], v[240:243], v[224:227], v[2:5]
	s_add_i32 s42, s42, 1
	s_cmp_lg_u32 s42, 3
	s_cselect_b32 s42, s42, 0
	s_add_i32 s43, s43, 1
	s_cmp_lg_u32 s43, 3
	s_cselect_b32 s43, s43, 0
	s_setprio 0
	s_add_i32 s20, s20, 1
	s_cmp_lg_u32 s20, 32
	s_cbranch_scc1 .LBB0_529
	s_branch .LBB0_535

; template <int OFF> DEVI bf16x8 ldsr(unsigned a) { bf16x8 v; asm volatile("ds_read_b128 %0, %1 offset:%2" : "=v"(v) : "v"(a), "n"(OFF)); return v; }
; #define RAW_BARRIER() do { asm volatile("s_waitcnt lgkmcnt(0)" ::: "memory"); __builtin_amdgcn_s_barrier(); } while (0)
; template <int EPI, int NB>
; DEVI void gemm_tile(const GemmJob& J, int m0, int n0, unsigned char* smem) {
;     ...
;   for (int kt = 0; kt < nk; ++kt) {
;     if (nk - 1 - kt >= S - 2) {
;       if constexpr (NB == 8) asm volatile("s_waitcnt vmcnt(6)" ::: "memory");
;       else                   asm volatile("s_waitcnt vmcnt(8)" ::: "memory");
;     } else {
;       asm volatile("s_waitcnt vmcnt(0)" ::: "memory");
;     }
;     RAW_BARRIER();
;     if (kt + S - 1 < nk) GEMM_ISSUE(kt + S - 1, is);
;     is = (is + 1 == S) ? 0 : is + 1;
;     const unsigned cur = lbase + cs * STG;
;     cs = (cs + 1 == S) ? 0 : cs + 1;
;     bf16x8 af[4], bfr[NB];
;     const unsigned aa = cur + aofs, ba = cur + bofs;
;     af[0] = ldsr<0>(aa); af[1] = ldsr<1024>(aa); af[2] = ldsr<2048>(aa); af[3] = ldsr<3072>(aa);
;     bfr[0] = ldsr<0>(ba); bfr[1] = ldsr<1024>(ba); bfr[2] = ldsr<2048>(ba); bfr[3] = ldsr<3072>(ba);
;     __builtin_amdgcn_s_setprio(1);
; #pragma unroll
;     for (int nb = 0; nb < NB; ++nb) {
;       if (nb == 0) asm volatile("s_waitcnt lgkmcnt(3)" : "+v"(af[0]), "+v"(af[1]), "+v"(af[2]), "+v"(af[3]), "+v"(bfr[0]) :: "memory");
;       else if (nb <= NB - 4) asm volatile("s_waitcnt lgkmcnt(3)" : "+v"(bfr[nb]) :: "memory");
;       else if (nb == NB - 3) asm volatile("s_waitcnt lgkmcnt(2)" : "+v"(bfr[nb]) :: "memory");
;       else if (nb == NB - 2) asm volatile("s_waitcnt lgkmcnt(1)" : "+v"(bfr[nb]) :: "memory");
;       else asm volatile("s_waitcnt lgkmcnt(0)" : "+v"(bfr[nb]) :: "memory");
;       __builtin_amdgcn_sched_barrier(0);
; #pragma unroll
;       for (int mb = 0; mb < 4; ++mb) {
;         if constexpr (SWAP) acc[mb][nb] = __builtin_amdgcn_mfma_f32_16x16x32_bf16(bfr[nb], af[mb], acc[mb][nb], 0, 0, 0);
;         else                acc[mb][nb] = __builtin_amdgcn_mfma_f32_16x16x32_bf16(af[mb], bfr[nb], acc[mb][nb], 0, 0, 0);
.LBB0_607:
	s_mul_i32 s1, s43, 0x6000
	v_add_u32_e32 v222, s1, v208
	v_add_u32_e32 v242, s1, v209
	s_mul_i32 m0, s42, 0x6000
	s_add_u32 m0, m0, s0
	s_cmp_gt_u32 s20, 30
	s_cbranch_scc1 .Lgk5_w0
	s_waitcnt vmcnt(6)
.Lgk5_bar:
	s_waitcnt lgkmcnt(0)
	s_barrier
	s_setprio 1
	ds_read_b128 v[210:213], v222 offset:0
	ds_read_b128 v[226:229], v242 offset:0
	ds_read_b128 v[214:217], v222 offset:0x400
	ds_read_b128 v[218:221], v222 offset:0x800
	ds_read_b128 v[222:225], v222 offset:0xc00
	ds_read_b128 v[230:233], v242 offset:0x400
	ds_read_b128 v[234:237], v242 offset:0x800
	ds_read_b128 v[238:241], v242 offset:0xc00
	s_cmp_gt_u32 s20, 29
	s_cbranch_scc1 .Lgk5_tail
	s_waitcnt lgkmcnt(6)
	v_mfma_f32_16x16x32_bf16 v[126:129], v[210:213], v[226:229], v[126:129]
	s_waitcnt lgkmcnt(5)
	v_mfma_f32_16x16x32_bf16 v[94:97], v[214:217], v[226:229], v[94:97]
	s_waitcnt lgkmcnt(4)
	v_mfma_f32_16x16x32_bf16 v[62:65], v[218:221], v[226:229], v[62:65]
	s_waitcnt lgkmcnt(3)
	v_mfma_f32_16x16x32_bf16 v[30:33], v[222:225], v[226:229], v[30:33]
	ds_read_b128 v[226:229], v242 offset:0x1000
	global_load_lds_dwordx4 v182, s[100:101]
	s_add_u32 m0, m0, 0x1000
	s_waitcnt lgkmcnt(3)
	v_mfma_f32_16x16x32_bf16 v[122:125], v[210:213], v[230:233], v[122:125]
	v_mfma_f32_16x16x32_bf16 v[90:93], v[214:217], v[230:233], v[90:93]
	v_mfma_f32_16x16x32_bf16 v[58:61], v[218:221], v[230:233], v[58:61]
	v_mfma_f32_16x16x32_bf16 v[26:29], v[222:225], v[230:233], v[26:29]
	ds_read_b128 v[230:233], v242 offset:0x1400
	global_load_lds_dwordx4 v183, s[100:101]
	s_add_u32 m0, m0, 0x1000
	s_waitcnt lgkmcnt(3)
	v_mfma_f32_16x16x32_bf16 v[118:121], v[210:213], v[234:237], v[118:121]
	v_mfma_f32_16x16x32_bf16 v[86:89], v[214:217], v[234:237], v[86:89]
	v_mfma_f32_16x16x32_bf16 v[54:57], v[218:221], v[234:237], v[54:57]
	v_mfma_f32_16x16x32_bf16 v[22:25], v[222:225], v[234:237], v[22:25]
	ds_read_b128 v[234:237], v242 offset:0x1800
	global_load_lds_dwordx4 v180, vcc
	s_add_u32 m0, m0, 0x1000
	s_waitcnt lgkmcnt(3)
	v_mfma_f32_16x16x32_bf16 v[114:117], v[210:213], v[238:241], v[114:117]
	v_mfma_f32_16x16x32_bf16 v[82:85], v[214:217], v[238:241], v[82:85]
	v_mfma_f32_16x16x32_bf16 v[50:53], v[218:221], v[238:241], v[50:53]
	v_mfma_f32_16x16x32_bf16 v[18:21], v[222:225], v[238:241], v[18:21]
	ds_read_b128 v[238:241], v242 offset:0x1c00
	global_load_lds_dwordx4 v181, vcc
	s_add_u32 m0, m0, 0x1000
	s_waitcnt lgkmcnt(3)
	v_mfma_f32_16x16x32_bf16 v[110:113], v[210:213], v[226:229], v[110:113]
	v_mfma_f32_16x16x32_bf16 v[78:81], v[214:217], v[226:229], v[78:81]
	v_mfma_f32_16x16x32_bf16 v[46:49], v[218:221], v[226:229], v[46:49]
	v_mfma_f32_16x16x32_bf16 v[14:17], v[222:225], v[226:229], v[14:17]
	global_load_lds_dwordx4 v253, vcc
	s_add_u32 m0, m0, 0x1000
	s_waitcnt lgkmcnt(2)
	v_mfma_f32_16x16x32_bf16 v[106:109], v[210:213], v[230:233], v[106:109]
	v_mfma_f32_16x16x32_bf16 v[74:77], v[214:217], v[230:233], v[74:77]
	v_mfma_f32_16x16x32_bf16 v[42:45], v[218:221], v[230:233], v[42:45]
	v_mfma_f32_16x16x32_bf16 v[10:13], v[222:225], v[230:233], v[10:13]
	global_load_lds_dwordx4 v254, vcc
	s_waitcnt lgkmcnt(1)
	v_mfma_f32_16x16x32_bf16 v[102:105], v[210:213], v[234:237], v[102:105]
	v_mfma_f32_16x16x32_bf16 v[70:73], v[214:217], v[234:237], v[70:73]
	v_mfma_f32_16x16x32_bf16 v[38:41], v[218:221], v[234:237], v[38:41]
	v_mfma_f32_16x16x32_bf16 v[6:9], v[222:225], v[234:237], v[6:9]
	s_waitcnt lgkmcnt(0)
	v_mfma_f32_16x16x32_bf16 v[98:101], v[210:213], v[238:241], v[98:101]
	v_mfma_f32_16x16x32_bf16 v[66:69], v[214:217], v[238:241], v[66:69]
	v_mfma_f32_16x16x32_bf16 v[34:37], v[218:221], v[238:241], v[34:37]
	v_mfma_f32_16x16x32_bf16 v[2:5], v[222:225], v[238:241], v[2:5]
	s_add_u32 s100, s100, s94
	s_addc_u32 s101, s101, s95
	s_add_u32 vcc_lo, vcc_lo, s4
	s_addc_u32 vcc_hi, vcc_hi, s5
	s_add_i32 s42, s42, 1
	s_cmp_lg_u32 s42, 3
	s_cselect_b32 s42, s42, 0
	s_add_i32 s43, s43, 1
	s_cmp_lg_u32 s43, 3
	s_cselect_b32 s43, s43, 0
	s_setprio 0
	s_add_i32 s20, s20, 1
	s_branch .LBB0_607
.Lgk5_tail:
	s_waitcnt lgkmcnt(6)
	v_mfma_f32_16x16x32_bf16 v[126:129], v[210:213], v[226:229], v[126:129]
	s_waitcnt lgkmcnt(5)
	v_mfma_f32_16x16x32_bf16 v[94:97], v[214:217], v[226:229], v[94:97]
	s_waitcnt lgkmcnt(4)
	v_mfma_f32_16x16x32_bf16 v[62:65], v[218:221], v[226:229], v[62:65]
	s_waitcnt lgkmcnt(3)
	v_mfma_f32_16x16x32_bf16 v[30:33], v[222:225], v[226:229], v[30:33]
	ds_read_b128 v[226:229], v242 offset:0x1000
	s_waitcnt lgkmcnt(3)
	v_mfma_f32_16x16x32_bf16 v[122:125], v[210:213], v[230:233], v[122:125]
	v_mfma_f32_16x16x32_bf16 v[90:93], v[214:217], v[230:233], v[90:93]
	v_mfma_f32_16x16x32_bf16 v[58:61], v[218:221], v[230:233], v[58:61]
	v_mfma_f32_16x16x32_bf16 v[26:29], v[222:225], v[230:233], v[26:29]
	ds_read_b128 v[230:233], v242 offset:0x1400
	s_waitcnt lgkmcnt(3)
	v_mfma_f32_16x16x32_bf16 v[118:121], v[210:213], v[234:237], v[118:121]
	v_mfma_f32_16x16x32_bf16 v[86:89], v[214:217], v[234:237], v[86:89]
	v_mfma_f32_16x16x32_bf16 v[54:57], v[218:221], v[234:237], v[54:57]
	v_mfma_f32_16x16x32_bf16 v[22:25], v[222:225], v[234:237], v[22:25]
	ds_read_b128 v[234:237], v242 offset:0x1800
	s_waitcnt lgkmcnt(3)
	v_mfma_f32_16x16x32_bf16 v[114:117], v[210:213], v[238:241], v[114:117]
	v_mfma_f32_16x16x32_bf16 v[82:85], v[214:217], v[238:241], v[82:85]
	v_mfma_f32_16x16x32_bf16 v[50:53], v[218:221], v[238:241], v[50:53]
	v_mfma_f32_16x16x32_bf16 v[18:21], v[222:225], v[238:241], v[18:21]
	ds_read_b128 v[238:241], v242 offset:0x1c00
	s_waitcnt lgkmcnt(3)
	v_mfma_f32_16x16x32_bf16 v[110:113], v[210:213], v[226:229], v[110:113]
	v_mfma_f32_16x16x32_bf16 v[78:81], v[214:217], v[226:229], v[78:81]
	v_mfma_f32_16x16x32_bf16 v[46:49], v[218:221], v[226:229], v[46:49]
	v_mfma_f32_16x16x32_bf16 v[14:17], v[222:225], v[226:229], v[14:17]
	s_waitcnt lgkmcnt(2)
	v_mfma_f32_16x16x32_bf16 v[106:109], v[210:213], v[230:233], v[106:109]
	v_mfma_f32_16x16x32_bf16 v[74:77], v[214:217], v[230:233], v[74:77]
	v_mfma_f32_16x16x32_bf16 v[42:45], v[218:221], v[230:233], v[42:45]
	v_mfma_f32_16x16x32_bf16 v[10:13], v[222:225], v[230:233], v[10:13]
	s_waitcnt lgkmcnt(1)
	v_mfma_f32_16x16x32_bf16 v[102:105], v[210:213], v[234:237], v[102:105]
	v_mfma_f32_16x16x32_bf16 v[70:73], v[214:217], v[234:237], v[70:73]
	v_mfma_f32_16x16x32_bf16 v[38:41], v[218:221], v[234:237], v[38:41]
	v_mfma_f32_16x16x32_bf16 v[6:9], v[222:225], v[234:237], v[6:9]
	s_waitcnt lgkmcnt(0)
	v_mfma_f32_16x16x32_bf16 v[98:101], v[210:213], v[238:241], v[98:101]
	v_mfma_f32_16x16x32_bf16 v[66:69], v[214:217], v[238:241], v[66:69]
	v_mfma_f32_16x16x32_bf16 v[34:37], v[218:221], v[238:241], v[34:37]
	v_mfma_f32_16x16x32_bf16 v[2:5], v[222:225], v[238:241], v[2:5]
	s_add_i32 s42, s42, 1
	s_cmp_lg_u32 s42, 3
	s_cselect_b32 s42, s42, 0
	s_add_i32 s43, s43, 1
	s_cmp_lg_u32 s43, 3
	s_cselect_b32 s43, s43, 0
	s_setprio 0
	s_add_i32 s20, s20, 1
	s_cmp_lg_u32 s20, 32
	s_cbranch_scc1 .LBB0_607
	s_branch .LBB0_613

; template <int OFF> DEVI bf16x8 ldsr(unsigned a) { bf16x8 v; asm volatile("ds_read_b128 %0, %1 offset:%2" : "=v"(v) : "v"(a), "n"(OFF)); return v; }
; #define RAW_BARRIER() do { asm volatile("s_waitcnt lgkmcnt(0)" ::: "memory"); __builtin_amdgcn_s_barrier(); } while (0)
; template <int EPI, int NB>
; DEVI void gemm_tile(const GemmJob& J, int m0, int n0, unsigned char* smem) {
;     ...
;   for (int kt = 0; kt < nk; ++kt) {
;     if (nk - 1 - kt >= S - 2) {
;       if constexpr (NB == 8) asm volatile("s_waitcnt vmcnt(6)" ::: "memory");
;       else                   asm volatile("s_waitcnt vmcnt(8)" ::: "memory");
;     } else {
;       asm volatile("s_waitcnt vmcnt(0)" ::: "memory");
;     }
;     RAW_BARRIER();
;     if (kt + S - 1 < nk) GEMM_ISSUE(kt + S - 1, is);
;     is = (is + 1 == S) ? 0 : is + 1;
;     const unsigned cur = lbase + cs * STG;
;     cs = (cs + 1 == S) ? 0 : cs + 1;
;     bf16x8 af[4], bfr[NB];
;     const unsigned aa = cur + aofs, ba = cur + bofs;
;     af[0] = ldsr<0>(aa); af[1] = ldsr<1024>(aa); af[2] = ldsr<2048>(aa); af[3] = ldsr<3072>(aa);
;     bfr[0] = ldsr<0>(ba); bfr[1] = ldsr<1024>(ba); bfr[2] = ldsr<2048>(ba); bfr[3] = ldsr<3072>(ba);
;     __builtin_amdgcn_s_setprio(1);
; #pragma unroll
;     for (int nb = 0; nb < NB; ++nb) {
;       if (nb == 0) asm volatile("s_waitcnt lgkmcnt(3)" : "+v"(af[0]), "+v"(af[1]), "+v"(af[2]), "+v"(af[3]), "+v"(bfr[0]) :: "memory");
;       else if (nb <= NB - 4) asm volatile("s_waitcnt lgkmcnt(3)" : "+v"(bfr[nb]) :: "memory");
;       else if (nb == NB - 3) asm volatile("s_waitcnt lgkmcnt(2)" : "+v"(bfr[nb]) :: "memory");
;       else if (nb == NB - 2) asm volatile("s_waitcnt lgkmcnt(1)" : "+v"(bfr[nb]) :: "memory");
;       else asm volatile("s_waitcnt lgkmcnt(0)" : "+v"(bfr[nb]) :: "memory");
;       __builtin_amdgcn_sched_barrier(0);
; #pragma unroll
;       for (int mb = 0; mb < 4; ++mb) {
;         if constexpr (SWAP) acc[mb][nb] = __builtin_amdgcn_mfma_f32_16x16x32_bf16(bfr[nb], af[mb], acc[mb][nb], 0, 0, 0);
;         else                acc[mb][nb] = __builtin_amdgcn_mfma_f32_16x16x32_bf16(af[mb], bfr[nb], acc[mb][nb], 0, 0, 0);
;       }
.LBB0_696:
	s_mul_i32 s1, s43, 0x6000
	v_add_u32_e32 v211, s1, v209
	v_add_u32_e32 v244, s1, v210
	s_mul_i32 m0, s42, 0x6000
	s_add_u32 m0, m0, s0
	s_cmp_gt_u32 s2, 30
	s_cbranch_scc1 .Lgk6_w0
	s_waitcnt vmcnt(6)
.Lgk6_bar:
	s_waitcnt lgkmcnt(0)
	s_barrier
	s_setprio 1
	ds_read_b128 v[212:215], v211 offset:0
	ds_read_b128 v[228:231], v244 offset:0
	ds_read_b128 v[216:219], v211 offset:0x400
	ds_read_b128 v[220:223], v211 offset:0x800
	ds_read_b128 v[224:227], v211 offset:0xc00
	ds_read_b128 v[232:235], v244 offset:0x400
	ds_read_b128 v[236:239], v244 offset:0x800
	ds_read_b128 v[240:243], v244 offset:0xc00
	s_cmp_gt_u32 s2, 29
	s_cbranch_scc1 .Lgk6_tail
	s_waitcnt lgkmcnt(6)
	v_mfma_f32_16x16x32_bf16 v[126:129], v[228:231], v[212:215], v[126:129]
	s_waitcnt lgkmcnt(5)
	v_mfma_f32_16x16x32_bf16 v[94:97], v[228:231], v[216:219], v[94:97]
	s_waitcnt lgkmcnt(4)
	v_mfma_f32_16x16x32_bf16 v[62:65], v[228:231], v[220:223], v[62:65]
	s_waitcnt lgkmcnt(3)
	v_mfma_f32_16x16x32_bf16 v[30:33], v[228:231], v[224:227], v[30:33]
	ds_read_b128 v[228:231], v244 offset:0x1000
	global_load_lds_dwordx4 v182, s[100:101]
	s_add_u32 m0, m0, 0x1000
	s_waitcnt lgkmcnt(3)
	v_mfma_f32_16x16x32_bf16 v[122:125], v[232:235], v[212:215], v[122:125]
	v_mfma_f32_16x16x32_bf16 v[90:93], v[232:235], v[216:219], v[90:93]
	v_mfma_f32_16x16x32_bf16 v[58:61], v[232:235], v[220:223], v[58:61]
	v_mfma_f32_16x16x32_bf16 v[26:29], v[232:235], v[224:227], v[26:29]
	ds_read_b128 v[232:235], v244 offset:0x1400
	global_load_lds_dwordx4 v183, s[100:101]
	s_add_u32 m0, m0, 0x1000
	s_waitcnt lgkmcnt(3)
	v_mfma_f32_16x16x32_bf16 v[118:121], v[236:239], v[212:215], v[118:121]
	v_mfma_f32_16x16x32_bf16 v[86:89], v[236:239], v[216:219], v[86:89]
	v_mfma_f32_16x16x32_bf16 v[54:57], v[236:239], v[220:223], v[54:57]
	v_mfma_f32_16x16x32_bf16 v[22:25], v[236:239], v[224:227], v[22:25]
	ds_read_b128 v[236:239], v244 offset:0x1800
	global_load_lds_dwordx4 v180, vcc
	s_add_u32 m0, m0, 0x1000
	s_waitcnt lgkmcnt(3)
	v_mfma_f32_16x16x32_bf16 v[114:117], v[240:243], v[212:215], v[114:117]
	v_mfma_f32_16x16x32_bf16 v[82:85], v[240:243], v[216:219], v[82:85]
	v_mfma_f32_16x16x32_bf16 v[50:53], v[240:243], v[220:223], v[50:53]
	v_mfma_f32_16x16x32_bf16 v[18:21], v[240:243], v[224:227], v[18:21]
	ds_read_b128 v[240:243], v244 offset:0x1c00
	global_load_lds_dwordx4 v181, vcc
	s_add_u32 m0, m0, 0x1000
	s_waitcnt lgkmcnt(3)
	v_mfma_f32_16x16x32_bf16 v[110:113], v[228:231], v[212:215], v[110:113]
	v_mfma_f32_16x16x32_bf16 v[78:81], v[228:231], v[216:219], v[78:81]
	v_mfma_f32_16x16x32_bf16 v[46:49], v[228:231], v[220:223], v[46:49]
	v_mfma_f32_16x16x32_bf16 v[14:17], v[228:231], v[224:227], v[14:17]
	global_load_lds_dwordx4 v253, vcc
	s_add_u32 m0, m0, 0x1000
	s_waitcnt lgkmcnt(2)
	v_mfma_f32_16x16x32_bf16 v[106:109], v[232:235], v[212:215], v[106:109]
	v_mfma_f32_16x16x32_bf16 v[74:77], v[232:235], v[216:219], v[74:77]
	v_mfma_f32_16x16x32_bf16 v[42:45], v[232:235], v[220:223], v[42:45]
	v_mfma_f32_16x16x32_bf16 v[10:13], v[232:235], v[224:227], v[10:13]
	global_load_lds_dwordx4 v254, vcc
	s_waitcnt lgkmcnt(1)
	v_mfma_f32_16x16x32_bf16 v[102:105], v[236:239], v[212:215], v[102:105]
	v_mfma_f32_16x16x32_bf16 v[70:73], v[236:239], v[216:219], v[70:73]
	v_mfma_f32_16x16x32_bf16 v[38:41], v[236:239], v[220:223], v[38:41]
	v_mfma_f32_16x16x32_bf16 v[6:9], v[236:239], v[224:227], v[6:9]
	s_waitcnt lgkmcnt(0)
	v_mfma_f32_16x16x32_bf16 v[98:101], v[240:243], v[212:215], v[98:101]
	v_mfma_f32_16x16x32_bf16 v[66:69], v[240:243], v[216:219], v[66:69]
	v_mfma_f32_16x16x32_bf16 v[34:37], v[240:243], v[220:223], v[34:37]
	v_mfma_f32_16x16x32_bf16 v[2:5], v[240:243], v[224:227], v[2:5]
	s_add_u32 s100, s100, s94
	s_addc_u32 s101, s101, s95
	s_add_u32 vcc_lo, vcc_lo, s4
	s_addc_u32 vcc_hi, vcc_hi, s5
	s_add_i32 s42, s42, 1
	s_cmp_lg_u32 s42, 3
	s_cselect_b32 s42, s42, 0
	s_add_i32 s43, s43, 1
	s_cmp_lg_u32 s43, 3
	s_cselect_b32 s43, s43, 0
	s_setprio 0
	s_add_i32 s2, s2, 1
	s_branch .LBB0_696
.Lgk6_tail:
	s_waitcnt lgkmcnt(6)
	v_mfma_f32_16x16x32_bf16 v[126:129], v[228:231], v[212:215], v[126:129]
	s_waitcnt lgkmcnt(5)
	v_mfma_f32_16x16x32_bf16 v[94:97], v[228:231], v[216:219], v[94:97]
	s_waitcnt lgkmcnt(4)
	v_mfma_f32_16x16x32_bf16 v[62:65], v[228:231], v[220:223], v[62:65]
	s_waitcnt lgkmcnt(3)
	v_mfma_f32_16x16x32_bf16 v[30:33], v[228:231], v[224:227], v[30:33]
	ds_read_b128 v[228:231], v244 offset:0x1000
	s_waitcnt lgkmcnt(3)
	v_mfma_f32_16x16x32_bf16 v[122:125], v[232:235], v[212:215], v[122:125]
	v_mfma_f32_16x16x32_bf16 v[90:93], v[232:235], v[216:219], v[90:93]
	v_mfma_f32_16x16x32_bf16 v[58:61], v[232:235], v[220:223], v[58:61]
	v_mfma_f32_16x16x32_bf16 v[26:29], v[232:235], v[224:227], v[26:29]
	ds_read_b128 v[232:235], v244 offset:0x1400
	s_waitcnt lgkmcnt(3)
	v_mfma_f32_16x16x32_bf16 v[118:121], v[236:239], v[212:215], v[118:121]
	v_mfma_f32_16x16x32_bf16 v[86:89], v[236:239], v[216:219], v[86:89]
	v_mfma_f32_16x16x32_bf16 v[54:57], v[236:239], v[220:223], v[54:57]
	v_mfma_f32_16x16x32_bf16 v[22:25], v[236:239], v[224:227], v[22:25]
	ds_read_b128 v[236:239], v244 offset:0x1800
	s_waitcnt lgkmcnt(3)
	v_mfma_f32_16x16x32_bf16 v[114:117], v[240:243], v[212:215], v[114:117]
	v_mfma_f32_16x16x32_bf16 v[82:85], v[240:243], v[216:219], v[82:85]
	v_mfma_f32_16x16x32_bf16 v[50:53], v[240:243], v[220:223], v[50:53]
	v_mfma_f32_16x16x32_bf16 v[18:21], v[240:243], v[224:227], v[18:21]
	ds_read_b128 v[240:243], v244 offset:0x1c00
	s_waitcnt lgkmcnt(3)
	v_mfma_f32_16x16x32_bf16 v[110:113], v[228:231], v[212:215], v[110:113]
	v_mfma_f32_16x16x32_bf16 v[78:81], v[228:231], v[216:219], v[78:81]
	v_mfma_f32_16x16x32_bf16 v[46:49], v[228:231], v[220:223], v[46:49]
	v_mfma_f32_16x16x32_bf16 v[14:17], v[228:231], v[224:227], v[14:17]
	s_waitcnt lgkmcnt(2)
	v_mfma_f32_16x16x32_bf16 v[106:109], v[232:235], v[212:215], v[106:109]
	v_mfma_f32_16x16x32_bf16 v[74:77], v[232:235], v[216:219], v[74:77]
	v_mfma_f32_16x16x32_bf16 v[42:45], v[232:235], v[220:223], v[42:45]
	v_mfma_f32_16x16x32_bf16 v[10:13], v[232:235], v[224:227], v[10:13]
	s_waitcnt lgkmcnt(1)
	v_mfma_f32_16x16x32_bf16 v[102:105], v[236:239], v[212:215], v[102:105]
	v_mfma_f32_16x16x32_bf16 v[70:73], v[236:239], v[216:219], v[70:73]
	v_mfma_f32_16x16x32_bf16 v[38:41], v[236:239], v[220:223], v[38:41]
	v_mfma_f32_16x16x32_bf16 v[6:9], v[236:239], v[224:227], v[6:9]
	s_waitcnt lgkmcnt(0)
	v_mfma_f32_16x16x32_bf16 v[98:101], v[240:243], v[212:215], v[98:101]
	v_mfma_f32_16x16x32_bf16 v[66:69], v[240:243], v[216:219], v[66:69]
	v_mfma_f32_16x16x32_bf16 v[34:37], v[240:243], v[220:223], v[34:37]
	v_mfma_f32_16x16x32_bf16 v[2:5], v[240:243], v[224:227], v[2:5]
	s_add_i32 s42, s42, 1
	s_cmp_lg_u32 s42, 3
	s_cselect_b32 s42, s42, 0
	s_add_i32 s43, s43, 1
	s_cmp_lg_u32 s43, 3
	s_cselect_b32 s43, s43, 0
	s_setprio 0
	s_add_i32 s2, s2, 1
	s_cmp_lg_u32 s2, 32
	s_cbranch_scc1 .LBB0_696
	s_branch .LBB0_702

; template <int OFF> DEVI bf16x8 ldsr(unsigned a) { bf16x8 v; asm volatile("ds_read_b128 %0, %1 offset:%2" : "=v"(v) : "v"(a), "n"(OFF)); return v; }
; #define RAW_BARRIER() do { asm volatile("s_waitcnt lgkmcnt(0)" ::: "memory"); __builtin_amdgcn_s_barrier(); } while (0)
; template <int EPI, int NB>
; DEVI void gemm_tile(const GemmJob& J, int m0, int n0, unsigned char* smem) {
;     ...
;   for (int kt = 0; kt < nk; ++kt) {
;     if (nk - 1 - kt >= S - 2) {
;       if constexpr (NB == 8) asm volatile("s_waitcnt vmcnt(6)" ::: "memory");
;       else                   asm volatile("s_waitcnt vmcnt(8)" ::: "memory");
;     } else {
;       asm volatile("s_waitcnt vmcnt(0)" ::: "memory");
;     }
;     RAW_BARRIER();
;     if (kt + S - 1 < nk) GEMM_ISSUE(kt + S - 1, is);
;     is = (is + 1 == S) ? 0 : is + 1;
;     const unsigned cur = lbase + cs * STG;
;     cs = (cs + 1 == S) ? 0 : cs + 1;
;     bf16x8 af[4], bfr[NB];
;     const unsigned aa = cur + aofs, ba = cur + bofs;
;     af[0] = ldsr<0>(aa); af[1] = ldsr<1024>(aa); af[2] = ldsr<2048>(aa); af[3] = ldsr<3072>(aa);
;     bfr[0] = ldsr<0>(ba); bfr[1] = ldsr<1024>(ba); bfr[2] = ldsr<2048>(ba); bfr[3] = ldsr<3072>(ba);
;     __builtin_amdgcn_s_setprio(1);
; #pragma unroll
;     for (int nb = 0; nb < NB; ++nb) {
;       if (nb == 0) asm volatile("s_waitcnt lgkmcnt(3)" : "+v"(af[0]), "+v"(af[1]), "+v"(af[2]), "+v"(af[3]), "+v"(bfr[0]) :: "memory");
;       else if (nb <= NB - 4) asm volatile("s_waitcnt lgkmcnt(3)" : "+v"(bfr[nb]) :: "memory");
;       else if (nb == NB - 3) asm volatile("s_waitcnt lgkmcnt(2)" : "+v"(bfr[nb]) :: "memory");
;       else if (nb == NB - 2) asm volatile("s_waitcnt lgkmcnt(1)" : "+v"(bfr[nb]) :: "memory");
;       else asm volatile("s_waitcnt lgkmcnt(0)" : "+v"(bfr[nb]) :: "memory");
;       __builtin_amdgcn_sched_barrier(0);
; #pragma unroll
;       for (int mb = 0; mb < 4; ++mb) {
;         if constexpr (SWAP) acc[mb][nb] = __builtin_amdgcn_mfma_f32_16x16x32_bf16(bfr[nb], af[mb], acc[mb][nb], 0, 0, 0);
;         else                acc[mb][nb] = __builtin_amdgcn_mfma_f32_16x16x32_bf16(af[mb], bfr[nb], acc[mb][nb], 0, 0, 0);
.LBB0_774:
	s_mul_i32 s1, s43, 0x6000
	v_add_u32_e32 v222, s1, v208
	v_add_u32_e32 v242, s1, v209
	s_mul_i32 m0, s42, 0x6000
	s_add_u32 m0, m0, s0
	s_cmp_gt_u32 s3, 30
	s_cbranch_scc1 .Lgk7_w0
	s_waitcnt vmcnt(6)
.Lgk7_bar:
	s_waitcnt lgkmcnt(0)
	s_barrier
	s_setprio 1
	ds_read_b128 v[210:213], v222 offset:0
	ds_read_b128 v[226:229], v242 offset:0
	ds_read_b128 v[214:217], v222 offset:0x400
	ds_read_b128 v[218:221], v222 offset:0x800
	ds_read_b128 v[222:225], v222 offset:0xc00
	ds_read_b128 v[230:233], v242 offset:0x400
	ds_read_b128 v[234:237], v242 offset:0x800
	ds_read_b128 v[238:241], v242 offset:0xc00
	s_cmp_gt_u32 s3, 29
	s_cbranch_scc1 .Lgk7_tail
	s_waitcnt lgkmcnt(6)
	v_mfma_f32_16x16x32_bf16 v[126:129], v[210:213], v[226:229], v[126:129]
	s_waitcnt lgkmcnt(5)
	v_mfma_f32_16x16x32_bf16 v[94:97], v[214:217], v[226:229], v[94:97]
	s_waitcnt lgkmcnt(4)
	v_mfma_f32_16x16x32_bf16 v[62:65], v[218:221], v[226:229], v[62:65]
	s_waitcnt lgkmcnt(3)
	v_mfma_f32_16x16x32_bf16 v[30:33], v[222:225], v[226:229], v[30:33]
	ds_read_b128 v[226:229], v242 offset:0x1000
	global_load_lds_dwordx4 v182, s[100:101]
	s_add_u32 m0, m0, 0x1000
	s_waitcnt lgkmcnt(3)
	v_mfma_f32_16x16x32_bf16 v[122:125], v[210:213], v[230:233], v[122:125]
	v_mfma_f32_16x16x32_bf16 v[90:93], v[214:217], v[230:233], v[90:93]
	v_mfma_f32_16x16x32_bf16 v[58:61], v[218:221], v[230:233], v[58:61]
	v_mfma_f32_16x16x32_bf16 v[26:29], v[222:225], v[230:233], v[26:29]
	ds_read_b128 v[230:233], v242 offset:0x1400
	global_load_lds_dwordx4 v183, s[100:101]
	s_add_u32 m0, m0, 0x1000
	s_waitcnt lgkmcnt(3)
	v_mfma_f32_16x16x32_bf16 v[118:121], v[210:213], v[234:237], v[118:121]
	v_mfma_f32_16x16x32_bf16 v[86:89], v[214:217], v[234:237], v[86:89]
	v_mfma_f32_16x16x32_bf16 v[54:57], v[218:221], v[234:237], v[54:57]
	v_mfma_f32_16x16x32_bf16 v[22:25], v[222:225], v[234:237], v[22:25]
	ds_read_b128 v[234:237], v242 offset:0x1800
	global_load_lds_dwordx4 v180, vcc
	s_add_u32 m0, m0, 0x1000
	s_waitcnt lgkmcnt(3)
	v_mfma_f32_16x16x32_bf16 v[114:117], v[210:213], v[238:241], v[114:117]
	v_mfma_f32_16x16x32_bf16 v[82:85], v[214:217], v[238:241], v[82:85]
	v_mfma_f32_16x16x32_bf16 v[50:53], v[218:221], v[238:241], v[50:53]
	v_mfma_f32_16x16x32_bf16 v[18:21], v[222:225], v[238:241], v[18:21]
	ds_read_b128 v[238:241], v242 offset:0x1c00
	global_load_lds_dwordx4 v181, vcc
	s_add_u32 m0, m0, 0x1000
	s_waitcnt lgkmcnt(3)
	v_mfma_f32_16x16x32_bf16 v[110:113], v[210:213], v[226:229], v[110:113]
	v_mfma_f32_16x16x32_bf16 v[78:81], v[214:217], v[226:229], v[78:81]
	v_mfma_f32_16x16x32_bf16 v[46:49], v[218:221], v[226:229], v[46:49]
	v_mfma_f32_16x16x32_bf16 v[14:17], v[222:225], v[226:229], v[14:17]
	global_load_lds_dwordx4 v253, vcc
	s_add_u32 m0, m0, 0x1000
	s_waitcnt lgkmcnt(2)
	v_mfma_f32_16x16x32_bf16 v[106:109], v[210:213], v[230:233], v[106:109]
	v_mfma_f32_16x16x32_bf16 v[74:77], v[214:217], v[230:233], v[74:77]
	v_mfma_f32_16x16x32_bf16 v[42:45], v[218:221], v[230:233], v[42:45]
	v_mfma_f32_16x16x32_bf16 v[10:13], v[222:225], v[230:233], v[10:13]
	global_load_lds_dwordx4 v254, vcc
	s_waitcnt lgkmcnt(1)
	v_mfma_f32_16x16x32_bf16 v[102:105], v[210:213], v[234:237], v[102:105]
	v_mfma_f32_16x16x32_bf16 v[70:73], v[214:217], v[234:237], v[70:73]
	v_mfma_f32_16x16x32_bf16 v[38:41], v[218:221], v[234:237], v[38:41]
	v_mfma_f32_16x16x32_bf16 v[6:9], v[222:225], v[234:237], v[6:9]
	s_waitcnt lgkmcnt(0)
	v_mfma_f32_16x16x32_bf16 v[98:101], v[210:213], v[238:241], v[98:101]
	v_mfma_f32_16x16x32_bf16 v[66:69], v[214:217], v[238:241], v[66:69]
	v_mfma_f32_16x16x32_bf16 v[34:37], v[218:221], v[238:241], v[34:37]
	v_mfma_f32_16x16x32_bf16 v[2:5], v[222:225], v[238:241], v[2:5]
	s_add_u32 s100, s100, s94
	s_addc_u32 s101, s101, s95
	s_add_u32 vcc_lo, vcc_lo, s4
	s_addc_u32 vcc_hi, vcc_hi, s5
	s_add_i32 s42, s42, 1
	s_cmp_lg_u32 s42, 3
	s_cselect_b32 s42, s42, 0
	s_add_i32 s43, s43, 1
	s_cmp_lg_u32 s43, 3
	s_cselect_b32 s43, s43, 0
	s_setprio 0
	s_add_i32 s3, s3, 1
	s_branch .LBB0_774
.Lgk7_tail:
	s_waitcnt lgkmcnt(6)
	v_mfma_f32_16x16x32_bf16 v[126:129], v[210:213], v[226:229], v[126:129]
	s_waitcnt lgkmcnt(5)
	v_mfma_f32_16x16x32_bf16 v[94:97], v[214:217], v[226:229], v[94:97]
	s_waitcnt lgkmcnt(4)
	v_mfma_f32_16x16x32_bf16 v[62:65], v[218:221], v[226:229], v[62:65]
	s_waitcnt lgkmcnt(3)
	v_mfma_f32_16x16x32_bf16 v[30:33], v[222:225], v[226:229], v[30:33]
	ds_read_b128 v[226:229], v242 offset:0x1000
	s_waitcnt lgkmcnt(3)
	v_mfma_f32_16x16x32_bf16 v[122:125], v[210:213], v[230:233], v[122:125]
	v_mfma_f32_16x16x32_bf16 v[90:93], v[214:217], v[230:233], v[90:93]
	v_mfma_f32_16x16x32_bf16 v[58:61], v[218:221], v[230:233], v[58:61]
	v_mfma_f32_16x16x32_bf16 v[26:29], v[222:225], v[230:233], v[26:29]
	ds_read_b128 v[230:233], v242 offset:0x1400
	s_waitcnt lgkmcnt(3)
	v_mfma_f32_16x16x32_bf16 v[118:121], v[210:213], v[234:237], v[118:121]
	v_mfma_f32_16x16x32_bf16 v[86:89], v[214:217], v[234:237], v[86:89]
	v_mfma_f32_16x16x32_bf16 v[54:57], v[218:221], v[234:237], v[54:57]
	v_mfma_f32_16x16x32_bf16 v[22:25], v[222:225], v[234:237], v[22:25]
	ds_read_b128 v[234:237], v242 offset:0x1800
	s_waitcnt lgkmcnt(3)
	v_mfma_f32_16x16x32_bf16 v[114:117], v[210:213], v[238:241], v[114:117]
	v_mfma_f32_16x16x32_bf16 v[82:85], v[214:217], v[238:241], v[82:85]
	v_mfma_f32_16x16x32_bf16 v[50:53], v[218:221], v[238:241], v[50:53]
	v_mfma_f32_16x16x32_bf16 v[18:21], v[222:225], v[238:241], v[18:21]
	ds_read_b128 v[238:241], v242 offset:0x1c00
	s_waitcnt lgkmcnt(3)
	v_mfma_f32_16x16x32_bf16 v[110:113], v[210:213], v[226:229], v[110:113]
	v_mfma_f32_16x16x32_bf16 v[78:81], v[214:217], v[226:229], v[78:81]
	v_mfma_f32_16x16x32_bf16 v[46:49], v[218:221], v[226:229], v[46:49]
	v_mfma_f32_16x16x32_bf16 v[14:17], v[222:225], v[226:229], v[14:17]
	s_waitcnt lgkmcnt(2)
	v_mfma_f32_16x16x32_bf16 v[106:109], v[210:213], v[230:233], v[106:109]
	v_mfma_f32_16x16x32_bf16 v[74:77], v[214:217], v[230:233], v[74:77]
	v_mfma_f32_16x16x32_bf16 v[42:45], v[218:221], v[230:233], v[42:45]
	v_mfma_f32_16x16x32_bf16 v[10:13], v[222:225], v[230:233], v[10:13]
	s_waitcnt lgkmcnt(1)
	v_mfma_f32_16x16x32_bf16 v[102:105], v[210:213], v[234:237], v[102:105]
	v_mfma_f32_16x16x32_bf16 v[70:73], v[214:217], v[234:237], v[70:73]
	v_mfma_f32_16x16x32_bf16 v[38:41], v[218:221], v[234:237], v[38:41]
	v_mfma_f32_16x16x32_bf16 v[6:9], v[222:225], v[234:237], v[6:9]
	s_waitcnt lgkmcnt(0)
	v_mfma_f32_16x16x32_bf16 v[98:101], v[210:213], v[238:241], v[98:101]
	v_mfma_f32_16x16x32_bf16 v[66:69], v[214:217], v[238:241], v[66:69]
	v_mfma_f32_16x16x32_bf16 v[34:37], v[218:221], v[238:241], v[34:37]
	v_mfma_f32_16x16x32_bf16 v[2:5], v[222:225], v[238:241], v[2:5]
	s_add_i32 s42, s42, 1
	s_cmp_lg_u32 s42, 3
	s_cselect_b32 s42, s42, 0
	s_add_i32 s43, s43, 1
	s_cmp_lg_u32 s43, 3
	s_cselect_b32 s43, s43, 0
	s_setprio 0
	s_add_i32 s3, s3, 1
	s_cmp_lg_u32 s3, 32
	s_cbranch_scc1 .LBB0_774
	s_branch .LBB0_780

; template <int OFF> DEVI bf16x8 ldsr(unsigned a) { bf16x8 v; asm volatile("ds_read_b128 %0, %1 offset:%2" : "=v"(v) : "v"(a), "n"(OFF)); return v; }
; #define RAW_BARRIER() do { asm volatile("s_waitcnt lgkmcnt(0)" ::: "memory"); __builtin_amdgcn_s_barrier(); } while (0)
; template <int EPI, int NB>
; DEVI void gemm_tile(const GemmJob& J, int m0, int n0, unsigned char* smem) {
;     ...
;     RAW_BARRIER();
;     if (kt + S - 1 < nk) GEMM_ISSUE(kt + S - 1, is);
;     is = (is + 1 == S) ? 0 : is + 1;
;     const unsigned cur = lbase + cs * STG;
;     cs = (cs + 1 == S) ? 0 : cs + 1;
;     bf16x8 af[4], bfr[NB];
;     const unsigned aa = cur + aofs, ba = cur + bofs;
;     af[0] = ldsr<0>(aa); af[1] = ldsr<1024>(aa); af[2] = ldsr<2048>(aa); af[3] = ldsr<3072>(aa);
;     bfr[0] = ldsr<0>(ba); bfr[1] = ldsr<1024>(ba); bfr[2] = ldsr<2048>(ba); bfr[3] = ldsr<3072>(ba);
;     __builtin_amdgcn_s_setprio(1);
; #pragma unroll
;     for (int nb = 0; nb < NB; ++nb) {
;       if (nb == 0) asm volatile("s_waitcnt lgkmcnt(3)" : "+v"(af[0]), "+v"(af[1]), "+v"(af[2]), "+v"(af[3]), "+v"(bfr[0]) :: "memory");
;       else if (nb <= NB - 4) asm volatile("s_waitcnt lgkmcnt(3)" : "+v"(bfr[nb]) :: "memory");
;       else if (nb == NB - 3) asm volatile("s_waitcnt lgkmcnt(2)" : "+v"(bfr[nb]) :: "memory");
;       else if (nb == NB - 2) asm volatile("s_waitcnt lgkmcnt(1)" : "+v"(bfr[nb]) :: "memory");
;       else asm volatile("s_waitcnt lgkmcnt(0)" : "+v"(bfr[nb]) :: "memory");
;       __builtin_amdgcn_sched_barrier(0);
; #pragma unroll
;       for (int mb = 0; mb < 4; ++mb) {
;         if constexpr (SWAP) acc[mb][nb] = __builtin_amdgcn_mfma_f32_16x16x32_bf16(bfr[nb], af[mb], acc[mb][nb], 0, 0, 0);
;         else                acc[mb][nb] = __builtin_amdgcn_mfma_f32_16x16x32_bf16(af[mb], bfr[nb], acc[mb][nb], 0, 0, 0);
;       }
.Lgk8_bar:
	s_waitcnt lgkmcnt(0)
	s_barrier
	s_setprio 1
	ds_read_b128 v[212:215], v211 offset:0
	ds_read_b128 v[228:231], v244 offset:0
	ds_read_b128 v[216:219], v211 offset:0x400
	ds_read_b128 v[220:223], v211 offset:0x800
	ds_read_b128 v[224:227], v211 offset:0xc00
	ds_read_b128 v[232:235], v244 offset:0x400
	ds_read_b128 v[236:239], v244 offset:0x800
	ds_read_b128 v[240:243], v244 offset:0xc00
	s_cmp_gt_u32 s20, 29
	s_cbranch_scc1 .Lgk8_tail
	s_waitcnt lgkmcnt(6)
	v_mfma_f32_16x16x32_bf16 v[126:129], v[228:231], v[212:215], v[126:129]
	s_waitcnt lgkmcnt(5)
	v_mfma_f32_16x16x32_bf16 v[94:97], v[228:231], v[216:219], v[94:97]
	s_waitcnt lgkmcnt(4)
	v_mfma_f32_16x16x32_bf16 v[62:65], v[228:231], v[220:223], v[62:65]
	s_waitcnt lgkmcnt(3)
	v_mfma_f32_16x16x32_bf16 v[30:33], v[228:231], v[224:227], v[30:33]
	ds_read_b128 v[228:231], v244 offset:0x1000
	global_load_lds_dwordx4 v182, s[100:101]
	s_add_u32 m0, m0, 0x1000
	s_waitcnt lgkmcnt(3)
	v_mfma_f32_16x16x32_bf16 v[122:125], v[232:235], v[212:215], v[122:125]
	v_mfma_f32_16x16x32_bf16 v[90:93], v[232:235], v[216:219], v[90:93]
	v_mfma_f32_16x16x32_bf16 v[58:61], v[232:235], v[220:223], v[58:61]
	v_mfma_f32_16x16x32_bf16 v[26:29], v[232:235], v[224:227], v[26:29]
	ds_read_b128 v[232:235], v244 offset:0x1400
	global_load_lds_dwordx4 v183, s[100:101]
	s_add_u32 m0, m0, 0x1000
	s_waitcnt lgkmcnt(3)
	v_mfma_f32_16x16x32_bf16 v[118:121], v[236:239], v[212:215], v[118:121]
	v_mfma_f32_16x16x32_bf16 v[86:89], v[236:239], v[216:219], v[86:89]
	v_mfma_f32_16x16x32_bf16 v[54:57], v[236:239], v[220:223], v[54:57]
	v_mfma_f32_16x16x32_bf16 v[22:25], v[236:239], v[224:227], v[22:25]
	ds_read_b128 v[236:239], v244 offset:0x1800
	global_load_lds_dwordx4 v180, vcc
	s_add_u32 m0, m0, 0x1000
	s_waitcnt lgkmcnt(3)
	v_mfma_f32_16x16x32_bf16 v[114:117], v[240:243], v[212:215], v[114:117]
	v_mfma_f32_16x16x32_bf16 v[82:85], v[240:243], v[216:219], v[82:85]
	v_mfma_f32_16x16x32_bf16 v[50:53], v[240:243], v[220:223], v[50:53]
	v_mfma_f32_16x16x32_bf16 v[18:21], v[240:243], v[224:227], v[18:21]
	ds_read_b128 v[240:243], v244 offset:0x1c00
	global_load_lds_dwordx4 v181, vcc
	s_add_u32 m0, m0, 0x1000
	s_waitcnt lgkmcnt(3)
	v_mfma_f32_16x16x32_bf16 v[110:113], v[228:231], v[212:215], v[110:113]
	v_mfma_f32_16x16x32_bf16 v[78:81], v[228:231], v[216:219], v[78:81]
	v_mfma_f32_16x16x32_bf16 v[46:49], v[228:231], v[220:223], v[46:49]
	v_mfma_f32_16x16x32_bf16 v[14:17], v[228:231], v[224:227], v[14:17]
	global_load_lds_dwordx4 v253, vcc
	s_add_u32 m0, m0, 0x1000
	s_waitcnt lgkmcnt(2)
	v_mfma_f32_16x16x32_bf16 v[106:109], v[232:235], v[212:215], v[106:109]
	v_mfma_f32_16x16x32_bf16 v[74:77], v[232:235], v[216:219], v[74:77]
	v_mfma_f32_16x16x32_bf16 v[42:45], v[232:235], v[220:223], v[42:45]
	v_mfma_f32_16x16x32_bf16 v[10:13], v[232:235], v[224:227], v[10:13]
	global_load_lds_dwordx4 v254, vcc
	s_waitcnt lgkmcnt(1)
	v_mfma_f32_16x16x32_bf16 v[102:105], v[236:239], v[212:215], v[102:105]
	v_mfma_f32_16x16x32_bf16 v[70:73], v[236:239], v[216:219], v[70:73]
	v_mfma_f32_16x16x32_bf16 v[38:41], v[236:239], v[220:223], v[38:41]
	v_mfma_f32_16x16x32_bf16 v[6:9], v[236:239], v[224:227], v[6:9]
	s_waitcnt lgkmcnt(0)
	v_mfma_f32_16x16x32_bf16 v[98:101], v[240:243], v[212:215], v[98:101]
	v_mfma_f32_16x16x32_bf16 v[66:69], v[240:243], v[216:219], v[66:69]
	v_mfma_f32_16x16x32_bf16 v[34:37], v[240:243], v[220:223], v[34:37]
	v_mfma_f32_16x16x32_bf16 v[2:5], v[240:243], v[224:227], v[2:5]
	s_add_u32 s100, s100, s94
	s_addc_u32 s101, s101, s95
	s_add_u32 vcc_lo, vcc_lo, s22
	s_addc_u32 vcc_hi, vcc_hi, s23
	s_add_i32 s42, s42, 1
	s_cmp_lg_u32 s42, 3
	s_cselect_b32 s42, s42, 0
	s_add_i32 s43, s43, 1
	s_cmp_lg_u32 s43, 3
	s_cselect_b32 s43, s43, 0
	s_setprio 0
	s_add_i32 s20, s20, 1
	s_branch .LBB0_1012

; template <int OFF> DEVI bf16x8 ldsr(unsigned a) { bf16x8 v; asm volatile("ds_read_b128 %0, %1 offset:%2" : "=v"(v) : "v"(a), "n"(OFF)); return v; }
; #define RAW_BARRIER() do { asm volatile("s_waitcnt lgkmcnt(0)" ::: "memory"); __builtin_amdgcn_s_barrier(); } while (0)
; template <int EPI, int NB>
; DEVI void gemm_tile(const GemmJob& J, int m0, int n0, unsigned char* smem) {
;     ...
;     RAW_BARRIER();
;     if (kt + S - 1 < nk) GEMM_ISSUE(kt + S - 1, is);
;     is = (is + 1 == S) ? 0 : is + 1;
;     const unsigned cur = lbase + cs * STG;
;     cs = (cs + 1 == S) ? 0 : cs + 1;
;     bf16x8 af[4], bfr[NB];
;     const unsigned aa = cur + aofs, ba = cur + bofs;
;     af[0] = ldsr<0>(aa); af[1] = ldsr<1024>(aa); af[2] = ldsr<2048>(aa); af[3] = ldsr<3072>(aa);
;     bfr[0] = ldsr<0>(ba); bfr[1] = ldsr<1024>(ba); bfr[2] = ldsr<2048>(ba); bfr[3] = ldsr<3072>(ba);
;     __builtin_amdgcn_s_setprio(1);
; #pragma unroll
;     for (int nb = 0; nb < NB; ++nb) {
;       if (nb == 0) asm volatile("s_waitcnt lgkmcnt(3)" : "+v"(af[0]), "+v"(af[1]), "+v"(af[2]), "+v"(af[3]), "+v"(bfr[0]) :: "memory");
;       else if (nb <= NB - 4) asm volatile("s_waitcnt lgkmcnt(3)" : "+v"(bfr[nb]) :: "memory");
;       else if (nb == NB - 3) asm volatile("s_waitcnt lgkmcnt(2)" : "+v"(bfr[nb]) :: "memory");
;       else if (nb == NB - 2) asm volatile("s_waitcnt lgkmcnt(1)" : "+v"(bfr[nb]) :: "memory");
;       else asm volatile("s_waitcnt lgkmcnt(0)" : "+v"(bfr[nb]) :: "memory");
;       __builtin_amdgcn_sched_barrier(0);
; #pragma unroll
;       for (int mb = 0; mb < 4; ++mb) {
;         if constexpr (SWAP) acc[mb][nb] = __builtin_amdgcn_mfma_f32_16x16x32_bf16(bfr[nb], af[mb], acc[mb][nb], 0, 0, 0);
;         else                acc[mb][nb] = __builtin_amdgcn_mfma_f32_16x16x32_bf16(af[mb], bfr[nb], acc[mb][nb], 0, 0, 0);
;       }
.Lgk9_bar:
	s_waitcnt lgkmcnt(0)
	s_barrier
	s_setprio 1
	ds_read_b128 v[212:215], v211 offset:0
	ds_read_b128 v[228:231], v244 offset:0
	ds_read_b128 v[216:219], v211 offset:0x400
	ds_read_b128 v[220:223], v211 offset:0x800
	ds_read_b128 v[224:227], v211 offset:0xc00
	ds_read_b128 v[232:235], v244 offset:0x400
	ds_read_b128 v[236:239], v244 offset:0x800
	ds_read_b128 v[240:243], v244 offset:0xc00
	s_cmp_gt_u32 s2, 29
	s_cbranch_scc1 .Lgk9_tail
	s_waitcnt lgkmcnt(6)
	v_mfma_f32_16x16x32_bf16 v[126:129], v[228:231], v[212:215], v[126:129]
	s_waitcnt lgkmcnt(5)
	v_mfma_f32_16x16x32_bf16 v[94:97], v[228:231], v[216:219], v[94:97]
	s_waitcnt lgkmcnt(4)
	v_mfma_f32_16x16x32_bf16 v[62:65], v[228:231], v[220:223], v[62:65]
	s_waitcnt lgkmcnt(3)
	v_mfma_f32_16x16x32_bf16 v[30:33], v[228:231], v[224:227], v[30:33]
	ds_read_b128 v[228:231], v244 offset:0x1000
	global_load_lds_dwordx4 v182, s[100:101]
	s_add_u32 m0, m0, 0x1000
	s_waitcnt lgkmcnt(3)
	v_mfma_f32_16x16x32_bf16 v[122:125], v[232:235], v[212:215], v[122:125]
	v_mfma_f32_16x16x32_bf16 v[90:93], v[232:235], v[216:219], v[90:93]
	v_mfma_f32_16x16x32_bf16 v[58:61], v[232:235], v[220:223], v[58:61]
	v_mfma_f32_16x16x32_bf16 v[26:29], v[232:235], v[224:227], v[26:29]
	ds_read_b128 v[232:235], v244 offset:0x1400
	global_load_lds_dwordx4 v183, s[100:101]
	s_add_u32 m0, m0, 0x1000
	s_waitcnt lgkmcnt(3)
	v_mfma_f32_16x16x32_bf16 v[118:121], v[236:239], v[212:215], v[118:121]
	v_mfma_f32_16x16x32_bf16 v[86:89], v[236:239], v[216:219], v[86:89]
	v_mfma_f32_16x16x32_bf16 v[54:57], v[236:239], v[220:223], v[54:57]
	v_mfma_f32_16x16x32_bf16 v[22:25], v[236:239], v[224:227], v[22:25]
	ds_read_b128 v[236:239], v244 offset:0x1800
	global_load_lds_dwordx4 v180, vcc
	s_add_u32 m0, m0, 0x1000
	s_waitcnt lgkmcnt(3)
	v_mfma_f32_16x16x32_bf16 v[114:117], v[240:243], v[212:215], v[114:117]
	v_mfma_f32_16x16x32_bf16 v[82:85], v[240:243], v[216:219], v[82:85]
	v_mfma_f32_16x16x32_bf16 v[50:53], v[240:243], v[220:223], v[50:53]
	v_mfma_f32_16x16x32_bf16 v[18:21], v[240:243], v[224:227], v[18:21]
	ds_read_b128 v[240:243], v244 offset:0x1c00
	global_load_lds_dwordx4 v181, vcc
	s_add_u32 m0, m0, 0x1000
	s_waitcnt lgkmcnt(3)
	v_mfma_f32_16x16x32_bf16 v[110:113], v[228:231], v[212:215], v[110:113]
	v_mfma_f32_16x16x32_bf16 v[78:81], v[228:231], v[216:219], v[78:81]
	v_mfma_f32_16x16x32_bf16 v[46:49], v[228:231], v[220:223], v[46:49]
	v_mfma_f32_16x16x32_bf16 v[14:17], v[228:231], v[224:227], v[14:17]
	global_load_lds_dwordx4 v253, vcc
	s_add_u32 m0, m0, 0x1000
	s_waitcnt lgkmcnt(2)
	v_mfma_f32_16x16x32_bf16 v[106:109], v[232:235], v[212:215], v[106:109]
	v_mfma_f32_16x16x32_bf16 v[74:77], v[232:235], v[216:219], v[74:77]
	v_mfma_f32_16x16x32_bf16 v[42:45], v[232:235], v[220:223], v[42:45]
	v_mfma_f32_16x16x32_bf16 v[10:13], v[232:235], v[224:227], v[10:13]
	global_load_lds_dwordx4 v254, vcc
	s_waitcnt lgkmcnt(1)
	v_mfma_f32_16x16x32_bf16 v[102:105], v[236:239], v[212:215], v[102:105]
	v_mfma_f32_16x16x32_bf16 v[70:73], v[236:239], v[216:219], v[70:73]
	v_mfma_f32_16x16x32_bf16 v[38:41], v[236:239], v[220:223], v[38:41]
	v_mfma_f32_16x16x32_bf16 v[6:9], v[236:239], v[224:227], v[6:9]
	s_waitcnt lgkmcnt(0)
	v_mfma_f32_16x16x32_bf16 v[98:101], v[240:243], v[212:215], v[98:101]
	v_mfma_f32_16x16x32_bf16 v[66:69], v[240:243], v[216:219], v[66:69]
	v_mfma_f32_16x16x32_bf16 v[34:37], v[240:243], v[220:223], v[34:37]
	v_mfma_f32_16x16x32_bf16 v[2:5], v[240:243], v[224:227], v[2:5]
	s_add_u32 s100, s100, s94
	s_addc_u32 s101, s101, s95
	s_add_u32 vcc_lo, vcc_lo, s22
	s_addc_u32 vcc_hi, vcc_hi, s23
	s_add_i32 s42, s42, 1
	s_cmp_lg_u32 s42, 3
	s_cselect_b32 s42, s42, 0
	s_add_i32 s43, s43, 1
	s_cmp_lg_u32 s43, 3
	s_cselect_b32 s43, s43, 0
	s_setprio 0
	s_add_i32 s2, s2, 1
	s_branch .LBB0_1090

; template <int OFF> DEVI bf16x8 ldsr(unsigned a) { bf16x8 v; asm volatile("ds_read_b128 %0, %1 offset:%2" : "=v"(v) : "v"(a), "n"(OFF)); return v; }
; #define RAW_BARRIER() do { asm volatile("s_waitcnt lgkmcnt(0)" ::: "memory"); __builtin_amdgcn_s_barrier(); } while (0)
; template <int EPI, int NB>
; DEVI void gemm_tile(const GemmJob& J, int m0, int n0, unsigned char* smem) {
;     ...
;     RAW_BARRIER();
;     if (kt + S - 1 < nk) GEMM_ISSUE(kt + S - 1, is);
;     is = (is + 1 == S) ? 0 : is + 1;
;     const unsigned cur = lbase + cs * STG;
;     cs = (cs + 1 == S) ? 0 : cs + 1;
;     bf16x8 af[4], bfr[NB];
;     const unsigned aa = cur + aofs, ba = cur + bofs;
;     af[0] = ldsr<0>(aa); af[1] = ldsr<1024>(aa); af[2] = ldsr<2048>(aa); af[3] = ldsr<3072>(aa);
;     bfr[0] = ldsr<0>(ba); bfr[1] = ldsr<1024>(ba); bfr[2] = ldsr<2048>(ba); bfr[3] = ldsr<3072>(ba);
;     __builtin_amdgcn_s_setprio(1);
; #pragma unroll
;     for (int nb = 0; nb < NB; ++nb) {
;       if (nb == 0) asm volatile("s_waitcnt lgkmcnt(3)" : "+v"(af[0]), "+v"(af[1]), "+v"(af[2]), "+v"(af[3]), "+v"(bfr[0]) :: "memory");
;       else if (nb <= NB - 4) asm volatile("s_waitcnt lgkmcnt(3)" : "+v"(bfr[nb]) :: "memory");
;       else if (nb == NB - 3) asm volatile("s_waitcnt lgkmcnt(2)" : "+v"(bfr[nb]) :: "memory");
;       else if (nb == NB - 2) asm volatile("s_waitcnt lgkmcnt(1)" : "+v"(bfr[nb]) :: "memory");
;       else asm volatile("s_waitcnt lgkmcnt(0)" : "+v"(bfr[nb]) :: "memory");
;       __builtin_amdgcn_sched_barrier(0);
; #pragma unroll
;       for (int mb = 0; mb < 4; ++mb) {
;         if constexpr (SWAP) acc[mb][nb] = __builtin_amdgcn_mfma_f32_16x16x32_bf16(bfr[nb], af[mb], acc[mb][nb], 0, 0, 0);
;         else                acc[mb][nb] = __builtin_amdgcn_mfma_f32_16x16x32_bf16(af[mb], bfr[nb], acc[mb][nb], 0, 0, 0);
;       }
.Lgk10_bar:
	s_waitcnt lgkmcnt(0)
	s_barrier
	s_setprio 1
	ds_read_b128 v[212:215], v211 offset:0
	ds_read_b128 v[228:231], v244 offset:0
	ds_read_b128 v[216:219], v211 offset:0x400
	ds_read_b128 v[220:223], v211 offset:0x800
	ds_read_b128 v[224:227], v211 offset:0xc00
	ds_read_b128 v[232:235], v244 offset:0x400
	ds_read_b128 v[236:239], v244 offset:0x800
	ds_read_b128 v[240:243], v244 offset:0xc00
	s_cmp_gt_u32 s20, 29
	s_cbranch_scc1 .Lgk10_tail
	s_waitcnt lgkmcnt(6)
	v_mfma_f32_16x16x32_bf16 v[126:129], v[228:231], v[212:215], v[126:129]
	s_waitcnt lgkmcnt(5)
	v_mfma_f32_16x16x32_bf16 v[94:97], v[228:231], v[216:219], v[94:97]
	s_waitcnt lgkmcnt(4)
	v_mfma_f32_16x16x32_bf16 v[62:65], v[228:231], v[220:223], v[62:65]
	s_waitcnt lgkmcnt(3)
	v_mfma_f32_16x16x32_bf16 v[30:33], v[228:231], v[224:227], v[30:33]
	ds_read_b128 v[228:231], v244 offset:0x1000
	global_load_lds_dwordx4 v182, s[100:101]
	s_add_u32 m0, m0, 0x1000
	s_waitcnt lgkmcnt(3)
	v_mfma_f32_16x16x32_bf16 v[122:125], v[232:235], v[212:215], v[122:125]
	v_mfma_f32_16x16x32_bf16 v[90:93], v[232:235], v[216:219], v[90:93]
	v_mfma_f32_16x16x32_bf16 v[58:61], v[232:235], v[220:223], v[58:61]
	v_mfma_f32_16x16x32_bf16 v[26:29], v[232:235], v[224:227], v[26:29]
	ds_read_b128 v[232:235], v244 offset:0x1400
	global_load_lds_dwordx4 v183, s[100:101]
	s_add_u32 m0, m0, 0x1000
	s_waitcnt lgkmcnt(3)
	v_mfma_f32_16x16x32_bf16 v[118:121], v[236:239], v[212:215], v[118:121]
	v_mfma_f32_16x16x32_bf16 v[86:89], v[236:239], v[216:219], v[86:89]
	v_mfma_f32_16x16x32_bf16 v[54:57], v[236:239], v[220:223], v[54:57]
	v_mfma_f32_16x16x32_bf16 v[22:25], v[236:239], v[224:227], v[22:25]
	ds_read_b128 v[236:239], v244 offset:0x1800
	global_load_lds_dwordx4 v180, vcc
	s_add_u32 m0, m0, 0x1000
	s_waitcnt lgkmcnt(3)
	v_mfma_f32_16x16x32_bf16 v[114:117], v[240:243], v[212:215], v[114:117]
	v_mfma_f32_16x16x32_bf16 v[82:85], v[240:243], v[216:219], v[82:85]
	v_mfma_f32_16x16x32_bf16 v[50:53], v[240:243], v[220:223], v[50:53]
	v_mfma_f32_16x16x32_bf16 v[18:21], v[240:243], v[224:227], v[18:21]
	ds_read_b128 v[240:243], v244 offset:0x1c00
	global_load_lds_dwordx4 v181, vcc
	s_add_u32 m0, m0, 0x1000
	s_waitcnt lgkmcnt(3)
	v_mfma_f32_16x16x32_bf16 v[110:113], v[228:231], v[212:215], v[110:113]
	v_mfma_f32_16x16x32_bf16 v[78:81], v[228:231], v[216:219], v[78:81]
	v_mfma_f32_16x16x32_bf16 v[46:49], v[228:231], v[220:223], v[46:49]
	v_mfma_f32_16x16x32_bf16 v[14:17], v[228:231], v[224:227], v[14:17]
	global_load_lds_dwordx4 v253, vcc
	s_add_u32 m0, m0, 0x1000
	s_waitcnt lgkmcnt(2)
	v_mfma_f32_16x16x32_bf16 v[106:109], v[232:235], v[212:215], v[106:109]
	v_mfma_f32_16x16x32_bf16 v[74:77], v[232:235], v[216:219], v[74:77]
	v_mfma_f32_16x16x32_bf16 v[42:45], v[232:235], v[220:223], v[42:45]
	v_mfma_f32_16x16x32_bf16 v[10:13], v[232:235], v[224:227], v[10:13]
	global_load_lds_dwordx4 v254, vcc
	s_waitcnt lgkmcnt(1)
	v_mfma_f32_16x16x32_bf16 v[102:105], v[236:239], v[212:215], v[102:105]
	v_mfma_f32_16x16x32_bf16 v[70:73], v[236:239], v[216:219], v[70:73]
	v_mfma_f32_16x16x32_bf16 v[38:41], v[236:239], v[220:223], v[38:41]
	v_mfma_f32_16x16x32_bf16 v[6:9], v[236:239], v[224:227], v[6:9]
	s_waitcnt lgkmcnt(0)
	v_mfma_f32_16x16x32_bf16 v[98:101], v[240:243], v[212:215], v[98:101]
	v_mfma_f32_16x16x32_bf16 v[66:69], v[240:243], v[216:219], v[66:69]
	v_mfma_f32_16x16x32_bf16 v[34:37], v[240:243], v[220:223], v[34:37]
	v_mfma_f32_16x16x32_bf16 v[2:5], v[240:243], v[224:227], v[2:5]
	s_add_u32 s100, s100, s94
	s_addc_u32 s101, s101, s95
	s_add_u32 vcc_lo, vcc_lo, s38
	s_addc_u32 vcc_hi, vcc_hi, s39
	s_add_i32 s42, s42, 1
	s_cmp_lg_u32 s42, 3
	s_cselect_b32 s42, s42, 0
	s_add_i32 s43, s43, 1
	s_cmp_lg_u32 s43, 3
	s_cselect_b32 s43, s43, 0
	s_setprio 0
	s_add_i32 s20, s20, 1
	s_branch .LBB0_1217

; template <int OFF> DEVI bf16x8 ldsr(unsigned a) { bf16x8 v; asm volatile("ds_read_b128 %0, %1 offset:%2" : "=v"(v) : "v"(a), "n"(OFF)); return v; }
; #define RAW_BARRIER() do { asm volatile("s_waitcnt lgkmcnt(0)" ::: "memory"); __builtin_amdgcn_s_barrier(); } while (0)
; template <int EPI, int NB>
; DEVI void gemm_tile(const GemmJob& J, int m0, int n0, unsigned char* smem) {
;     ...
;   for (int kt = 0; kt < nk; ++kt) {
;     if (nk - 1 - kt >= S - 2) {
;       if constexpr (NB == 8) asm volatile("s_waitcnt vmcnt(6)" ::: "memory");
;       else                   asm volatile("s_waitcnt vmcnt(8)" ::: "memory");
;     } else {
;       asm volatile("s_waitcnt vmcnt(0)" ::: "memory");
;     }
;     RAW_BARRIER();
;     if (kt + S - 1 < nk) GEMM_ISSUE(kt + S - 1, is);
;     is = (is + 1 == S) ? 0 : is + 1;
;     const unsigned cur = lbase + cs * STG;
;     cs = (cs + 1 == S) ? 0 : cs + 1;
;     bf16x8 af[4], bfr[NB];
;     const unsigned aa = cur + aofs, ba = cur + bofs;
;     af[0] = ldsr<0>(aa); af[1] = ldsr<1024>(aa); af[2] = ldsr<2048>(aa); af[3] = ldsr<3072>(aa);
;     bfr[0] = ldsr<0>(ba); bfr[1] = ldsr<1024>(ba); bfr[2] = ldsr<2048>(ba); bfr[3] = ldsr<3072>(ba);
;     __builtin_amdgcn_s_setprio(1);
; #pragma unroll
;     for (int nb = 0; nb < NB; ++nb) {
;       if (nb == 0) asm volatile("s_waitcnt lgkmcnt(3)" : "+v"(af[0]), "+v"(af[1]), "+v"(af[2]), "+v"(af[3]), "+v"(bfr[0]) :: "memory");
;       else if (nb <= NB - 4) asm volatile("s_waitcnt lgkmcnt(3)" : "+v"(bfr[nb]) :: "memory");
;       else if (nb == NB - 3) asm volatile("s_waitcnt lgkmcnt(2)" : "+v"(bfr[nb]) :: "memory");
;       else if (nb == NB - 2) asm volatile("s_waitcnt lgkmcnt(1)" : "+v"(bfr[nb]) :: "memory");
;       else asm volatile("s_waitcnt lgkmcnt(0)" : "+v"(bfr[nb]) :: "memory");
;       __builtin_amdgcn_sched_barrier(0);
; #pragma unroll
;       for (int mb = 0; mb < 4; ++mb) {
;         if constexpr (SWAP) acc[mb][nb] = __builtin_amdgcn_mfma_f32_16x16x32_bf16(bfr[nb], af[mb], acc[mb][nb], 0, 0, 0);
;         else                acc[mb][nb] = __builtin_amdgcn_mfma_f32_16x16x32_bf16(af[mb], bfr[nb], acc[mb][nb], 0, 0, 0);
.LBB0_1295:
	s_mul_i32 s1, s42, 0x6000
	v_add_u32_e32 v211, s1, v209
	v_add_u32_e32 v244, s1, v210
	s_mul_i32 m0, s20, 0x6000
	s_add_u32 m0, m0, s0
	s_cmp_gt_u32 s9, 30
	s_cbranch_scc1 .Lgk11_w0
	s_waitcnt vmcnt(6)
.Lgk11_bar:
	s_waitcnt lgkmcnt(0)
	s_barrier
	s_setprio 1
	ds_read_b128 v[212:215], v211 offset:0
	ds_read_b128 v[228:231], v244 offset:0
	ds_read_b128 v[216:219], v211 offset:0x400
	ds_read_b128 v[220:223], v211 offset:0x800
	ds_read_b128 v[224:227], v211 offset:0xc00
	ds_read_b128 v[232:235], v244 offset:0x400
	ds_read_b128 v[236:239], v244 offset:0x800
	ds_read_b128 v[240:243], v244 offset:0xc00
	s_cmp_gt_u32 s9, 29
	s_cbranch_scc1 .Lgk11_tail
	s_waitcnt lgkmcnt(6)
	v_mfma_f32_16x16x32_bf16 v[126:129], v[212:215], v[228:231], v[126:129]
	s_waitcnt lgkmcnt(5)
	v_mfma_f32_16x16x32_bf16 v[94:97], v[216:219], v[228:231], v[94:97]
	s_waitcnt lgkmcnt(4)
	v_mfma_f32_16x16x32_bf16 v[62:65], v[220:223], v[228:231], v[62:65]
	s_waitcnt lgkmcnt(3)
	v_mfma_f32_16x16x32_bf16 v[30:33], v[224:227], v[228:231], v[30:33]
	ds_read_b128 v[228:231], v244 offset:0x1000
	global_load_lds_dwordx4 v182, s[100:101]
	s_add_u32 m0, m0, 0x1000
	s_waitcnt lgkmcnt(3)
	v_mfma_f32_16x16x32_bf16 v[122:125], v[212:215], v[232:235], v[122:125]
	v_mfma_f32_16x16x32_bf16 v[90:93], v[216:219], v[232:235], v[90:93]
	v_mfma_f32_16x16x32_bf16 v[58:61], v[220:223], v[232:235], v[58:61]
	v_mfma_f32_16x16x32_bf16 v[26:29], v[224:227], v[232:235], v[26:29]
	ds_read_b128 v[232:235], v244 offset:0x1400
	global_load_lds_dwordx4 v183, s[100:101]
	s_add_u32 m0, m0, 0x1000
	s_waitcnt lgkmcnt(3)
	v_mfma_f32_16x16x32_bf16 v[118:121], v[212:215], v[236:239], v[118:121]
	v_mfma_f32_16x16x32_bf16 v[86:89], v[216:219], v[236:239], v[86:89]
	v_mfma_f32_16x16x32_bf16 v[54:57], v[220:223], v[236:239], v[54:57]
	v_mfma_f32_16x16x32_bf16 v[22:25], v[224:227], v[236:239], v[22:25]
	ds_read_b128 v[236:239], v244 offset:0x1800
	global_load_lds_dwordx4 v180, vcc
	s_add_u32 m0, m0, 0x1000
	s_waitcnt lgkmcnt(3)
	v_mfma_f32_16x16x32_bf16 v[114:117], v[212:215], v[240:243], v[114:117]
	v_mfma_f32_16x16x32_bf16 v[82:85], v[216:219], v[240:243], v[82:85]
	v_mfma_f32_16x16x32_bf16 v[50:53], v[220:223], v[240:243], v[50:53]
	v_mfma_f32_16x16x32_bf16 v[18:21], v[224:227], v[240:243], v[18:21]
	ds_read_b128 v[240:243], v244 offset:0x1c00
	global_load_lds_dwordx4 v181, vcc
	s_add_u32 m0, m0, 0x1000
	s_waitcnt lgkmcnt(3)
	v_mfma_f32_16x16x32_bf16 v[110:113], v[212:215], v[228:231], v[110:113]
	v_mfma_f32_16x16x32_bf16 v[78:81], v[216:219], v[228:231], v[78:81]
	v_mfma_f32_16x16x32_bf16 v[46:49], v[220:223], v[228:231], v[46:49]
	v_mfma_f32_16x16x32_bf16 v[14:17], v[224:227], v[228:231], v[14:17]
	global_load_lds_dwordx4 v253, vcc
	s_add_u32 m0, m0, 0x1000
	s_waitcnt lgkmcnt(2)
	v_mfma_f32_16x16x32_bf16 v[106:109], v[212:215], v[232:235], v[106:109]
	v_mfma_f32_16x16x32_bf16 v[74:77], v[216:219], v[232:235], v[74:77]
	v_mfma_f32_16x16x32_bf16 v[42:45], v[220:223], v[232:235], v[42:45]
	v_mfma_f32_16x16x32_bf16 v[10:13], v[224:227], v[232:235], v[10:13]
	global_load_lds_dwordx4 v254, vcc
	s_waitcnt lgkmcnt(1)
	v_mfma_f32_16x16x32_bf16 v[102:105], v[212:215], v[236:239], v[102:105]
	v_mfma_f32_16x16x32_bf16 v[70:73], v[216:219], v[236:239], v[70:73]
	v_mfma_f32_16x16x32_bf16 v[38:41], v[220:223], v[236:239], v[38:41]
	v_mfma_f32_16x16x32_bf16 v[6:9], v[224:227], v[236:239], v[6:9]
	s_waitcnt lgkmcnt(0)
	v_mfma_f32_16x16x32_bf16 v[98:101], v[212:215], v[240:243], v[98:101]
	v_mfma_f32_16x16x32_bf16 v[66:69], v[216:219], v[240:243], v[66:69]
	v_mfma_f32_16x16x32_bf16 v[34:37], v[220:223], v[240:243], v[34:37]
	v_mfma_f32_16x16x32_bf16 v[2:5], v[224:227], v[240:243], v[2:5]
	s_add_u32 s100, s100, s94
	s_addc_u32 s101, s101, s95
	s_add_u32 vcc_lo, vcc_lo, s38
	s_addc_u32 vcc_hi, vcc_hi, s39
	s_add_i32 s20, s20, 1
	s_cmp_lg_u32 s20, 3
	s_cselect_b32 s20, s20, 0
	s_add_i32 s42, s42, 1
	s_cmp_lg_u32 s42, 3
	s_cselect_b32 s42, s42, 0
	s_setprio 0
	s_add_i32 s9, s9, 1
	s_branch .LBB0_1295
.Lgk11_tail:
	s_waitcnt lgkmcnt(6)
	v_mfma_f32_16x16x32_bf16 v[126:129], v[212:215], v[228:231], v[126:129]
	s_waitcnt lgkmcnt(5)
	v_mfma_f32_16x16x32_bf16 v[94:97], v[216:219], v[228:231], v[94:97]
	s_waitcnt lgkmcnt(4)
	v_mfma_f32_16x16x32_bf16 v[62:65], v[220:223], v[228:231], v[62:65]
	s_waitcnt lgkmcnt(3)
	v_mfma_f32_16x16x32_bf16 v[30:33], v[224:227], v[228:231], v[30:33]
	ds_read_b128 v[228:231], v244 offset:0x1000
	s_waitcnt lgkmcnt(3)
	v_mfma_f32_16x16x32_bf16 v[122:125], v[212:215], v[232:235], v[122:125]
	v_mfma_f32_16x16x32_bf16 v[90:93], v[216:219], v[232:235], v[90:93]
	v_mfma_f32_16x16x32_bf16 v[58:61], v[220:223], v[232:235], v[58:61]
	v_mfma_f32_16x16x32_bf16 v[26:29], v[224:227], v[232:235], v[26:29]
	ds_read_b128 v[232:235], v244 offset:0x1400
	s_waitcnt lgkmcnt(3)
	v_mfma_f32_16x16x32_bf16 v[118:121], v[212:215], v[236:239], v[118:121]
	v_mfma_f32_16x16x32_bf16 v[86:89], v[216:219], v[236:239], v[86:89]
	v_mfma_f32_16x16x32_bf16 v[54:57], v[220:223], v[236:239], v[54:57]
	v_mfma_f32_16x16x32_bf16 v[22:25], v[224:227], v[236:239], v[22:25]
	ds_read_b128 v[236:239], v244 offset:0x1800
	s_waitcnt lgkmcnt(3)
	v_mfma_f32_16x16x32_bf16 v[114:117], v[212:215], v[240:243], v[114:117]
	v_mfma_f32_16x16x32_bf16 v[82:85], v[216:219], v[240:243], v[82:85]
	v_mfma_f32_16x16x32_bf16 v[50:53], v[220:223], v[240:243], v[50:53]
	v_mfma_f32_16x16x32_bf16 v[18:21], v[224:227], v[240:243], v[18:21]
	ds_read_b128 v[240:243], v244 offset:0x1c00
	s_waitcnt lgkmcnt(3)
	v_mfma_f32_16x16x32_bf16 v[110:113], v[212:215], v[228:231], v[110:113]
	v_mfma_f32_16x16x32_bf16 v[78:81], v[216:219], v[228:231], v[78:81]
	v_mfma_f32_16x16x32_bf16 v[46:49], v[220:223], v[228:231], v[46:49]
	v_mfma_f32_16x16x32_bf16 v[14:17], v[224:227], v[228:231], v[14:17]
	s_waitcnt lgkmcnt(2)
	v_mfma_f32_16x16x32_bf16 v[106:109], v[212:215], v[232:235], v[106:109]
	v_mfma_f32_16x16x32_bf16 v[74:77], v[216:219], v[232:235], v[74:77]
	v_mfma_f32_16x16x32_bf16 v[42:45], v[220:223], v[232:235], v[42:45]
	v_mfma_f32_16x16x32_bf16 v[10:13], v[224:227], v[232:235], v[10:13]
	s_waitcnt lgkmcnt(1)
	v_mfma_f32_16x16x32_bf16 v[102:105], v[212:215], v[236:239], v[102:105]
	v_mfma_f32_16x16x32_bf16 v[70:73], v[216:219], v[236:239], v[70:73]
	v_mfma_f32_16x16x32_bf16 v[38:41], v[220:223], v[236:239], v[38:41]
	v_mfma_f32_16x16x32_bf16 v[6:9], v[224:227], v[236:239], v[6:9]
	s_waitcnt lgkmcnt(0)
	v_mfma_f32_16x16x32_bf16 v[98:101], v[212:215], v[240:243], v[98:101]
	v_mfma_f32_16x16x32_bf16 v[66:69], v[216:219], v[240:243], v[66:69]
	v_mfma_f32_16x16x32_bf16 v[34:37], v[220:223], v[240:243], v[34:37]
	v_mfma_f32_16x16x32_bf16 v[2:5], v[224:227], v[240:243], v[2:5]
	s_add_i32 s20, s20, 1
	s_cmp_lg_u32 s20, 3
	s_cselect_b32 s20, s20, 0
	s_add_i32 s42, s42, 1
	s_cmp_lg_u32 s42, 3
	s_cselect_b32 s42, s42, 0
	s_setprio 0
	s_add_i32 s9, s9, 1
	s_cmp_lg_u32 s9, 32
	s_cbranch_scc1 .LBB0_1295
	s_branch .LBB0_1301

; template <int OFF> DEVI bf16x8 ldsr(unsigned a) { bf16x8 v; asm volatile("ds_read_b128 %0, %1 offset:%2" : "=v"(v) : "v"(a), "n"(OFF)); return v; }
; #define RAW_BARRIER() do { asm volatile("s_waitcnt lgkmcnt(0)" ::: "memory"); __builtin_amdgcn_s_barrier(); } while (0)
; template <int EPI, int NB>
; DEVI void gemm_tile(const GemmJob& J, int m0, int n0, unsigned char* smem) {
;     ...
;     RAW_BARRIER();
;     if (kt + S - 1 < nk) GEMM_ISSUE(kt + S - 1, is);
;     is = (is + 1 == S) ? 0 : is + 1;
;     const unsigned cur = lbase + cs * STG;
;     cs = (cs + 1 == S) ? 0 : cs + 1;
;     bf16x8 af[4], bfr[NB];
;     const unsigned aa = cur + aofs, ba = cur + bofs;
;     af[0] = ldsr<0>(aa); af[1] = ldsr<1024>(aa); af[2] = ldsr<2048>(aa); af[3] = ldsr<3072>(aa);
;     bfr[0] = ldsr<0>(ba); bfr[1] = ldsr<1024>(ba); bfr[2] = ldsr<2048>(ba); bfr[3] = ldsr<3072>(ba);
;     __builtin_amdgcn_s_setprio(1);
; #pragma unroll
;     for (int nb = 0; nb < NB; ++nb) {
;       if (nb == 0) asm volatile("s_waitcnt lgkmcnt(3)" : "+v"(af[0]), "+v"(af[1]), "+v"(af[2]), "+v"(af[3]), "+v"(bfr[0]) :: "memory");
;       else if (nb <= NB - 4) asm volatile("s_waitcnt lgkmcnt(3)" : "+v"(bfr[nb]) :: "memory");
;       else if (nb == NB - 3) asm volatile("s_waitcnt lgkmcnt(2)" : "+v"(bfr[nb]) :: "memory");
;       else if (nb == NB - 2) asm volatile("s_waitcnt lgkmcnt(1)" : "+v"(bfr[nb]) :: "memory");
;       else asm volatile("s_waitcnt lgkmcnt(0)" : "+v"(bfr[nb]) :: "memory");
;       __builtin_amdgcn_sched_barrier(0);
; #pragma unroll
;       for (int mb = 0; mb < 4; ++mb) {
;         if constexpr (SWAP) acc[mb][nb] = __builtin_amdgcn_mfma_f32_16x16x32_bf16(bfr[nb], af[mb], acc[mb][nb], 0, 0, 0);
;         else                acc[mb][nb] = __builtin_amdgcn_mfma_f32_16x16x32_bf16(af[mb], bfr[nb], acc[mb][nb], 0, 0, 0);
;       }
.Lgk12_bar:
	s_waitcnt lgkmcnt(0)
	s_barrier
	s_setprio 1
	ds_read_b128 v[212:215], v211 offset:0
	ds_read_b128 v[228:231], v244 offset:0
	ds_read_b128 v[216:219], v211 offset:0x400
	ds_read_b128 v[220:223], v211 offset:0x800
	ds_read_b128 v[224:227], v211 offset:0xc00
	ds_read_b128 v[232:235], v244 offset:0x400
	ds_read_b128 v[236:239], v244 offset:0x800
	ds_read_b128 v[240:243], v244 offset:0xc00
	s_cmp_gt_u32 s2, 29
	s_cbranch_scc1 .Lgk12_tail
	s_waitcnt lgkmcnt(6)
	v_mfma_f32_16x16x32_bf16 v[126:129], v[228:231], v[212:215], v[126:129]
	s_waitcnt lgkmcnt(5)
	v_mfma_f32_16x16x32_bf16 v[94:97], v[228:231], v[216:219], v[94:97]
	s_waitcnt lgkmcnt(4)
	v_mfma_f32_16x16x32_bf16 v[62:65], v[228:231], v[220:223], v[62:65]
	s_waitcnt lgkmcnt(3)
	v_mfma_f32_16x16x32_bf16 v[30:33], v[228:231], v[224:227], v[30:33]
	ds_read_b128 v[228:231], v244 offset:0x1000
	global_load_lds_dwordx4 v182, s[100:101]
	s_add_u32 m0, m0, 0x1000
	s_waitcnt lgkmcnt(3)
	v_mfma_f32_16x16x32_bf16 v[122:125], v[232:235], v[212:215], v[122:125]
	v_mfma_f32_16x16x32_bf16 v[90:93], v[232:235], v[216:219], v[90:93]
	v_mfma_f32_16x16x32_bf16 v[58:61], v[232:235], v[220:223], v[58:61]
	v_mfma_f32_16x16x32_bf16 v[26:29], v[232:235], v[224:227], v[26:29]
	ds_read_b128 v[232:235], v244 offset:0x1400
	global_load_lds_dwordx4 v183, s[100:101]
	s_add_u32 m0, m0, 0x1000
	s_waitcnt lgkmcnt(3)
	v_mfma_f32_16x16x32_bf16 v[118:121], v[236:239], v[212:215], v[118:121]
	v_mfma_f32_16x16x32_bf16 v[86:89], v[236:239], v[216:219], v[86:89]
	v_mfma_f32_16x16x32_bf16 v[54:57], v[236:239], v[220:223], v[54:57]
	v_mfma_f32_16x16x32_bf16 v[22:25], v[236:239], v[224:227], v[22:25]
	ds_read_b128 v[236:239], v244 offset:0x1800
	global_load_lds_dwordx4 v180, vcc
	s_add_u32 m0, m0, 0x1000
	s_waitcnt lgkmcnt(3)
	v_mfma_f32_16x16x32_bf16 v[114:117], v[240:243], v[212:215], v[114:117]
	v_mfma_f32_16x16x32_bf16 v[82:85], v[240:243], v[216:219], v[82:85]
	v_mfma_f32_16x16x32_bf16 v[50:53], v[240:243], v[220:223], v[50:53]
	v_mfma_f32_16x16x32_bf16 v[18:21], v[240:243], v[224:227], v[18:21]
	ds_read_b128 v[240:243], v244 offset:0x1c00
	global_load_lds_dwordx4 v181, vcc
	s_add_u32 m0, m0, 0x1000
	s_waitcnt lgkmcnt(3)
	v_mfma_f32_16x16x32_bf16 v[110:113], v[228:231], v[212:215], v[110:113]
	v_mfma_f32_16x16x32_bf16 v[78:81], v[228:231], v[216:219], v[78:81]
	v_mfma_f32_16x16x32_bf16 v[46:49], v[228:231], v[220:223], v[46:49]
	v_mfma_f32_16x16x32_bf16 v[14:17], v[228:231], v[224:227], v[14:17]
	global_load_lds_dwordx4 v253, vcc
	s_add_u32 m0, m0, 0x1000
	s_waitcnt lgkmcnt(2)
	v_mfma_f32_16x16x32_bf16 v[106:109], v[232:235], v[212:215], v[106:109]
	v_mfma_f32_16x16x32_bf16 v[74:77], v[232:235], v[216:219], v[74:77]
	v_mfma_f32_16x16x32_bf16 v[42:45], v[232:235], v[220:223], v[42:45]
	v_mfma_f32_16x16x32_bf16 v[10:13], v[232:235], v[224:227], v[10:13]
	global_load_lds_dwordx4 v254, vcc
	s_waitcnt lgkmcnt(1)
	v_mfma_f32_16x16x32_bf16 v[102:105], v[236:239], v[212:215], v[102:105]
	v_mfma_f32_16x16x32_bf16 v[70:73], v[236:239], v[216:219], v[70:73]
	v_mfma_f32_16x16x32_bf16 v[38:41], v[236:239], v[220:223], v[38:41]
	v_mfma_f32_16x16x32_bf16 v[6:9], v[236:239], v[224:227], v[6:9]
	s_waitcnt lgkmcnt(0)
	v_mfma_f32_16x16x32_bf16 v[98:101], v[240:243], v[212:215], v[98:101]
	v_mfma_f32_16x16x32_bf16 v[66:69], v[240:243], v[216:219], v[66:69]
	v_mfma_f32_16x16x32_bf16 v[34:37], v[240:243], v[220:223], v[34:37]
	v_mfma_f32_16x16x32_bf16 v[2:5], v[240:243], v[224:227], v[2:5]
	s_add_u32 s100, s100, s94
	s_addc_u32 s101, s101, s95
	s_add_u32 vcc_lo, vcc_lo, s38
	s_addc_u32 vcc_hi, vcc_hi, s39
	s_add_i32 s42, s42, 1
	s_cmp_lg_u32 s42, 3
	s_cselect_b32 s42, s42, 0
	s_add_i32 s43, s43, 1
	s_cmp_lg_u32 s43, 3
	s_cselect_b32 s43, s43, 0
	s_setprio 0
	s_add_i32 s2, s2, 1
	s_branch .LBB0_1342

; template <int OFF> DEVI bf16x8 ldsr(unsigned a) { bf16x8 v; asm volatile("ds_read_b128 %0, %1 offset:%2" : "=v"(v) : "v"(a), "n"(OFF)); return v; }
; #define RAW_BARRIER() do { asm volatile("s_waitcnt lgkmcnt(0)" ::: "memory"); __builtin_amdgcn_s_barrier(); } while (0)
; template <int EPI, int NB>
; DEVI void gemm_tile(const GemmJob& J, int m0, int n0, unsigned char* smem) {
;     ...
;     RAW_BARRIER();
;     if (kt + S - 1 < nk) GEMM_ISSUE(kt + S - 1, is);
;     is = (is + 1 == S) ? 0 : is + 1;
;     const unsigned cur = lbase + cs * STG;
;     cs = (cs + 1 == S) ? 0 : cs + 1;
;     bf16x8 af[4], bfr[NB];
;     const unsigned aa = cur + aofs, ba = cur + bofs;
;     af[0] = ldsr<0>(aa); af[1] = ldsr<1024>(aa); af[2] = ldsr<2048>(aa); af[3] = ldsr<3072>(aa);
;     bfr[0] = ldsr<0>(ba); bfr[1] = ldsr<1024>(ba); bfr[2] = ldsr<2048>(ba); bfr[3] = ldsr<3072>(ba);
;     __builtin_amdgcn_s_setprio(1);
; #pragma unroll
;     for (int nb = 0; nb < NB; ++nb) {
;       if (nb == 0) asm volatile("s_waitcnt lgkmcnt(3)" : "+v"(af[0]), "+v"(af[1]), "+v"(af[2]), "+v"(af[3]), "+v"(bfr[0]) :: "memory");
;       else if (nb <= NB - 4) asm volatile("s_waitcnt lgkmcnt(3)" : "+v"(bfr[nb]) :: "memory");
;       else if (nb == NB - 3) asm volatile("s_waitcnt lgkmcnt(2)" : "+v"(bfr[nb]) :: "memory");
;       else if (nb == NB - 2) asm volatile("s_waitcnt lgkmcnt(1)" : "+v"(bfr[nb]) :: "memory");
;       else asm volatile("s_waitcnt lgkmcnt(0)" : "+v"(bfr[nb]) :: "memory");
;       __builtin_amdgcn_sched_barrier(0);
; #pragma unroll
;       for (int mb = 0; mb < 4; ++mb) {
;         if constexpr (SWAP) acc[mb][nb] = __builtin_amdgcn_mfma_f32_16x16x32_bf16(bfr[nb], af[mb], acc[mb][nb], 0, 0, 0);
;         else                acc[mb][nb] = __builtin_amdgcn_mfma_f32_16x16x32_bf16(af[mb], bfr[nb], acc[mb][nb], 0, 0, 0);
.Lgk13_bar:
	s_waitcnt lgkmcnt(0)
	s_barrier
	s_setprio 1
	ds_read_b128 v[210:213], v222 offset:0
	ds_read_b128 v[226:229], v242 offset:0
	ds_read_b128 v[214:217], v222 offset:0x400
	ds_read_b128 v[218:221], v222 offset:0x800
	ds_read_b128 v[222:225], v222 offset:0xc00
	ds_read_b128 v[230:233], v242 offset:0x400
	ds_read_b128 v[234:237], v242 offset:0x800
	ds_read_b128 v[238:241], v242 offset:0xc00
	s_cmp_gt_u32 s3, 29
	s_cbranch_scc1 .Lgk13_tail
	s_waitcnt lgkmcnt(6)
	v_mfma_f32_16x16x32_bf16 v[126:129], v[210:213], v[226:229], v[126:129]
	s_waitcnt lgkmcnt(5)
	v_mfma_f32_16x16x32_bf16 v[94:97], v[214:217], v[226:229], v[94:97]
	s_waitcnt lgkmcnt(4)
	v_mfma_f32_16x16x32_bf16 v[62:65], v[218:221], v[226:229], v[62:65]
	s_waitcnt lgkmcnt(3)
	v_mfma_f32_16x16x32_bf16 v[30:33], v[222:225], v[226:229], v[30:33]
	ds_read_b128 v[226:229], v242 offset:0x1000
	global_load_lds_dwordx4 v182, s[100:101]
	s_add_u32 m0, m0, 0x1000
	s_waitcnt lgkmcnt(3)
	v_mfma_f32_16x16x32_bf16 v[122:125], v[210:213], v[230:233], v[122:125]
	v_mfma_f32_16x16x32_bf16 v[90:93], v[214:217], v[230:233], v[90:93]
	v_mfma_f32_16x16x32_bf16 v[58:61], v[218:221], v[230:233], v[58:61]
	v_mfma_f32_16x16x32_bf16 v[26:29], v[222:225], v[230:233], v[26:29]
	ds_read_b128 v[230:233], v242 offset:0x1400
	global_load_lds_dwordx4 v183, s[100:101]
	s_add_u32 m0, m0, 0x1000
	s_waitcnt lgkmcnt(3)
	v_mfma_f32_16x16x32_bf16 v[118:121], v[210:213], v[234:237], v[118:121]
	v_mfma_f32_16x16x32_bf16 v[86:89], v[214:217], v[234:237], v[86:89]
	v_mfma_f32_16x16x32_bf16 v[54:57], v[218:221], v[234:237], v[54:57]
	v_mfma_f32_16x16x32_bf16 v[22:25], v[222:225], v[234:237], v[22:25]
	ds_read_b128 v[234:237], v242 offset:0x1800
	global_load_lds_dwordx4 v180, vcc
	s_add_u32 m0, m0, 0x1000
	s_waitcnt lgkmcnt(3)
	v_mfma_f32_16x16x32_bf16 v[114:117], v[210:213], v[238:241], v[114:117]
	v_mfma_f32_16x16x32_bf16 v[82:85], v[214:217], v[238:241], v[82:85]
	v_mfma_f32_16x16x32_bf16 v[50:53], v[218:221], v[238:241], v[50:53]
	v_mfma_f32_16x16x32_bf16 v[18:21], v[222:225], v[238:241], v[18:21]
	ds_read_b128 v[238:241], v242 offset:0x1c00
	global_load_lds_dwordx4 v181, vcc
	s_add_u32 m0, m0, 0x1000
	s_waitcnt lgkmcnt(3)
	v_mfma_f32_16x16x32_bf16 v[110:113], v[210:213], v[226:229], v[110:113]
	v_mfma_f32_16x16x32_bf16 v[78:81], v[214:217], v[226:229], v[78:81]
	v_mfma_f32_16x16x32_bf16 v[46:49], v[218:221], v[226:229], v[46:49]
	v_mfma_f32_16x16x32_bf16 v[14:17], v[222:225], v[226:229], v[14:17]
	global_load_lds_dwordx4 v253, vcc
	s_add_u32 m0, m0, 0x1000
	s_waitcnt lgkmcnt(2)
	v_mfma_f32_16x16x32_bf16 v[106:109], v[210:213], v[230:233], v[106:109]
	v_mfma_f32_16x16x32_bf16 v[74:77], v[214:217], v[230:233], v[74:77]
	v_mfma_f32_16x16x32_bf16 v[42:45], v[218:221], v[230:233], v[42:45]
	v_mfma_f32_16x16x32_bf16 v[10:13], v[222:225], v[230:233], v[10:13]
	global_load_lds_dwordx4 v254, vcc
	s_waitcnt lgkmcnt(1)
	v_mfma_f32_16x16x32_bf16 v[102:105], v[210:213], v[234:237], v[102:105]
	v_mfma_f32_16x16x32_bf16 v[70:73], v[214:217], v[234:237], v[70:73]
	v_mfma_f32_16x16x32_bf16 v[38:41], v[218:221], v[234:237], v[38:41]
	v_mfma_f32_16x16x32_bf16 v[6:9], v[222:225], v[234:237], v[6:9]
	s_waitcnt lgkmcnt(0)
	v_mfma_f32_16x16x32_bf16 v[98:101], v[210:213], v[238:241], v[98:101]
	v_mfma_f32_16x16x32_bf16 v[66:69], v[214:217], v[238:241], v[66:69]
	v_mfma_f32_16x16x32_bf16 v[34:37], v[218:221], v[238:241], v[34:37]
	v_mfma_f32_16x16x32_bf16 v[2:5], v[222:225], v[238:241], v[2:5]
	s_add_u32 s100, s100, s94
	s_addc_u32 s101, s101, s95
	s_add_u32 vcc_lo, vcc_lo, s38
	s_addc_u32 vcc_hi, vcc_hi, s39
	s_add_i32 s42, s42, 1
	s_cmp_lg_u32 s42, 3
	s_cselect_b32 s42, s42, 0
	s_add_i32 s43, s43, 1
	s_cmp_lg_u32 s43, 3
	s_cselect_b32 s43, s43, 0
	s_setprio 0
	s_add_i32 s3, s3, 1
	s_branch .LBB0_1421

; template <int OFF> DEVI bf16x8 ldsr(unsigned a) { bf16x8 v; asm volatile("ds_read_b128 %0, %1 offset:%2" : "=v"(v) : "v"(a), "n"(OFF)); return v; }
; #define RAW_BARRIER() do { asm volatile("s_waitcnt lgkmcnt(0)" ::: "memory"); __builtin_amdgcn_s_barrier(); } while (0)
; template <int EPI, int NB>
; DEVI void gemm_tile(const GemmJob& J, int m0, int n0, unsigned char* smem) {
;     ...
;   for (int kt = 0; kt < nk; ++kt) {
;     if (nk - 1 - kt >= S - 2) {
;       if constexpr (NB == 8) asm volatile("s_waitcnt vmcnt(6)" ::: "memory");
;       else                   asm volatile("s_waitcnt vmcnt(8)" ::: "memory");
;     } else {
;       asm volatile("s_waitcnt vmcnt(0)" ::: "memory");
;     }
;     RAW_BARRIER();
;     if (kt + S - 1 < nk) GEMM_ISSUE(kt + S - 1, is);
;     is = (is + 1 == S) ? 0 : is + 1;
;     const unsigned cur = lbase + cs * STG;
;     cs = (cs + 1 == S) ? 0 : cs + 1;
;     bf16x8 af[4], bfr[NB];
;     const unsigned aa = cur + aofs, ba = cur + bofs;
;     af[0] = ldsr<0>(aa); af[1] = ldsr<1024>(aa); af[2] = ldsr<2048>(aa); af[3] = ldsr<3072>(aa);
;     bfr[0] = ldsr<0>(ba); bfr[1] = ldsr<1024>(ba); bfr[2] = ldsr<2048>(ba); bfr[3] = ldsr<3072>(ba);
;     __builtin_amdgcn_s_setprio(1);
; #pragma unroll
;     for (int nb = 0; nb < NB; ++nb) {
;       if (nb == 0) asm volatile("s_waitcnt lgkmcnt(3)" : "+v"(af[0]), "+v"(af[1]), "+v"(af[2]), "+v"(af[3]), "+v"(bfr[0]) :: "memory");
;       else if (nb <= NB - 4) asm volatile("s_waitcnt lgkmcnt(3)" : "+v"(bfr[nb]) :: "memory");
;       else if (nb == NB - 3) asm volatile("s_waitcnt lgkmcnt(2)" : "+v"(bfr[nb]) :: "memory");
;       else if (nb == NB - 2) asm volatile("s_waitcnt lgkmcnt(1)" : "+v"(bfr[nb]) :: "memory");
;       else asm volatile("s_waitcnt lgkmcnt(0)" : "+v"(bfr[nb]) :: "memory");
;       __builtin_amdgcn_sched_barrier(0);
; #pragma unroll
;       for (int mb = 0; mb < 4; ++mb) {
;         if constexpr (SWAP) acc[mb][nb] = __builtin_amdgcn_mfma_f32_16x16x32_bf16(bfr[nb], af[mb], acc[mb][nb], 0, 0, 0);
;         else                acc[mb][nb] = __builtin_amdgcn_mfma_f32_16x16x32_bf16(af[mb], bfr[nb], acc[mb][nb], 0, 0, 0);
;       }
.LBB0_1625:
	s_mul_i32 s1, s43, 0x6000
	v_add_u32_e32 v211, s1, v209
	v_add_u32_e32 v244, s1, v210
	s_mul_i32 m0, s42, 0x6000
	s_add_u32 m0, m0, s0
	s_cmp_gt_u32 s20, 6
	s_cbranch_scc1 .Lgk14_w0
	s_waitcnt vmcnt(6)
.Lgk14_bar:
	s_waitcnt lgkmcnt(0)
	s_barrier
	s_setprio 1
	ds_read_b128 v[212:215], v211 offset:0
	ds_read_b128 v[228:231], v244 offset:0
	ds_read_b128 v[216:219], v211 offset:0x400
	ds_read_b128 v[220:223], v211 offset:0x800
	ds_read_b128 v[224:227], v211 offset:0xc00
	ds_read_b128 v[232:235], v244 offset:0x400
	ds_read_b128 v[236:239], v244 offset:0x800
	ds_read_b128 v[240:243], v244 offset:0xc00
	s_cmp_gt_u32 s20, 5
	s_cbranch_scc1 .Lgk14_tail
	s_waitcnt lgkmcnt(6)
	v_mfma_f32_16x16x32_bf16 v[126:129], v[228:231], v[212:215], v[126:129]
	s_waitcnt lgkmcnt(5)
	v_mfma_f32_16x16x32_bf16 v[94:97], v[228:231], v[216:219], v[94:97]
	s_waitcnt lgkmcnt(4)
	v_mfma_f32_16x16x32_bf16 v[62:65], v[228:231], v[220:223], v[62:65]
	s_waitcnt lgkmcnt(3)
	v_mfma_f32_16x16x32_bf16 v[30:33], v[228:231], v[224:227], v[30:33]
	ds_read_b128 v[228:231], v244 offset:0x1000
	global_load_lds_dwordx4 v182, s[100:101]
	s_add_u32 m0, m0, 0x1000
	s_waitcnt lgkmcnt(3)
	v_mfma_f32_16x16x32_bf16 v[122:125], v[232:235], v[212:215], v[122:125]
	v_mfma_f32_16x16x32_bf16 v[90:93], v[232:235], v[216:219], v[90:93]
	v_mfma_f32_16x16x32_bf16 v[58:61], v[232:235], v[220:223], v[58:61]
	v_mfma_f32_16x16x32_bf16 v[26:29], v[232:235], v[224:227], v[26:29]
	ds_read_b128 v[232:235], v244 offset:0x1400
	global_load_lds_dwordx4 v183, s[100:101]
	s_add_u32 m0, m0, 0x1000
	s_waitcnt lgkmcnt(3)
	v_mfma_f32_16x16x32_bf16 v[118:121], v[236:239], v[212:215], v[118:121]
	v_mfma_f32_16x16x32_bf16 v[86:89], v[236:239], v[216:219], v[86:89]
	v_mfma_f32_16x16x32_bf16 v[54:57], v[236:239], v[220:223], v[54:57]
	v_mfma_f32_16x16x32_bf16 v[22:25], v[236:239], v[224:227], v[22:25]
	ds_read_b128 v[236:239], v244 offset:0x1800
	global_load_lds_dwordx4 v180, vcc
	s_add_u32 m0, m0, 0x1000
	s_waitcnt lgkmcnt(3)
	v_mfma_f32_16x16x32_bf16 v[114:117], v[240:243], v[212:215], v[114:117]
	v_mfma_f32_16x16x32_bf16 v[82:85], v[240:243], v[216:219], v[82:85]
	v_mfma_f32_16x16x32_bf16 v[50:53], v[240:243], v[220:223], v[50:53]
	v_mfma_f32_16x16x32_bf16 v[18:21], v[240:243], v[224:227], v[18:21]
	ds_read_b128 v[240:243], v244 offset:0x1c00
	global_load_lds_dwordx4 v181, vcc
	s_add_u32 m0, m0, 0x1000
	s_waitcnt lgkmcnt(3)
	v_mfma_f32_16x16x32_bf16 v[110:113], v[228:231], v[212:215], v[110:113]
	v_mfma_f32_16x16x32_bf16 v[78:81], v[228:231], v[216:219], v[78:81]
	v_mfma_f32_16x16x32_bf16 v[46:49], v[228:231], v[220:223], v[46:49]
	v_mfma_f32_16x16x32_bf16 v[14:17], v[228:231], v[224:227], v[14:17]
	global_load_lds_dwordx4 v253, vcc
	s_add_u32 m0, m0, 0x1000
	s_waitcnt lgkmcnt(2)
	v_mfma_f32_16x16x32_bf16 v[106:109], v[232:235], v[212:215], v[106:109]
	v_mfma_f32_16x16x32_bf16 v[74:77], v[232:235], v[216:219], v[74:77]
	v_mfma_f32_16x16x32_bf16 v[42:45], v[232:235], v[220:223], v[42:45]
	v_mfma_f32_16x16x32_bf16 v[10:13], v[232:235], v[224:227], v[10:13]
	global_load_lds_dwordx4 v254, vcc
	s_waitcnt lgkmcnt(1)
	v_mfma_f32_16x16x32_bf16 v[102:105], v[236:239], v[212:215], v[102:105]
	v_mfma_f32_16x16x32_bf16 v[70:73], v[236:239], v[216:219], v[70:73]
	v_mfma_f32_16x16x32_bf16 v[38:41], v[236:239], v[220:223], v[38:41]
	v_mfma_f32_16x16x32_bf16 v[6:9], v[236:239], v[224:227], v[6:9]
	s_waitcnt lgkmcnt(0)
	v_mfma_f32_16x16x32_bf16 v[98:101], v[240:243], v[212:215], v[98:101]
	v_mfma_f32_16x16x32_bf16 v[66:69], v[240:243], v[216:219], v[66:69]
	v_mfma_f32_16x16x32_bf16 v[34:37], v[240:243], v[220:223], v[34:37]
	v_mfma_f32_16x16x32_bf16 v[2:5], v[240:243], v[224:227], v[2:5]
	s_add_u32 s100, s100, 0x40
	s_addc_u32 s101, s101, 0
	s_add_u32 vcc_lo, vcc_lo, s86
	s_addc_u32 vcc_hi, vcc_hi, s87
	s_add_i32 s42, s42, 1
	s_cmp_lg_u32 s42, 3
	s_cselect_b32 s42, s42, 0
	s_add_i32 s43, s43, 1
	s_cmp_lg_u32 s43, 3
	s_cselect_b32 s43, s43, 0
	s_setprio 0
	s_add_i32 s20, s20, 1
	s_branch .LBB0_1625
.Lgk14_tail:
	s_waitcnt lgkmcnt(6)
	v_mfma_f32_16x16x32_bf16 v[126:129], v[228:231], v[212:215], v[126:129]
	s_waitcnt lgkmcnt(5)
	v_mfma_f32_16x16x32_bf16 v[94:97], v[228:231], v[216:219], v[94:97]
	s_waitcnt lgkmcnt(4)
	v_mfma_f32_16x16x32_bf16 v[62:65], v[228:231], v[220:223], v[62:65]
	s_waitcnt lgkmcnt(3)
	v_mfma_f32_16x16x32_bf16 v[30:33], v[228:231], v[224:227], v[30:33]
	ds_read_b128 v[228:231], v244 offset:0x1000
	s_waitcnt lgkmcnt(3)
	v_mfma_f32_16x16x32_bf16 v[122:125], v[232:235], v[212:215], v[122:125]
	v_mfma_f32_16x16x32_bf16 v[90:93], v[232:235], v[216:219], v[90:93]
	v_mfma_f32_16x16x32_bf16 v[58:61], v[232:235], v[220:223], v[58:61]
	v_mfma_f32_16x16x32_bf16 v[26:29], v[232:235], v[224:227], v[26:29]
	ds_read_b128 v[232:235], v244 offset:0x1400
	s_waitcnt lgkmcnt(3)
	v_mfma_f32_16x16x32_bf16 v[118:121], v[236:239], v[212:215], v[118:121]
	v_mfma_f32_16x16x32_bf16 v[86:89], v[236:239], v[216:219], v[86:89]
	v_mfma_f32_16x16x32_bf16 v[54:57], v[236:239], v[220:223], v[54:57]
	v_mfma_f32_16x16x32_bf16 v[22:25], v[236:239], v[224:227], v[22:25]
	ds_read_b128 v[236:239], v244 offset:0x1800
	s_waitcnt lgkmcnt(3)
	v_mfma_f32_16x16x32_bf16 v[114:117], v[240:243], v[212:215], v[114:117]
	v_mfma_f32_16x16x32_bf16 v[82:85], v[240:243], v[216:219], v[82:85]
	v_mfma_f32_16x16x32_bf16 v[50:53], v[240:243], v[220:223], v[50:53]
	v_mfma_f32_16x16x32_bf16 v[18:21], v[240:243], v[224:227], v[18:21]
	ds_read_b128 v[240:243], v244 offset:0x1c00
	s_waitcnt lgkmcnt(3)
	v_mfma_f32_16x16x32_bf16 v[110:113], v[228:231], v[212:215], v[110:113]
	v_mfma_f32_16x16x32_bf16 v[78:81], v[228:231], v[216:219], v[78:81]
	v_mfma_f32_16x16x32_bf16 v[46:49], v[228:231], v[220:223], v[46:49]
	v_mfma_f32_16x16x32_bf16 v[14:17], v[228:231], v[224:227], v[14:17]
	s_waitcnt lgkmcnt(2)
	v_mfma_f32_16x16x32_bf16 v[106:109], v[232:235], v[212:215], v[106:109]
	v_mfma_f32_16x16x32_bf16 v[74:77], v[232:235], v[216:219], v[74:77]
	v_mfma_f32_16x16x32_bf16 v[42:45], v[232:235], v[220:223], v[42:45]
	v_mfma_f32_16x16x32_bf16 v[10:13], v[232:235], v[224:227], v[10:13]
	s_waitcnt lgkmcnt(1)
	v_mfma_f32_16x16x32_bf16 v[102:105], v[236:239], v[212:215], v[102:105]
	v_mfma_f32_16x16x32_bf16 v[70:73], v[236:239], v[216:219], v[70:73]
	v_mfma_f32_16x16x32_bf16 v[38:41], v[236:239], v[220:223], v[38:41]
	v_mfma_f32_16x16x32_bf16 v[6:9], v[236:239], v[224:227], v[6:9]
	s_waitcnt lgkmcnt(0)
	v_mfma_f32_16x16x32_bf16 v[98:101], v[240:243], v[212:215], v[98:101]
	v_mfma_f32_16x16x32_bf16 v[66:69], v[240:243], v[216:219], v[66:69]
	v_mfma_f32_16x16x32_bf16 v[34:37], v[240:243], v[220:223], v[34:37]
	v_mfma_f32_16x16x32_bf16 v[2:5], v[240:243], v[224:227], v[2:5]
	s_add_i32 s42, s42, 1
	s_cmp_lg_u32 s42, 3
	s_cselect_b32 s42, s42, 0
	s_add_i32 s43, s43, 1
	s_cmp_lg_u32 s43, 3
	s_cselect_b32 s43, s43, 0
	s_setprio 0
	s_add_i32 s20, s20, 1
	s_cmp_lg_u32 s20, 8
	s_cbranch_scc1 .LBB0_1625
	s_branch .LBB0_1631

; template <int OFF> DEVI bf16x8 ldsr(unsigned a) { bf16x8 v; asm volatile("ds_read_b128 %0, %1 offset:%2" : "=v"(v) : "v"(a), "n"(OFF)); return v; }
; #define RAW_BARRIER() do { asm volatile("s_waitcnt lgkmcnt(0)" ::: "memory"); __builtin_amdgcn_s_barrier(); } while (0)
; template <int EPI, int NB>
; DEVI void gemm_tile(const GemmJob& J, int m0, int n0, unsigned char* smem) {
;     ...
;   for (int kt = 0; kt < nk; ++kt) {
;     if (nk - 1 - kt >= S - 2) {
;       if constexpr (NB == 8) asm volatile("s_waitcnt vmcnt(6)" ::: "memory");
;       else                   asm volatile("s_waitcnt vmcnt(8)" ::: "memory");
;     } else {
;       asm volatile("s_waitcnt vmcnt(0)" ::: "memory");
;     }
;     RAW_BARRIER();
;     if (kt + S - 1 < nk) GEMM_ISSUE(kt + S - 1, is);
;     is = (is + 1 == S) ? 0 : is + 1;
;     const unsigned cur = lbase + cs * STG;
;     cs = (cs + 1 == S) ? 0 : cs + 1;
;     bf16x8 af[4], bfr[NB];
;     const unsigned aa = cur + aofs, ba = cur + bofs;
;     af[0] = ldsr<0>(aa); af[1] = ldsr<1024>(aa); af[2] = ldsr<2048>(aa); af[3] = ldsr<3072>(aa);
;     bfr[0] = ldsr<0>(ba); bfr[1] = ldsr<1024>(ba); bfr[2] = ldsr<2048>(ba); bfr[3] = ldsr<3072>(ba);
;     __builtin_amdgcn_s_setprio(1);
; #pragma unroll
;     for (int nb = 0; nb < NB; ++nb) {
;       if (nb == 0) asm volatile("s_waitcnt lgkmcnt(3)" : "+v"(af[0]), "+v"(af[1]), "+v"(af[2]), "+v"(af[3]), "+v"(bfr[0]) :: "memory");
;       else if (nb <= NB - 4) asm volatile("s_waitcnt lgkmcnt(3)" : "+v"(bfr[nb]) :: "memory");
;       else if (nb == NB - 3) asm volatile("s_waitcnt lgkmcnt(2)" : "+v"(bfr[nb]) :: "memory");
;       else if (nb == NB - 2) asm volatile("s_waitcnt lgkmcnt(1)" : "+v"(bfr[nb]) :: "memory");
;       else asm volatile("s_waitcnt lgkmcnt(0)" : "+v"(bfr[nb]) :: "memory");
;       __builtin_amdgcn_sched_barrier(0);
; #pragma unroll
;       for (int mb = 0; mb < 4; ++mb) {
;         if constexpr (SWAP) acc[mb][nb] = __builtin_amdgcn_mfma_f32_16x16x32_bf16(bfr[nb], af[mb], acc[mb][nb], 0, 0, 0);
;         else                acc[mb][nb] = __builtin_amdgcn_mfma_f32_16x16x32_bf16(af[mb], bfr[nb], acc[mb][nb], 0, 0, 0);
;       }
.LBB0_1751:
	s_mul_i32 s1, s43, 0x6000
	v_add_u32_e32 v211, s1, v209
	v_add_u32_e32 v244, s1, v210
	s_mul_i32 m0, s42, 0x6000
	s_add_u32 m0, m0, s0
	s_cmp_gt_u32 s20, 2
	s_cbranch_scc1 .Lgk15_w0
	s_waitcnt vmcnt(6)
.Lgk15_bar:
	s_waitcnt lgkmcnt(0)
	s_barrier
	s_setprio 1
	ds_read_b128 v[212:215], v211 offset:0
	ds_read_b128 v[228:231], v244 offset:0
	ds_read_b128 v[216:219], v211 offset:0x400
	ds_read_b128 v[220:223], v211 offset:0x800
	ds_read_b128 v[224:227], v211 offset:0xc00
	ds_read_b128 v[232:235], v244 offset:0x400
	ds_read_b128 v[236:239], v244 offset:0x800
	ds_read_b128 v[240:243], v244 offset:0xc00
	s_cmp_gt_u32 s20, 1
	s_cbranch_scc1 .Lgk15_tail
	s_waitcnt lgkmcnt(6)
	v_mfma_f32_16x16x32_bf16 v[126:129], v[228:231], v[212:215], v[126:129]
	s_waitcnt lgkmcnt(5)
	v_mfma_f32_16x16x32_bf16 v[94:97], v[228:231], v[216:219], v[94:97]
	s_waitcnt lgkmcnt(4)
	v_mfma_f32_16x16x32_bf16 v[62:65], v[228:231], v[220:223], v[62:65]
	s_waitcnt lgkmcnt(3)
	v_mfma_f32_16x16x32_bf16 v[30:33], v[228:231], v[224:227], v[30:33]
	ds_read_b128 v[228:231], v244 offset:0x1000
	global_load_lds_dwordx4 v182, s[100:101]
	s_add_u32 m0, m0, 0x1000
	s_waitcnt lgkmcnt(3)
	v_mfma_f32_16x16x32_bf16 v[122:125], v[232:235], v[212:215], v[122:125]
	v_mfma_f32_16x16x32_bf16 v[90:93], v[232:235], v[216:219], v[90:93]
	v_mfma_f32_16x16x32_bf16 v[58:61], v[232:235], v[220:223], v[58:61]
	v_mfma_f32_16x16x32_bf16 v[26:29], v[232:235], v[224:227], v[26:29]
	ds_read_b128 v[232:235], v244 offset:0x1400
	global_load_lds_dwordx4 v183, s[100:101]
	s_add_u32 m0, m0, 0x1000
	s_waitcnt lgkmcnt(3)
	v_mfma_f32_16x16x32_bf16 v[118:121], v[236:239], v[212:215], v[118:121]
	v_mfma_f32_16x16x32_bf16 v[86:89], v[236:239], v[216:219], v[86:89]
	v_mfma_f32_16x16x32_bf16 v[54:57], v[236:239], v[220:223], v[54:57]
	v_mfma_f32_16x16x32_bf16 v[22:25], v[236:239], v[224:227], v[22:25]
	ds_read_b128 v[236:239], v244 offset:0x1800
	global_load_lds_dwordx4 v180, vcc
	s_add_u32 m0, m0, 0x1000
	s_waitcnt lgkmcnt(3)
	v_mfma_f32_16x16x32_bf16 v[114:117], v[240:243], v[212:215], v[114:117]
	v_mfma_f32_16x16x32_bf16 v[82:85], v[240:243], v[216:219], v[82:85]
	v_mfma_f32_16x16x32_bf16 v[50:53], v[240:243], v[220:223], v[50:53]
	v_mfma_f32_16x16x32_bf16 v[18:21], v[240:243], v[224:227], v[18:21]
	ds_read_b128 v[240:243], v244 offset:0x1c00
	global_load_lds_dwordx4 v181, vcc
	s_add_u32 m0, m0, 0x1000
	s_waitcnt lgkmcnt(3)
	v_mfma_f32_16x16x32_bf16 v[110:113], v[228:231], v[212:215], v[110:113]
	v_mfma_f32_16x16x32_bf16 v[78:81], v[228:231], v[216:219], v[78:81]
	v_mfma_f32_16x16x32_bf16 v[46:49], v[228:231], v[220:223], v[46:49]
	v_mfma_f32_16x16x32_bf16 v[14:17], v[228:231], v[224:227], v[14:17]
	global_load_lds_dwordx4 v253, vcc
	s_add_u32 m0, m0, 0x1000
	s_waitcnt lgkmcnt(2)
	v_mfma_f32_16x16x32_bf16 v[106:109], v[232:235], v[212:215], v[106:109]
	v_mfma_f32_16x16x32_bf16 v[74:77], v[232:235], v[216:219], v[74:77]
	v_mfma_f32_16x16x32_bf16 v[42:45], v[232:235], v[220:223], v[42:45]
	v_mfma_f32_16x16x32_bf16 v[10:13], v[232:235], v[224:227], v[10:13]
	global_load_lds_dwordx4 v254, vcc
	s_waitcnt lgkmcnt(1)
	v_mfma_f32_16x16x32_bf16 v[102:105], v[236:239], v[212:215], v[102:105]
	v_mfma_f32_16x16x32_bf16 v[70:73], v[236:239], v[216:219], v[70:73]
	v_mfma_f32_16x16x32_bf16 v[38:41], v[236:239], v[220:223], v[38:41]
	v_mfma_f32_16x16x32_bf16 v[6:9], v[236:239], v[224:227], v[6:9]
	s_waitcnt lgkmcnt(0)
	v_mfma_f32_16x16x32_bf16 v[98:101], v[240:243], v[212:215], v[98:101]
	v_mfma_f32_16x16x32_bf16 v[66:69], v[240:243], v[216:219], v[66:69]
	v_mfma_f32_16x16x32_bf16 v[34:37], v[240:243], v[220:223], v[34:37]
	v_mfma_f32_16x16x32_bf16 v[2:5], v[240:243], v[224:227], v[2:5]
	s_add_u32 s100, s100, 0x40
	s_addc_u32 s101, s101, 0
	s_add_u32 vcc_lo, vcc_lo, s22
	s_addc_u32 vcc_hi, vcc_hi, s23
	s_add_i32 s42, s42, 1
	s_cmp_lg_u32 s42, 3
	s_cselect_b32 s42, s42, 0
	s_add_i32 s43, s43, 1
	s_cmp_lg_u32 s43, 3
	s_cselect_b32 s43, s43, 0
	s_setprio 0
	s_add_i32 s20, s20, 1
	s_branch .LBB0_1751
.Lgk15_tail:
	s_waitcnt lgkmcnt(6)
	v_mfma_f32_16x16x32_bf16 v[126:129], v[228:231], v[212:215], v[126:129]
	s_waitcnt lgkmcnt(5)
	v_mfma_f32_16x16x32_bf16 v[94:97], v[228:231], v[216:219], v[94:97]
	s_waitcnt lgkmcnt(4)
	v_mfma_f32_16x16x32_bf16 v[62:65], v[228:231], v[220:223], v[62:65]
	s_waitcnt lgkmcnt(3)
	v_mfma_f32_16x16x32_bf16 v[30:33], v[228:231], v[224:227], v[30:33]
	ds_read_b128 v[228:231], v244 offset:0x1000
	s_waitcnt lgkmcnt(3)
	v_mfma_f32_16x16x32_bf16 v[122:125], v[232:235], v[212:215], v[122:125]
	v_mfma_f32_16x16x32_bf16 v[90:93], v[232:235], v[216:219], v[90:93]
	v_mfma_f32_16x16x32_bf16 v[58:61], v[232:235], v[220:223], v[58:61]
	v_mfma_f32_16x16x32_bf16 v[26:29], v[232:235], v[224:227], v[26:29]
	ds_read_b128 v[232:235], v244 offset:0x1400
	s_waitcnt lgkmcnt(3)
	v_mfma_f32_16x16x32_bf16 v[118:121], v[236:239], v[212:215], v[118:121]
	v_mfma_f32_16x16x32_bf16 v[86:89], v[236:239], v[216:219], v[86:89]
	v_mfma_f32_16x16x32_bf16 v[54:57], v[236:239], v[220:223], v[54:57]
	v_mfma_f32_16x16x32_bf16 v[22:25], v[236:239], v[224:227], v[22:25]
	ds_read_b128 v[236:239], v244 offset:0x1800
	s_waitcnt lgkmcnt(3)
	v_mfma_f32_16x16x32_bf16 v[114:117], v[240:243], v[212:215], v[114:117]
	v_mfma_f32_16x16x32_bf16 v[82:85], v[240:243], v[216:219], v[82:85]
	v_mfma_f32_16x16x32_bf16 v[50:53], v[240:243], v[220:223], v[50:53]
	v_mfma_f32_16x16x32_bf16 v[18:21], v[240:243], v[224:227], v[18:21]
	ds_read_b128 v[240:243], v244 offset:0x1c00
	s_waitcnt lgkmcnt(3)
	v_mfma_f32_16x16x32_bf16 v[110:113], v[228:231], v[212:215], v[110:113]
	v_mfma_f32_16x16x32_bf16 v[78:81], v[228:231], v[216:219], v[78:81]
	v_mfma_f32_16x16x32_bf16 v[46:49], v[228:231], v[220:223], v[46:49]
	v_mfma_f32_16x16x32_bf16 v[14:17], v[228:231], v[224:227], v[14:17]
	s_waitcnt lgkmcnt(2)
	v_mfma_f32_16x16x32_bf16 v[106:109], v[232:235], v[212:215], v[106:109]
	v_mfma_f32_16x16x32_bf16 v[74:77], v[232:235], v[216:219], v[74:77]
	v_mfma_f32_16x16x32_bf16 v[42:45], v[232:235], v[220:223], v[42:45]
	v_mfma_f32_16x16x32_bf16 v[10:13], v[232:235], v[224:227], v[10:13]
	s_waitcnt lgkmcnt(1)
	v_mfma_f32_16x16x32_bf16 v[102:105], v[236:239], v[212:215], v[102:105]
	v_mfma_f32_16x16x32_bf16 v[70:73], v[236:239], v[216:219], v[70:73]
	v_mfma_f32_16x16x32_bf16 v[38:41], v[236:239], v[220:223], v[38:41]
	v_mfma_f32_16x16x32_bf16 v[6:9], v[236:239], v[224:227], v[6:9]
	s_waitcnt lgkmcnt(0)
	v_mfma_f32_16x16x32_bf16 v[98:101], v[240:243], v[212:215], v[98:101]
	v_mfma_f32_16x16x32_bf16 v[66:69], v[240:243], v[216:219], v[66:69]
	v_mfma_f32_16x16x32_bf16 v[34:37], v[240:243], v[220:223], v[34:37]
	v_mfma_f32_16x16x32_bf16 v[2:5], v[240:243], v[224:227], v[2:5]
	s_add_i32 s42, s42, 1
	s_cmp_lg_u32 s42, 3
	s_cselect_b32 s42, s42, 0
	s_add_i32 s43, s43, 1
	s_cmp_lg_u32 s43, 3
	s_cselect_b32 s43, s43, 0
	s_setprio 0
	s_add_i32 s20, s20, 1
	s_cmp_lg_u32 s20, 4
	s_cbranch_scc1 .LBB0_1751
	s_branch .LBB0_1757

; template <int OFF> DEVI bf16x8 ldsr(unsigned a) { bf16x8 v; asm volatile("ds_read_b128 %0, %1 offset:%2" : "=v"(v) : "v"(a), "n"(OFF)); return v; }
; #define RAW_BARRIER() do { asm volatile("s_waitcnt lgkmcnt(0)" ::: "memory"); __builtin_amdgcn_s_barrier(); } while (0)
; template <int EPI, int NB>
; DEVI void gemm_tile(const GemmJob& J, int m0, int n0, unsigned char* smem) {
;     ...
;   for (int kt = 0; kt < nk; ++kt) {
;     if (nk - 1 - kt >= S - 2) {
;       if constexpr (NB == 8) asm volatile("s_waitcnt vmcnt(6)" ::: "memory");
;       else                   asm volatile("s_waitcnt vmcnt(8)" ::: "memory");
;     } else {
;       asm volatile("s_waitcnt vmcnt(0)" ::: "memory");
;     }
;     RAW_BARRIER();
;     if (kt + S - 1 < nk) GEMM_ISSUE(kt + S - 1, is);
;     is = (is + 1 == S) ? 0 : is + 1;
;     const unsigned cur = lbase + cs * STG;
;     cs = (cs + 1 == S) ? 0 : cs + 1;
;     bf16x8 af[4], bfr[NB];
;     const unsigned aa = cur + aofs, ba = cur + bofs;
;     af[0] = ldsr<0>(aa); af[1] = ldsr<1024>(aa); af[2] = ldsr<2048>(aa); af[3] = ldsr<3072>(aa);
;     bfr[0] = ldsr<0>(ba); bfr[1] = ldsr<1024>(ba); bfr[2] = ldsr<2048>(ba); bfr[3] = ldsr<3072>(ba);
;     __builtin_amdgcn_s_setprio(1);
; #pragma unroll
;     for (int nb = 0; nb < NB; ++nb) {
;       if (nb == 0) asm volatile("s_waitcnt lgkmcnt(3)" : "+v"(af[0]), "+v"(af[1]), "+v"(af[2]), "+v"(af[3]), "+v"(bfr[0]) :: "memory");
;       else if (nb <= NB - 4) asm volatile("s_waitcnt lgkmcnt(3)" : "+v"(bfr[nb]) :: "memory");
;       else if (nb == NB - 3) asm volatile("s_waitcnt lgkmcnt(2)" : "+v"(bfr[nb]) :: "memory");
;       else if (nb == NB - 2) asm volatile("s_waitcnt lgkmcnt(1)" : "+v"(bfr[nb]) :: "memory");
;       else asm volatile("s_waitcnt lgkmcnt(0)" : "+v"(bfr[nb]) :: "memory");
;       __builtin_amdgcn_sched_barrier(0);
; #pragma unroll
;       for (int mb = 0; mb < 4; ++mb) {
;         if constexpr (SWAP) acc[mb][nb] = __builtin_amdgcn_mfma_f32_16x16x32_bf16(bfr[nb], af[mb], acc[mb][nb], 0, 0, 0);
;         else                acc[mb][nb] = __builtin_amdgcn_mfma_f32_16x16x32_bf16(af[mb], bfr[nb], acc[mb][nb], 0, 0, 0);
;       }
.LBB0_1824:
	s_mul_i32 s1, s43, 0x6000
	v_add_u32_e32 v211, s1, v209
	v_add_u32_e32 v244, s1, v210
	s_mul_i32 m0, s42, 0x6000
	s_add_u32 m0, m0, s0
	s_cmp_gt_u32 s3, 6
	s_cbranch_scc1 .Lgk16_w0
	s_waitcnt vmcnt(6)
.Lgk16_bar:
	s_waitcnt lgkmcnt(0)
	s_barrier
	s_setprio 1
	ds_read_b128 v[212:215], v211 offset:0
	ds_read_b128 v[228:231], v244 offset:0
	ds_read_b128 v[216:219], v211 offset:0x400
	ds_read_b128 v[220:223], v211 offset:0x800
	ds_read_b128 v[224:227], v211 offset:0xc00
	ds_read_b128 v[232:235], v244 offset:0x400
	ds_read_b128 v[236:239], v244 offset:0x800
	ds_read_b128 v[240:243], v244 offset:0xc00
	s_cmp_gt_u32 s3, 5
	s_cbranch_scc1 .Lgk16_tail
	s_waitcnt lgkmcnt(6)
	v_mfma_f32_16x16x32_bf16 v[126:129], v[228:231], v[212:215], v[126:129]
	s_waitcnt lgkmcnt(5)
	v_mfma_f32_16x16x32_bf16 v[94:97], v[228:231], v[216:219], v[94:97]
	s_waitcnt lgkmcnt(4)
	v_mfma_f32_16x16x32_bf16 v[62:65], v[228:231], v[220:223], v[62:65]
	s_waitcnt lgkmcnt(3)
	v_mfma_f32_16x16x32_bf16 v[30:33], v[228:231], v[224:227], v[30:33]
	ds_read_b128 v[228:231], v244 offset:0x1000
	global_load_lds_dwordx4 v182, s[100:101]
	s_add_u32 m0, m0, 0x1000
	s_waitcnt lgkmcnt(3)
	v_mfma_f32_16x16x32_bf16 v[122:125], v[232:235], v[212:215], v[122:125]
	v_mfma_f32_16x16x32_bf16 v[90:93], v[232:235], v[216:219], v[90:93]
	v_mfma_f32_16x16x32_bf16 v[58:61], v[232:235], v[220:223], v[58:61]
	v_mfma_f32_16x16x32_bf16 v[26:29], v[232:235], v[224:227], v[26:29]
	ds_read_b128 v[232:235], v244 offset:0x1400
	global_load_lds_dwordx4 v183, s[100:101]
	s_add_u32 m0, m0, 0x1000
	s_waitcnt lgkmcnt(3)
	v_mfma_f32_16x16x32_bf16 v[118:121], v[236:239], v[212:215], v[118:121]
	v_mfma_f32_16x16x32_bf16 v[86:89], v[236:239], v[216:219], v[86:89]
	v_mfma_f32_16x16x32_bf16 v[54:57], v[236:239], v[220:223], v[54:57]
	v_mfma_f32_16x16x32_bf16 v[22:25], v[236:239], v[224:227], v[22:25]
	ds_read_b128 v[236:239], v244 offset:0x1800
	global_load_lds_dwordx4 v180, vcc
	s_add_u32 m0, m0, 0x1000
	s_waitcnt lgkmcnt(3)
	v_mfma_f32_16x16x32_bf16 v[114:117], v[240:243], v[212:215], v[114:117]
	v_mfma_f32_16x16x32_bf16 v[82:85], v[240:243], v[216:219], v[82:85]
	v_mfma_f32_16x16x32_bf16 v[50:53], v[240:243], v[220:223], v[50:53]
	v_mfma_f32_16x16x32_bf16 v[18:21], v[240:243], v[224:227], v[18:21]
	ds_read_b128 v[240:243], v244 offset:0x1c00
	global_load_lds_dwordx4 v181, vcc
	s_add_u32 m0, m0, 0x1000
	s_waitcnt lgkmcnt(3)
	v_mfma_f32_16x16x32_bf16 v[110:113], v[228:231], v[212:215], v[110:113]
	v_mfma_f32_16x16x32_bf16 v[78:81], v[228:231], v[216:219], v[78:81]
	v_mfma_f32_16x16x32_bf16 v[46:49], v[228:231], v[220:223], v[46:49]
	v_mfma_f32_16x16x32_bf16 v[14:17], v[228:231], v[224:227], v[14:17]
	global_load_lds_dwordx4 v253, vcc
	s_add_u32 m0, m0, 0x1000
	s_waitcnt lgkmcnt(2)
	v_mfma_f32_16x16x32_bf16 v[106:109], v[232:235], v[212:215], v[106:109]
	v_mfma_f32_16x16x32_bf16 v[74:77], v[232:235], v[216:219], v[74:77]
	v_mfma_f32_16x16x32_bf16 v[42:45], v[232:235], v[220:223], v[42:45]
	v_mfma_f32_16x16x32_bf16 v[10:13], v[232:235], v[224:227], v[10:13]
	global_load_lds_dwordx4 v254, vcc
	s_waitcnt lgkmcnt(1)
	v_mfma_f32_16x16x32_bf16 v[102:105], v[236:239], v[212:215], v[102:105]
	v_mfma_f32_16x16x32_bf16 v[70:73], v[236:239], v[216:219], v[70:73]
	v_mfma_f32_16x16x32_bf16 v[38:41], v[236:239], v[220:223], v[38:41]
	v_mfma_f32_16x16x32_bf16 v[6:9], v[236:239], v[224:227], v[6:9]
	s_waitcnt lgkmcnt(0)
	v_mfma_f32_16x16x32_bf16 v[98:101], v[240:243], v[212:215], v[98:101]
	v_mfma_f32_16x16x32_bf16 v[66:69], v[240:243], v[216:219], v[66:69]
	v_mfma_f32_16x16x32_bf16 v[34:37], v[240:243], v[220:223], v[34:37]
	v_mfma_f32_16x16x32_bf16 v[2:5], v[240:243], v[224:227], v[2:5]
	s_add_u32 s100, s100, 0x40
	s_addc_u32 s101, s101, 0
	s_add_u32 vcc_lo, vcc_lo, s86
	s_addc_u32 vcc_hi, vcc_hi, s87
	s_add_i32 s42, s42, 1
	s_cmp_lg_u32 s42, 3
	s_cselect_b32 s42, s42, 0
	s_add_i32 s43, s43, 1
	s_cmp_lg_u32 s43, 3
	s_cselect_b32 s43, s43, 0
	s_setprio 0
	s_add_i32 s3, s3, 1
	s_branch .LBB0_1824
.Lgk16_tail:
	s_waitcnt lgkmcnt(6)
	v_mfma_f32_16x16x32_bf16 v[126:129], v[228:231], v[212:215], v[126:129]
	s_waitcnt lgkmcnt(5)
	v_mfma_f32_16x16x32_bf16 v[94:97], v[228:231], v[216:219], v[94:97]
	s_waitcnt lgkmcnt(4)
	v_mfma_f32_16x16x32_bf16 v[62:65], v[228:231], v[220:223], v[62:65]
	s_waitcnt lgkmcnt(3)
	v_mfma_f32_16x16x32_bf16 v[30:33], v[228:231], v[224:227], v[30:33]
	ds_read_b128 v[228:231], v244 offset:0x1000
	s_waitcnt lgkmcnt(3)
	v_mfma_f32_16x16x32_bf16 v[122:125], v[232:235], v[212:215], v[122:125]
	v_mfma_f32_16x16x32_bf16 v[90:93], v[232:235], v[216:219], v[90:93]
	v_mfma_f32_16x16x32_bf16 v[58:61], v[232:235], v[220:223], v[58:61]
	v_mfma_f32_16x16x32_bf16 v[26:29], v[232:235], v[224:227], v[26:29]
	ds_read_b128 v[232:235], v244 offset:0x1400
	s_waitcnt lgkmcnt(3)
	v_mfma_f32_16x16x32_bf16 v[118:121], v[236:239], v[212:215], v[118:121]
	v_mfma_f32_16x16x32_bf16 v[86:89], v[236:239], v[216:219], v[86:89]
	v_mfma_f32_16x16x32_bf16 v[54:57], v[236:239], v[220:223], v[54:57]
	v_mfma_f32_16x16x32_bf16 v[22:25], v[236:239], v[224:227], v[22:25]
	ds_read_b128 v[236:239], v244 offset:0x1800
	s_waitcnt lgkmcnt(3)
	v_mfma_f32_16x16x32_bf16 v[114:117], v[240:243], v[212:215], v[114:117]
	v_mfma_f32_16x16x32_bf16 v[82:85], v[240:243], v[216:219], v[82:85]
	v_mfma_f32_16x16x32_bf16 v[50:53], v[240:243], v[220:223], v[50:53]
	v_mfma_f32_16x16x32_bf16 v[18:21], v[240:243], v[224:227], v[18:21]
	ds_read_b128 v[240:243], v244 offset:0x1c00
	s_waitcnt lgkmcnt(3)
	v_mfma_f32_16x16x32_bf16 v[110:113], v[228:231], v[212:215], v[110:113]
	v_mfma_f32_16x16x32_bf16 v[78:81], v[228:231], v[216:219], v[78:81]
	v_mfma_f32_16x16x32_bf16 v[46:49], v[228:231], v[220:223], v[46:49]
	v_mfma_f32_16x16x32_bf16 v[14:17], v[228:231], v[224:227], v[14:17]
	s_waitcnt lgkmcnt(2)
	v_mfma_f32_16x16x32_bf16 v[106:109], v[232:235], v[212:215], v[106:109]
	v_mfma_f32_16x16x32_bf16 v[74:77], v[232:235], v[216:219], v[74:77]
	v_mfma_f32_16x16x32_bf16 v[42:45], v[232:235], v[220:223], v[42:45]
	v_mfma_f32_16x16x32_bf16 v[10:13], v[232:235], v[224:227], v[10:13]
	s_waitcnt lgkmcnt(1)
	v_mfma_f32_16x16x32_bf16 v[102:105], v[236:239], v[212:215], v[102:105]
	v_mfma_f32_16x16x32_bf16 v[70:73], v[236:239], v[216:219], v[70:73]
	v_mfma_f32_16x16x32_bf16 v[38:41], v[236:239], v[220:223], v[38:41]
	v_mfma_f32_16x16x32_bf16 v[6:9], v[236:239], v[224:227], v[6:9]
	s_waitcnt lgkmcnt(0)
	v_mfma_f32_16x16x32_bf16 v[98:101], v[240:243], v[212:215], v[98:101]
	v_mfma_f32_16x16x32_bf16 v[66:69], v[240:243], v[216:219], v[66:69]
	v_mfma_f32_16x16x32_bf16 v[34:37], v[240:243], v[220:223], v[34:37]
	v_mfma_f32_16x16x32_bf16 v[2:5], v[240:243], v[224:227], v[2:5]
	s_add_i32 s42, s42, 1
	s_cmp_lg_u32 s42, 3
	s_cselect_b32 s42, s42, 0
	s_add_i32 s43, s43, 1
	s_cmp_lg_u32 s43, 3
	s_cselect_b32 s43, s43, 0
	s_setprio 0
	s_add_i32 s3, s3, 1
	s_cmp_lg_u32 s3, 8
	s_cbranch_scc1 .LBB0_1824
	s_branch .LBB0_1830

; template <int OFF> DEVI bf16x8 ldsr(unsigned a) { bf16x8 v; asm volatile("ds_read_b128 %0, %1 offset:%2" : "=v"(v) : "v"(a), "n"(OFF)); return v; }
; #define RAW_BARRIER() do { asm volatile("s_waitcnt lgkmcnt(0)" ::: "memory"); __builtin_amdgcn_s_barrier(); } while (0)
; template <int EPI, int NB>
; DEVI void gemm_tile(const GemmJob& J, int m0, int n0, unsigned char* smem) {
;     ...
;   for (int kt = 0; kt < nk; ++kt) {
;     if (nk - 1 - kt >= S - 2) {
;       if constexpr (NB == 8) asm volatile("s_waitcnt vmcnt(6)" ::: "memory");
;       else                   asm volatile("s_waitcnt vmcnt(8)" ::: "memory");
;     } else {
;       asm volatile("s_waitcnt vmcnt(0)" ::: "memory");
;     }
;     RAW_BARRIER();
;     if (kt + S - 1 < nk) GEMM_ISSUE(kt + S - 1, is);
;     is = (is + 1 == S) ? 0 : is + 1;
;     const unsigned cur = lbase + cs * STG;
;     cs = (cs + 1 == S) ? 0 : cs + 1;
;     bf16x8 af[4], bfr[NB];
;     const unsigned aa = cur + aofs, ba = cur + bofs;
;     af[0] = ldsr<0>(aa); af[1] = ldsr<1024>(aa); af[2] = ldsr<2048>(aa); af[3] = ldsr<3072>(aa);
;     bfr[0] = ldsr<0>(ba); bfr[1] = ldsr<1024>(ba); bfr[2] = ldsr<2048>(ba); bfr[3] = ldsr<3072>(ba);
;     __builtin_amdgcn_s_setprio(1);
; #pragma unroll
;     for (int nb = 0; nb < NB; ++nb) {
;       if (nb == 0) asm volatile("s_waitcnt lgkmcnt(3)" : "+v"(af[0]), "+v"(af[1]), "+v"(af[2]), "+v"(af[3]), "+v"(bfr[0]) :: "memory");
;       else if (nb <= NB - 4) asm volatile("s_waitcnt lgkmcnt(3)" : "+v"(bfr[nb]) :: "memory");
;       else if (nb == NB - 3) asm volatile("s_waitcnt lgkmcnt(2)" : "+v"(bfr[nb]) :: "memory");
;       else if (nb == NB - 2) asm volatile("s_waitcnt lgkmcnt(1)" : "+v"(bfr[nb]) :: "memory");
;       else asm volatile("s_waitcnt lgkmcnt(0)" : "+v"(bfr[nb]) :: "memory");
;       __builtin_amdgcn_sched_barrier(0);
; #pragma unroll
;       for (int mb = 0; mb < 4; ++mb) {
;         if constexpr (SWAP) acc[mb][nb] = __builtin_amdgcn_mfma_f32_16x16x32_bf16(bfr[nb], af[mb], acc[mb][nb], 0, 0, 0);
;         else                acc[mb][nb] = __builtin_amdgcn_mfma_f32_16x16x32_bf16(af[mb], bfr[nb], acc[mb][nb], 0, 0, 0);
.LBB0_1950:
	s_mul_i32 s1, s43, 0x6000
	v_add_u32_e32 v222, s1, v208
	v_add_u32_e32 v242, s1, v209
	s_mul_i32 m0, s42, 0x6000
	s_add_u32 m0, m0, s0
	s_cmp_gt_u32 s20, 2
	s_cbranch_scc1 .Lgk17_w0
	s_waitcnt vmcnt(6)
.Lgk17_bar:
	s_waitcnt lgkmcnt(0)
	s_barrier
	s_setprio 1
	ds_read_b128 v[210:213], v222 offset:0
	ds_read_b128 v[226:229], v242 offset:0
	ds_read_b128 v[214:217], v222 offset:0x400
	ds_read_b128 v[218:221], v222 offset:0x800
	ds_read_b128 v[222:225], v222 offset:0xc00
	ds_read_b128 v[230:233], v242 offset:0x400
	ds_read_b128 v[234:237], v242 offset:0x800
	ds_read_b128 v[238:241], v242 offset:0xc00
	s_cmp_gt_u32 s20, 1
	s_cbranch_scc1 .Lgk17_tail
	s_waitcnt lgkmcnt(6)
	v_mfma_f32_16x16x32_bf16 v[126:129], v[210:213], v[226:229], v[126:129]
	s_waitcnt lgkmcnt(5)
	v_mfma_f32_16x16x32_bf16 v[94:97], v[214:217], v[226:229], v[94:97]
	s_waitcnt lgkmcnt(4)
	v_mfma_f32_16x16x32_bf16 v[62:65], v[218:221], v[226:229], v[62:65]
	s_waitcnt lgkmcnt(3)
	v_mfma_f32_16x16x32_bf16 v[30:33], v[222:225], v[226:229], v[30:33]
	ds_read_b128 v[226:229], v242 offset:0x1000
	global_load_lds_dwordx4 v182, s[100:101]
	s_add_u32 m0, m0, 0x1000
	s_waitcnt lgkmcnt(3)
	v_mfma_f32_16x16x32_bf16 v[122:125], v[210:213], v[230:233], v[122:125]
	v_mfma_f32_16x16x32_bf16 v[90:93], v[214:217], v[230:233], v[90:93]
	v_mfma_f32_16x16x32_bf16 v[58:61], v[218:221], v[230:233], v[58:61]
	v_mfma_f32_16x16x32_bf16 v[26:29], v[222:225], v[230:233], v[26:29]
	ds_read_b128 v[230:233], v242 offset:0x1400
	global_load_lds_dwordx4 v183, s[100:101]
	s_add_u32 m0, m0, 0x1000
	s_waitcnt lgkmcnt(3)
	v_mfma_f32_16x16x32_bf16 v[118:121], v[210:213], v[234:237], v[118:121]
	v_mfma_f32_16x16x32_bf16 v[86:89], v[214:217], v[234:237], v[86:89]
	v_mfma_f32_16x16x32_bf16 v[54:57], v[218:221], v[234:237], v[54:57]
	v_mfma_f32_16x16x32_bf16 v[22:25], v[222:225], v[234:237], v[22:25]
	ds_read_b128 v[234:237], v242 offset:0x1800
	global_load_lds_dwordx4 v180, vcc
	s_add_u32 m0, m0, 0x1000
	s_waitcnt lgkmcnt(3)
	v_mfma_f32_16x16x32_bf16 v[114:117], v[210:213], v[238:241], v[114:117]
	v_mfma_f32_16x16x32_bf16 v[82:85], v[214:217], v[238:241], v[82:85]
	v_mfma_f32_16x16x32_bf16 v[50:53], v[218:221], v[238:241], v[50:53]
	v_mfma_f32_16x16x32_bf16 v[18:21], v[222:225], v[238:241], v[18:21]
	ds_read_b128 v[238:241], v242 offset:0x1c00
	global_load_lds_dwordx4 v181, vcc
	s_add_u32 m0, m0, 0x1000
	s_waitcnt lgkmcnt(3)
	v_mfma_f32_16x16x32_bf16 v[110:113], v[210:213], v[226:229], v[110:113]
	v_mfma_f32_16x16x32_bf16 v[78:81], v[214:217], v[226:229], v[78:81]
	v_mfma_f32_16x16x32_bf16 v[46:49], v[218:221], v[226:229], v[46:49]
	v_mfma_f32_16x16x32_bf16 v[14:17], v[222:225], v[226:229], v[14:17]
	global_load_lds_dwordx4 v253, vcc
	s_add_u32 m0, m0, 0x1000
	s_waitcnt lgkmcnt(2)
	v_mfma_f32_16x16x32_bf16 v[106:109], v[210:213], v[230:233], v[106:109]
	v_mfma_f32_16x16x32_bf16 v[74:77], v[214:217], v[230:233], v[74:77]
	v_mfma_f32_16x16x32_bf16 v[42:45], v[218:221], v[230:233], v[42:45]
	v_mfma_f32_16x16x32_bf16 v[10:13], v[222:225], v[230:233], v[10:13]
	global_load_lds_dwordx4 v254, vcc
	s_waitcnt lgkmcnt(1)
	v_mfma_f32_16x16x32_bf16 v[102:105], v[210:213], v[234:237], v[102:105]
	v_mfma_f32_16x16x32_bf16 v[70:73], v[214:217], v[234:237], v[70:73]
	v_mfma_f32_16x16x32_bf16 v[38:41], v[218:221], v[234:237], v[38:41]
	v_mfma_f32_16x16x32_bf16 v[6:9], v[222:225], v[234:237], v[6:9]
	s_waitcnt lgkmcnt(0)
	v_mfma_f32_16x16x32_bf16 v[98:101], v[210:213], v[238:241], v[98:101]
	v_mfma_f32_16x16x32_bf16 v[66:69], v[214:217], v[238:241], v[66:69]
	v_mfma_f32_16x16x32_bf16 v[34:37], v[218:221], v[238:241], v[34:37]
	v_mfma_f32_16x16x32_bf16 v[2:5], v[222:225], v[238:241], v[2:5]
	s_add_u32 s100, s100, 0x40
	s_addc_u32 s101, s101, 0
	s_add_u32 vcc_lo, vcc_lo, s22
	s_addc_u32 vcc_hi, vcc_hi, s23
	s_add_i32 s42, s42, 1
	s_cmp_lg_u32 s42, 3
	s_cselect_b32 s42, s42, 0
	s_add_i32 s43, s43, 1
	s_cmp_lg_u32 s43, 3
	s_cselect_b32 s43, s43, 0
	s_setprio 0
	s_add_i32 s20, s20, 1
	s_branch .LBB0_1950
.Lgk17_tail:
	s_waitcnt lgkmcnt(6)
	v_mfma_f32_16x16x32_bf16 v[126:129], v[210:213], v[226:229], v[126:129]
	s_waitcnt lgkmcnt(5)
	v_mfma_f32_16x16x32_bf16 v[94:97], v[214:217], v[226:229], v[94:97]
	s_waitcnt lgkmcnt(4)
	v_mfma_f32_16x16x32_bf16 v[62:65], v[218:221], v[226:229], v[62:65]
	s_waitcnt lgkmcnt(3)
	v_mfma_f32_16x16x32_bf16 v[30:33], v[222:225], v[226:229], v[30:33]
	ds_read_b128 v[226:229], v242 offset:0x1000
	s_waitcnt lgkmcnt(3)
	v_mfma_f32_16x16x32_bf16 v[122:125], v[210:213], v[230:233], v[122:125]
	v_mfma_f32_16x16x32_bf16 v[90:93], v[214:217], v[230:233], v[90:93]
	v_mfma_f32_16x16x32_bf16 v[58:61], v[218:221], v[230:233], v[58:61]
	v_mfma_f32_16x16x32_bf16 v[26:29], v[222:225], v[230:233], v[26:29]
	ds_read_b128 v[230:233], v242 offset:0x1400
	s_waitcnt lgkmcnt(3)
	v_mfma_f32_16x16x32_bf16 v[118:121], v[210:213], v[234:237], v[118:121]
	v_mfma_f32_16x16x32_bf16 v[86:89], v[214:217], v[234:237], v[86:89]
	v_mfma_f32_16x16x32_bf16 v[54:57], v[218:221], v[234:237], v[54:57]
	v_mfma_f32_16x16x32_bf16 v[22:25], v[222:225], v[234:237], v[22:25]
	ds_read_b128 v[234:237], v242 offset:0x1800
	s_waitcnt lgkmcnt(3)
	v_mfma_f32_16x16x32_bf16 v[114:117], v[210:213], v[238:241], v[114:117]
	v_mfma_f32_16x16x32_bf16 v[82:85], v[214:217], v[238:241], v[82:85]
	v_mfma_f32_16x16x32_bf16 v[50:53], v[218:221], v[238:241], v[50:53]
	v_mfma_f32_16x16x32_bf16 v[18:21], v[222:225], v[238:241], v[18:21]
	ds_read_b128 v[238:241], v242 offset:0x1c00
	s_waitcnt lgkmcnt(3)
	v_mfma_f32_16x16x32_bf16 v[110:113], v[210:213], v[226:229], v[110:113]
	v_mfma_f32_16x16x32_bf16 v[78:81], v[214:217], v[226:229], v[78:81]
	v_mfma_f32_16x16x32_bf16 v[46:49], v[218:221], v[226:229], v[46:49]
	v_mfma_f32_16x16x32_bf16 v[14:17], v[222:225], v[226:229], v[14:17]
	s_waitcnt lgkmcnt(2)
	v_mfma_f32_16x16x32_bf16 v[106:109], v[210:213], v[230:233], v[106:109]
	v_mfma_f32_16x16x32_bf16 v[74:77], v[214:217], v[230:233], v[74:77]
	v_mfma_f32_16x16x32_bf16 v[42:45], v[218:221], v[230:233], v[42:45]
	v_mfma_f32_16x16x32_bf16 v[10:13], v[222:225], v[230:233], v[10:13]
	s_waitcnt lgkmcnt(1)
	v_mfma_f32_16x16x32_bf16 v[102:105], v[210:213], v[234:237], v[102:105]
	v_mfma_f32_16x16x32_bf16 v[70:73], v[214:217], v[234:237], v[70:73]
	v_mfma_f32_16x16x32_bf16 v[38:41], v[218:221], v[234:237], v[38:41]
	v_mfma_f32_16x16x32_bf16 v[6:9], v[222:225], v[234:237], v[6:9]
	s_waitcnt lgkmcnt(0)
	v_mfma_f32_16x16x32_bf16 v[98:101], v[210:213], v[238:241], v[98:101]
	v_mfma_f32_16x16x32_bf16 v[66:69], v[214:217], v[238:241], v[66:69]
	v_mfma_f32_16x16x32_bf16 v[34:37], v[218:221], v[238:241], v[34:37]
	v_mfma_f32_16x16x32_bf16 v[2:5], v[222:225], v[238:241], v[2:5]
	s_add_i32 s42, s42, 1
	s_cmp_lg_u32 s42, 3
	s_cselect_b32 s42, s42, 0
	s_add_i32 s43, s43, 1
	s_cmp_lg_u32 s43, 3
	s_cselect_b32 s43, s43, 0
	s_setprio 0
	s_add_i32 s20, s20, 1
	s_cmp_lg_u32 s20, 4
	s_cbranch_scc1 .LBB0_1950
	s_branch .LBB0_1956

; template <int OFF> DEVI bf16x8 ldsr(unsigned a) { bf16x8 v; asm volatile("ds_read_b128 %0, %1 offset:%2" : "=v"(v) : "v"(a), "n"(OFF)); return v; }
; #define RAW_BARRIER() do { asm volatile("s_waitcnt lgkmcnt(0)" ::: "memory"); __builtin_amdgcn_s_barrier(); } while (0)
; template <int EPI, int NB>
; DEVI void gemm_tile(const GemmJob& J, int m0, int n0, unsigned char* smem) {
;     ...
;   for (int kt = 0; kt < nk; ++kt) {
;     if (nk - 1 - kt >= S - 2) {
;       if constexpr (NB == 8) asm volatile("s_waitcnt vmcnt(6)" ::: "memory");
;       else                   asm volatile("s_waitcnt vmcnt(8)" ::: "memory");
;     } else {
;       asm volatile("s_waitcnt vmcnt(0)" ::: "memory");
;     }
;     RAW_BARRIER();
;     if (kt + S - 1 < nk) GEMM_ISSUE(kt + S - 1, is);
;     is = (is + 1 == S) ? 0 : is + 1;
;     const unsigned cur = lbase + cs * STG;
;     cs = (cs + 1 == S) ? 0 : cs + 1;
;     bf16x8 af[4], bfr[NB];
;     const unsigned aa = cur + aofs, ba = cur + bofs;
;     af[0] = ldsr<0>(aa); af[1] = ldsr<1024>(aa); af[2] = ldsr<2048>(aa); af[3] = ldsr<3072>(aa);
;     bfr[0] = ldsr<0>(ba); bfr[1] = ldsr<1024>(ba); bfr[2] = ldsr<2048>(ba); bfr[3] = ldsr<3072>(ba);
;     __builtin_amdgcn_s_setprio(1);
; #pragma unroll
;     for (int nb = 0; nb < NB; ++nb) {
;       if (nb == 0) asm volatile("s_waitcnt lgkmcnt(3)" : "+v"(af[0]), "+v"(af[1]), "+v"(af[2]), "+v"(af[3]), "+v"(bfr[0]) :: "memory");
;       else if (nb <= NB - 4) asm volatile("s_waitcnt lgkmcnt(3)" : "+v"(bfr[nb]) :: "memory");
;       else if (nb == NB - 3) asm volatile("s_waitcnt lgkmcnt(2)" : "+v"(bfr[nb]) :: "memory");
;       else if (nb == NB - 2) asm volatile("s_waitcnt lgkmcnt(1)" : "+v"(bfr[nb]) :: "memory");
;       else asm volatile("s_waitcnt lgkmcnt(0)" : "+v"(bfr[nb]) :: "memory");
;       __builtin_amdgcn_sched_barrier(0);
; #pragma unroll
;       for (int mb = 0; mb < 4; ++mb) {
;         if constexpr (SWAP) acc[mb][nb] = __builtin_amdgcn_mfma_f32_16x16x32_bf16(bfr[nb], af[mb], acc[mb][nb], 0, 0, 0);
;         else                acc[mb][nb] = __builtin_amdgcn_mfma_f32_16x16x32_bf16(af[mb], bfr[nb], acc[mb][nb], 0, 0, 0);
;       }
.LBB0_2039:
	s_mul_i32 s1, s43, 0x6000
	v_add_u32_e32 v211, s1, v209
	v_add_u32_e32 v244, s1, v210
	s_mul_i32 m0, s42, 0x6000
	s_add_u32 m0, m0, s0
	s_cmp_gt_u32 s2, 2
	s_cbranch_scc1 .Lgk18_w0
	s_waitcnt vmcnt(6)
.Lgk18_bar:
	s_waitcnt lgkmcnt(0)
	s_barrier
	s_setprio 1
	ds_read_b128 v[212:215], v211 offset:0
	ds_read_b128 v[228:231], v244 offset:0
	ds_read_b128 v[216:219], v211 offset:0x400
	ds_read_b128 v[220:223], v211 offset:0x800
	ds_read_b128 v[224:227], v211 offset:0xc00
	ds_read_b128 v[232:235], v244 offset:0x400
	ds_read_b128 v[236:239], v244 offset:0x800
	ds_read_b128 v[240:243], v244 offset:0xc00
	s_cmp_gt_u32 s2, 1
	s_cbranch_scc1 .Lgk18_tail
	s_waitcnt lgkmcnt(6)
	v_mfma_f32_16x16x32_bf16 v[126:129], v[228:231], v[212:215], v[126:129]
	s_waitcnt lgkmcnt(5)
	v_mfma_f32_16x16x32_bf16 v[94:97], v[228:231], v[216:219], v[94:97]
	s_waitcnt lgkmcnt(4)
	v_mfma_f32_16x16x32_bf16 v[62:65], v[228:231], v[220:223], v[62:65]
	s_waitcnt lgkmcnt(3)
	v_mfma_f32_16x16x32_bf16 v[30:33], v[228:231], v[224:227], v[30:33]
	ds_read_b128 v[228:231], v244 offset:0x1000
	global_load_lds_dwordx4 v182, s[100:101]
	s_add_u32 m0, m0, 0x1000
	s_waitcnt lgkmcnt(3)
	v_mfma_f32_16x16x32_bf16 v[122:125], v[232:235], v[212:215], v[122:125]
	v_mfma_f32_16x16x32_bf16 v[90:93], v[232:235], v[216:219], v[90:93]
	v_mfma_f32_16x16x32_bf16 v[58:61], v[232:235], v[220:223], v[58:61]
	v_mfma_f32_16x16x32_bf16 v[26:29], v[232:235], v[224:227], v[26:29]
	ds_read_b128 v[232:235], v244 offset:0x1400
	global_load_lds_dwordx4 v183, s[100:101]
	s_add_u32 m0, m0, 0x1000
	s_waitcnt lgkmcnt(3)
	v_mfma_f32_16x16x32_bf16 v[118:121], v[236:239], v[212:215], v[118:121]
	v_mfma_f32_16x16x32_bf16 v[86:89], v[236:239], v[216:219], v[86:89]
	v_mfma_f32_16x16x32_bf16 v[54:57], v[236:239], v[220:223], v[54:57]
	v_mfma_f32_16x16x32_bf16 v[22:25], v[236:239], v[224:227], v[22:25]
	ds_read_b128 v[236:239], v244 offset:0x1800
	global_load_lds_dwordx4 v180, vcc
	s_add_u32 m0, m0, 0x1000
	s_waitcnt lgkmcnt(3)
	v_mfma_f32_16x16x32_bf16 v[114:117], v[240:243], v[212:215], v[114:117]
	v_mfma_f32_16x16x32_bf16 v[82:85], v[240:243], v[216:219], v[82:85]
	v_mfma_f32_16x16x32_bf16 v[50:53], v[240:243], v[220:223], v[50:53]
	v_mfma_f32_16x16x32_bf16 v[18:21], v[240:243], v[224:227], v[18:21]
	ds_read_b128 v[240:243], v244 offset:0x1c00
	global_load_lds_dwordx4 v181, vcc
	s_add_u32 m0, m0, 0x1000
	s_waitcnt lgkmcnt(3)
	v_mfma_f32_16x16x32_bf16 v[110:113], v[228:231], v[212:215], v[110:113]
	v_mfma_f32_16x16x32_bf16 v[78:81], v[228:231], v[216:219], v[78:81]
	v_mfma_f32_16x16x32_bf16 v[46:49], v[228:231], v[220:223], v[46:49]
	v_mfma_f32_16x16x32_bf16 v[14:17], v[228:231], v[224:227], v[14:17]
	global_load_lds_dwordx4 v253, vcc
	s_add_u32 m0, m0, 0x1000
	s_waitcnt lgkmcnt(2)
	v_mfma_f32_16x16x32_bf16 v[106:109], v[232:235], v[212:215], v[106:109]
	v_mfma_f32_16x16x32_bf16 v[74:77], v[232:235], v[216:219], v[74:77]
	v_mfma_f32_16x16x32_bf16 v[42:45], v[232:235], v[220:223], v[42:45]
	v_mfma_f32_16x16x32_bf16 v[10:13], v[232:235], v[224:227], v[10:13]
	global_load_lds_dwordx4 v254, vcc
	s_waitcnt lgkmcnt(1)
	v_mfma_f32_16x16x32_bf16 v[102:105], v[236:239], v[212:215], v[102:105]
	v_mfma_f32_16x16x32_bf16 v[70:73], v[236:239], v[216:219], v[70:73]
	v_mfma_f32_16x16x32_bf16 v[38:41], v[236:239], v[220:223], v[38:41]
	v_mfma_f32_16x16x32_bf16 v[6:9], v[236:239], v[224:227], v[6:9]
	s_waitcnt lgkmcnt(0)
	v_mfma_f32_16x16x32_bf16 v[98:101], v[240:243], v[212:215], v[98:101]
	v_mfma_f32_16x16x32_bf16 v[66:69], v[240:243], v[216:219], v[66:69]
	v_mfma_f32_16x16x32_bf16 v[34:37], v[240:243], v[220:223], v[34:37]
	v_mfma_f32_16x16x32_bf16 v[2:5], v[240:243], v[224:227], v[2:5]
	s_add_u32 s100, s100, 0x40
	s_addc_u32 s101, s101, 0
	s_add_u32 vcc_lo, vcc_lo, s22
	s_addc_u32 vcc_hi, vcc_hi, s23
	s_add_i32 s42, s42, 1
	s_cmp_lg_u32 s42, 3
	s_cselect_b32 s42, s42, 0
	s_add_i32 s43, s43, 1
	s_cmp_lg_u32 s43, 3
	s_cselect_b32 s43, s43, 0
	s_setprio 0
	s_add_i32 s2, s2, 1
	s_branch .LBB0_2039
.Lgk18_tail:
	s_waitcnt lgkmcnt(6)
	v_mfma_f32_16x16x32_bf16 v[126:129], v[228:231], v[212:215], v[126:129]
	s_waitcnt lgkmcnt(5)
	v_mfma_f32_16x16x32_bf16 v[94:97], v[228:231], v[216:219], v[94:97]
	s_waitcnt lgkmcnt(4)
	v_mfma_f32_16x16x32_bf16 v[62:65], v[228:231], v[220:223], v[62:65]
	s_waitcnt lgkmcnt(3)
	v_mfma_f32_16x16x32_bf16 v[30:33], v[228:231], v[224:227], v[30:33]
	ds_read_b128 v[228:231], v244 offset:0x1000
	s_waitcnt lgkmcnt(3)
	v_mfma_f32_16x16x32_bf16 v[122:125], v[232:235], v[212:215], v[122:125]
	v_mfma_f32_16x16x32_bf16 v[90:93], v[232:235], v[216:219], v[90:93]
	v_mfma_f32_16x16x32_bf16 v[58:61], v[232:235], v[220:223], v[58:61]
	v_mfma_f32_16x16x32_bf16 v[26:29], v[232:235], v[224:227], v[26:29]
	ds_read_b128 v[232:235], v244 offset:0x1400
	s_waitcnt lgkmcnt(3)
	v_mfma_f32_16x16x32_bf16 v[118:121], v[236:239], v[212:215], v[118:121]
	v_mfma_f32_16x16x32_bf16 v[86:89], v[236:239], v[216:219], v[86:89]
	v_mfma_f32_16x16x32_bf16 v[54:57], v[236:239], v[220:223], v[54:57]
	v_mfma_f32_16x16x32_bf16 v[22:25], v[236:239], v[224:227], v[22:25]
	ds_read_b128 v[236:239], v244 offset:0x1800
	s_waitcnt lgkmcnt(3)
	v_mfma_f32_16x16x32_bf16 v[114:117], v[240:243], v[212:215], v[114:117]
	v_mfma_f32_16x16x32_bf16 v[82:85], v[240:243], v[216:219], v[82:85]
	v_mfma_f32_16x16x32_bf16 v[50:53], v[240:243], v[220:223], v[50:53]
	v_mfma_f32_16x16x32_bf16 v[18:21], v[240:243], v[224:227], v[18:21]
	ds_read_b128 v[240:243], v244 offset:0x1c00
	s_waitcnt lgkmcnt(3)
	v_mfma_f32_16x16x32_bf16 v[110:113], v[228:231], v[212:215], v[110:113]
	v_mfma_f32_16x16x32_bf16 v[78:81], v[228:231], v[216:219], v[78:81]
	v_mfma_f32_16x16x32_bf16 v[46:49], v[228:231], v[220:223], v[46:49]
	v_mfma_f32_16x16x32_bf16 v[14:17], v[228:231], v[224:227], v[14:17]
	s_waitcnt lgkmcnt(2)
	v_mfma_f32_16x16x32_bf16 v[106:109], v[232:235], v[212:215], v[106:109]
	v_mfma_f32_16x16x32_bf16 v[74:77], v[232:235], v[216:219], v[74:77]
	v_mfma_f32_16x16x32_bf16 v[42:45], v[232:235], v[220:223], v[42:45]
	v_mfma_f32_16x16x32_bf16 v[10:13], v[232:235], v[224:227], v[10:13]
	s_waitcnt lgkmcnt(1)
	v_mfma_f32_16x16x32_bf16 v[102:105], v[236:239], v[212:215], v[102:105]
	v_mfma_f32_16x16x32_bf16 v[70:73], v[236:239], v[216:219], v[70:73]
	v_mfma_f32_16x16x32_bf16 v[38:41], v[236:239], v[220:223], v[38:41]
	v_mfma_f32_16x16x32_bf16 v[6:9], v[236:239], v[224:227], v[6:9]
	s_waitcnt lgkmcnt(0)
	v_mfma_f32_16x16x32_bf16 v[98:101], v[240:243], v[212:215], v[98:101]
	v_mfma_f32_16x16x32_bf16 v[66:69], v[240:243], v[216:219], v[66:69]
	v_mfma_f32_16x16x32_bf16 v[34:37], v[240:243], v[220:223], v[34:37]
	v_mfma_f32_16x16x32_bf16 v[2:5], v[240:243], v[224:227], v[2:5]
	s_add_i32 s42, s42, 1
	s_cmp_lg_u32 s42, 3
	s_cselect_b32 s42, s42, 0
	s_add_i32 s43, s43, 1
	s_cmp_lg_u32 s43, 3
	s_cselect_b32 s43, s43, 0
	s_setprio 0
	s_add_i32 s2, s2, 1
	s_cmp_lg_u32 s2, 4
	s_cbranch_scc1 .LBB0_2039
	s_branch .LBB0_2045

; template <int OFF> DEVI bf16x8 ldsr(unsigned a) { bf16x8 v; asm volatile("ds_read_b128 %0, %1 offset:%2" : "=v"(v) : "v"(a), "n"(OFF)); return v; }
; #define RAW_BARRIER() do { asm volatile("s_waitcnt lgkmcnt(0)" ::: "memory"); __builtin_amdgcn_s_barrier(); } while (0)
; template <int EPI, int NB>
; DEVI void gemm_tile(const GemmJob& J, int m0, int n0, unsigned char* smem) {
;     ...
;   for (int kt = 0; kt < nk; ++kt) {
;     if (nk - 1 - kt >= S - 2) {
;       if constexpr (NB == 8) asm volatile("s_waitcnt vmcnt(6)" ::: "memory");
;       else                   asm volatile("s_waitcnt vmcnt(8)" ::: "memory");
;     } else {
;       asm volatile("s_waitcnt vmcnt(0)" ::: "memory");
;     }
;     RAW_BARRIER();
;     if (kt + S - 1 < nk) GEMM_ISSUE(kt + S - 1, is);
;     is = (is + 1 == S) ? 0 : is + 1;
;     const unsigned cur = lbase + cs * STG;
;     cs = (cs + 1 == S) ? 0 : cs + 1;
;     bf16x8 af[4], bfr[NB];
;     const unsigned aa = cur + aofs, ba = cur + bofs;
;     af[0] = ldsr<0>(aa); af[1] = ldsr<1024>(aa); af[2] = ldsr<2048>(aa); af[3] = ldsr<3072>(aa);
;     bfr[0] = ldsr<0>(ba); bfr[1] = ldsr<1024>(ba); bfr[2] = ldsr<2048>(ba); bfr[3] = ldsr<3072>(ba);
;     __builtin_amdgcn_s_setprio(1);
; #pragma unroll
;     for (int nb = 0; nb < NB; ++nb) {
;       if (nb == 0) asm volatile("s_waitcnt lgkmcnt(3)" : "+v"(af[0]), "+v"(af[1]), "+v"(af[2]), "+v"(af[3]), "+v"(bfr[0]) :: "memory");
;       else if (nb <= NB - 4) asm volatile("s_waitcnt lgkmcnt(3)" : "+v"(bfr[nb]) :: "memory");
;       else if (nb == NB - 3) asm volatile("s_waitcnt lgkmcnt(2)" : "+v"(bfr[nb]) :: "memory");
;       else if (nb == NB - 2) asm volatile("s_waitcnt lgkmcnt(1)" : "+v"(bfr[nb]) :: "memory");
;       else asm volatile("s_waitcnt lgkmcnt(0)" : "+v"(bfr[nb]) :: "memory");
;       __builtin_amdgcn_sched_barrier(0);
; #pragma unroll
;       for (int mb = 0; mb < 4; ++mb) {
;         if constexpr (SWAP) acc[mb][nb] = __builtin_amdgcn_mfma_f32_16x16x32_bf16(bfr[nb], af[mb], acc[mb][nb], 0, 0, 0);
;         else                acc[mb][nb] = __builtin_amdgcn_mfma_f32_16x16x32_bf16(af[mb], bfr[nb], acc[mb][nb], 0, 0, 0);
.LBB0_2117:
	s_mul_i32 s1, s43, 0x6000
	v_add_u32_e32 v222, s1, v208
	v_add_u32_e32 v242, s1, v209
	s_mul_i32 m0, s42, 0x6000
	s_add_u32 m0, m0, s0
	s_cmp_gt_u32 s3, 2
	s_cbranch_scc1 .Lgk19_w0
	s_waitcnt vmcnt(6)
.Lgk19_bar:
	s_waitcnt lgkmcnt(0)
	s_barrier
	s_setprio 1
	ds_read_b128 v[210:213], v222 offset:0
	ds_read_b128 v[226:229], v242 offset:0
	ds_read_b128 v[214:217], v222 offset:0x400
	ds_read_b128 v[218:221], v222 offset:0x800
	ds_read_b128 v[222:225], v222 offset:0xc00
	ds_read_b128 v[230:233], v242 offset:0x400
	ds_read_b128 v[234:237], v242 offset:0x800
	ds_read_b128 v[238:241], v242 offset:0xc00
	s_cmp_gt_u32 s3, 1
	s_cbranch_scc1 .Lgk19_tail
	s_waitcnt lgkmcnt(6)
	v_mfma_f32_16x16x32_bf16 v[126:129], v[210:213], v[226:229], v[126:129]
	s_waitcnt lgkmcnt(5)
	v_mfma_f32_16x16x32_bf16 v[94:97], v[214:217], v[226:229], v[94:97]
	s_waitcnt lgkmcnt(4)
	v_mfma_f32_16x16x32_bf16 v[62:65], v[218:221], v[226:229], v[62:65]
	s_waitcnt lgkmcnt(3)
	v_mfma_f32_16x16x32_bf16 v[30:33], v[222:225], v[226:229], v[30:33]
	ds_read_b128 v[226:229], v242 offset:0x1000
	global_load_lds_dwordx4 v182, s[100:101]
	s_add_u32 m0, m0, 0x1000
	s_waitcnt lgkmcnt(3)
	v_mfma_f32_16x16x32_bf16 v[122:125], v[210:213], v[230:233], v[122:125]
	v_mfma_f32_16x16x32_bf16 v[90:93], v[214:217], v[230:233], v[90:93]
	v_mfma_f32_16x16x32_bf16 v[58:61], v[218:221], v[230:233], v[58:61]
	v_mfma_f32_16x16x32_bf16 v[26:29], v[222:225], v[230:233], v[26:29]
	ds_read_b128 v[230:233], v242 offset:0x1400
	global_load_lds_dwordx4 v183, s[100:101]
	s_add_u32 m0, m0, 0x1000
	s_waitcnt lgkmcnt(3)
	v_mfma_f32_16x16x32_bf16 v[118:121], v[210:213], v[234:237], v[118:121]
	v_mfma_f32_16x16x32_bf16 v[86:89], v[214:217], v[234:237], v[86:89]
	v_mfma_f32_16x16x32_bf16 v[54:57], v[218:221], v[234:237], v[54:57]
	v_mfma_f32_16x16x32_bf16 v[22:25], v[222:225], v[234:237], v[22:25]
	ds_read_b128 v[234:237], v242 offset:0x1800
	global_load_lds_dwordx4 v180, vcc
	s_add_u32 m0, m0, 0x1000
	s_waitcnt lgkmcnt(3)
	v_mfma_f32_16x16x32_bf16 v[114:117], v[210:213], v[238:241], v[114:117]
	v_mfma_f32_16x16x32_bf16 v[82:85], v[214:217], v[238:241], v[82:85]
	v_mfma_f32_16x16x32_bf16 v[50:53], v[218:221], v[238:241], v[50:53]
	v_mfma_f32_16x16x32_bf16 v[18:21], v[222:225], v[238:241], v[18:21]
	ds_read_b128 v[238:241], v242 offset:0x1c00
	global_load_lds_dwordx4 v181, vcc
	s_add_u32 m0, m0, 0x1000
	s_waitcnt lgkmcnt(3)
	v_mfma_f32_16x16x32_bf16 v[110:113], v[210:213], v[226:229], v[110:113]
	v_mfma_f32_16x16x32_bf16 v[78:81], v[214:217], v[226:229], v[78:81]
	v_mfma_f32_16x16x32_bf16 v[46:49], v[218:221], v[226:229], v[46:49]
	v_mfma_f32_16x16x32_bf16 v[14:17], v[222:225], v[226:229], v[14:17]
	global_load_lds_dwordx4 v253, vcc
	s_add_u32 m0, m0, 0x1000
	s_waitcnt lgkmcnt(2)
	v_mfma_f32_16x16x32_bf16 v[106:109], v[210:213], v[230:233], v[106:109]
	v_mfma_f32_16x16x32_bf16 v[74:77], v[214:217], v[230:233], v[74:77]
	v_mfma_f32_16x16x32_bf16 v[42:45], v[218:221], v[230:233], v[42:45]
	v_mfma_f32_16x16x32_bf16 v[10:13], v[222:225], v[230:233], v[10:13]
	global_load_lds_dwordx4 v254, vcc
	s_waitcnt lgkmcnt(1)
	v_mfma_f32_16x16x32_bf16 v[102:105], v[210:213], v[234:237], v[102:105]
	v_mfma_f32_16x16x32_bf16 v[70:73], v[214:217], v[234:237], v[70:73]
	v_mfma_f32_16x16x32_bf16 v[38:41], v[218:221], v[234:237], v[38:41]
	v_mfma_f32_16x16x32_bf16 v[6:9], v[222:225], v[234:237], v[6:9]
	s_waitcnt lgkmcnt(0)
	v_mfma_f32_16x16x32_bf16 v[98:101], v[210:213], v[238:241], v[98:101]
	v_mfma_f32_16x16x32_bf16 v[66:69], v[214:217], v[238:241], v[66:69]
	v_mfma_f32_16x16x32_bf16 v[34:37], v[218:221], v[238:241], v[34:37]
	v_mfma_f32_16x16x32_bf16 v[2:5], v[222:225], v[238:241], v[2:5]
	s_add_u32 s100, s100, 0x40
	s_addc_u32 s101, s101, 0
	s_add_u32 vcc_lo, vcc_lo, s22
	s_addc_u32 vcc_hi, vcc_hi, s23
	s_add_i32 s42, s42, 1
	s_cmp_lg_u32 s42, 3
	s_cselect_b32 s42, s42, 0
	s_add_i32 s43, s43, 1
	s_cmp_lg_u32 s43, 3
	s_cselect_b32 s43, s43, 0
	s_setprio 0
	s_add_i32 s3, s3, 1
	s_branch .LBB0_2117
.Lgk19_tail:
	s_waitcnt lgkmcnt(6)
	v_mfma_f32_16x16x32_bf16 v[126:129], v[210:213], v[226:229], v[126:129]
	s_waitcnt lgkmcnt(5)
	v_mfma_f32_16x16x32_bf16 v[94:97], v[214:217], v[226:229], v[94:97]
	s_waitcnt lgkmcnt(4)
	v_mfma_f32_16x16x32_bf16 v[62:65], v[218:221], v[226:229], v[62:65]
	s_waitcnt lgkmcnt(3)
	v_mfma_f32_16x16x32_bf16 v[30:33], v[222:225], v[226:229], v[30:33]
	ds_read_b128 v[226:229], v242 offset:0x1000
	s_waitcnt lgkmcnt(3)
	v_mfma_f32_16x16x32_bf16 v[122:125], v[210:213], v[230:233], v[122:125]
	v_mfma_f32_16x16x32_bf16 v[90:93], v[214:217], v[230:233], v[90:93]
	v_mfma_f32_16x16x32_bf16 v[58:61], v[218:221], v[230:233], v[58:61]
	v_mfma_f32_16x16x32_bf16 v[26:29], v[222:225], v[230:233], v[26:29]
	ds_read_b128 v[230:233], v242 offset:0x1400
	s_waitcnt lgkmcnt(3)
	v_mfma_f32_16x16x32_bf16 v[118:121], v[210:213], v[234:237], v[118:121]
	v_mfma_f32_16x16x32_bf16 v[86:89], v[214:217], v[234:237], v[86:89]
	v_mfma_f32_16x16x32_bf16 v[54:57], v[218:221], v[234:237], v[54:57]
	v_mfma_f32_16x16x32_bf16 v[22:25], v[222:225], v[234:237], v[22:25]
	ds_read_b128 v[234:237], v242 offset:0x1800
	s_waitcnt lgkmcnt(3)
	v_mfma_f32_16x16x32_bf16 v[114:117], v[210:213], v[238:241], v[114:117]
	v_mfma_f32_16x16x32_bf16 v[82:85], v[214:217], v[238:241], v[82:85]
	v_mfma_f32_16x16x32_bf16 v[50:53], v[218:221], v[238:241], v[50:53]
	v_mfma_f32_16x16x32_bf16 v[18:21], v[222:225], v[238:241], v[18:21]
	ds_read_b128 v[238:241], v242 offset:0x1c00
	s_waitcnt lgkmcnt(3)
	v_mfma_f32_16x16x32_bf16 v[110:113], v[210:213], v[226:229], v[110:113]
	v_mfma_f32_16x16x32_bf16 v[78:81], v[214:217], v[226:229], v[78:81]
	v_mfma_f32_16x16x32_bf16 v[46:49], v[218:221], v[226:229], v[46:49]
	v_mfma_f32_16x16x32_bf16 v[14:17], v[222:225], v[226:229], v[14:17]
	s_waitcnt lgkmcnt(2)
	v_mfma_f32_16x16x32_bf16 v[106:109], v[210:213], v[230:233], v[106:109]
	v_mfma_f32_16x16x32_bf16 v[74:77], v[214:217], v[230:233], v[74:77]
	v_mfma_f32_16x16x32_bf16 v[42:45], v[218:221], v[230:233], v[42:45]
	v_mfma_f32_16x16x32_bf16 v[10:13], v[222:225], v[230:233], v[10:13]
	s_waitcnt lgkmcnt(1)
	v_mfma_f32_16x16x32_bf16 v[102:105], v[210:213], v[234:237], v[102:105]
	v_mfma_f32_16x16x32_bf16 v[70:73], v[214:217], v[234:237], v[70:73]
	v_mfma_f32_16x16x32_bf16 v[38:41], v[218:221], v[234:237], v[38:41]
	v_mfma_f32_16x16x32_bf16 v[6:9], v[222:225], v[234:237], v[6:9]
	s_waitcnt lgkmcnt(0)
	v_mfma_f32_16x16x32_bf16 v[98:101], v[210:213], v[238:241], v[98:101]
	v_mfma_f32_16x16x32_bf16 v[66:69], v[214:217], v[238:241], v[66:69]
	v_mfma_f32_16x16x32_bf16 v[34:37], v[218:221], v[238:241], v[34:37]
	v_mfma_f32_16x16x32_bf16 v[2:5], v[222:225], v[238:241], v[2:5]
	s_add_i32 s42, s42, 1
	s_cmp_lg_u32 s42, 3
	s_cselect_b32 s42, s42, 0
	s_add_i32 s43, s43, 1
	s_cmp_lg_u32 s43, 3
	s_cselect_b32 s43, s43, 0
	s_setprio 0
	s_add_i32 s3, s3, 1
	s_cmp_lg_u32 s3, 4
	s_cbranch_scc1 .LBB0_2117
	s_branch .LBB0_2123

; template <int EPI, int NB>
; DEVI void gemm_tile(const GemmJob& J, int m0, int n0, unsigned char* smem) {
;     ...
;   asm volatile("s_waitcnt vmcnt(0)" ::: "memory");
;   RAW_BARRIER();
; #pragma unroll
;   for (int st = 0; st < S - 1; ++st) GEMM_ISSUE(st, st);
;   const int fsl = (g ^ ((0 - (l16 >> 2)) & 3)) << 4;
;   const int aofs = (wm * 64 + l16) * 64 + fsl;
;   const int bofs = A_BYTES + (wn * NB * 16 + l16) * 64 + fsl;
;   int cs = 0, is = S - 1;
; #pragma clang loop unroll(disable)
;   for (int kt = 0; kt < nk; ++kt) {
;     if (nk - 1 - kt >= S - 2) {
;       if constexpr (NB == 8) asm volatile("s_waitcnt vmcnt(6)" ::: "memory");
;       else                   asm volatile("s_waitcnt vmcnt(8)" ::: "memory");
;     } else {
;       asm volatile("s_waitcnt vmcnt(0)" ::: "memory");
;     }
;     RAW_BARRIER();
;     if (kt + S - 1 < nk) GEMM_ISSUE(kt + S - 1, is);
;     is = (is + 1 == S) ? 0 : is + 1;
;     const unsigned cur = lbase + cs * STG;
;     cs = (cs + 1 == S) ? 0 : cs + 1;
;     bf16x8 af[4], bfr[NB];
;     const unsigned aa = cur + aofs, ba = cur + bofs;
;     af[0] = ldsr<0>(aa); af[1] = ldsr<1024>(aa); af[2] = ldsr<2048>(aa); af[3] = ldsr<3072>(aa);
;     bfr[0] = ldsr<0>(ba); bfr[1] = ldsr<1024>(ba); bfr[2] = ldsr<2048>(ba); bfr[3] = ldsr<3072>(ba);
;     __builtin_amdgcn_s_setprio(1);
; #pragma unroll
;     for (int nb = 0; nb < NB; ++nb) {
;       if (nb == 0) asm volatile("s_waitcnt lgkmcnt(3)" : "+v"(af[0]), "+v"(af[1]), "+v"(af[2]), "+v"(af[3]), "+v"(bfr[0]) :: "memory");
;       else if (nb <= NB - 4) asm volatile("s_waitcnt lgkmcnt(3)" : "+v"(bfr[nb]) :: "memory");
;       else if (nb == NB - 3) asm volatile("s_waitcnt lgkmcnt(2)" : "+v"(bfr[nb]) :: "memory");
;       else if (nb == NB - 2) asm volatile("s_waitcnt lgkmcnt(1)" : "+v"(bfr[nb]) :: "memory");
;       else asm volatile("s_waitcnt lgkmcnt(0)" : "+v"(bfr[nb]) :: "memory");
;       __builtin_amdgcn_sched_barrier(0);
; #pragma unroll
;       for (int mb = 0; mb < 4; ++mb) {
;         if constexpr (SWAP) acc[mb][nb] = __builtin_amdgcn_mfma_f32_16x16x32_bf16(bfr[nb], af[mb], acc[mb][nb], 0, 0, 0);
;         else                acc[mb][nb] = __builtin_amdgcn_mfma_f32_16x16x32_bf16(af[mb], bfr[nb], acc[mb][nb], 0, 0, 0);
;       }
;       if constexpr (NB == 8) {
;         __builtin_amdgcn_sched_barrier(0);
;         if (nb == 0) bfr[4] = ldsr<4096>(ba);
.LBB0_2665:
	s_mul_i32 s1, s43, 0x6000
	v_add_u32_e32 v215, s1, v212
	v_add_u32_e32 v248, s1, v214
	s_mul_i32 m0, s42, 0x6000
	s_add_u32 m0, m0, s0
	s_cmp_gt_u32 s20, 30
	s_cbranch_scc1 .Lgk22_w0
	s_waitcnt vmcnt(6)
.Lgk22_bar:
	s_waitcnt lgkmcnt(0)
	s_barrier
	s_setprio 1
	ds_read_b128 v[216:219], v215 offset:0
	ds_read_b128 v[232:235], v248 offset:0
	ds_read_b128 v[220:223], v215 offset:0x400
	ds_read_b128 v[224:227], v215 offset:0x800
	ds_read_b128 v[228:231], v215 offset:0xc00
	ds_read_b128 v[236:239], v248 offset:0x400
	ds_read_b128 v[240:243], v248 offset:0x800
	ds_read_b128 v[244:247], v248 offset:0xc00
	s_cmp_gt_u32 s20, 29
	s_cbranch_scc1 .Lgk22_tail
	s_waitcnt lgkmcnt(6)
	v_mfma_f32_16x16x32_bf16 v[122:125], v[232:235], v[216:219], v[122:125]
	s_waitcnt lgkmcnt(5)
	v_mfma_f32_16x16x32_bf16 v[90:93], v[232:235], v[220:223], v[90:93]
	s_waitcnt lgkmcnt(4)
	v_mfma_f32_16x16x32_bf16 v[58:61], v[232:235], v[224:227], v[58:61]
	s_waitcnt lgkmcnt(3)
	v_mfma_f32_16x16x32_bf16 v[26:29], v[232:235], v[228:231], v[26:29]
	ds_read_b128 v[232:235], v248 offset:0x1000
	global_load_lds_dwordx4 v186, s[100:101]
	s_add_u32 m0, m0, 0x1000
	s_waitcnt lgkmcnt(3)
	v_mfma_f32_16x16x32_bf16 v[114:117], v[236:239], v[216:219], v[114:117]
	v_mfma_f32_16x16x32_bf16 v[82:85], v[236:239], v[220:223], v[82:85]
	v_mfma_f32_16x16x32_bf16 v[50:53], v[236:239], v[224:227], v[50:53]
	v_mfma_f32_16x16x32_bf16 v[18:21], v[236:239], v[228:231], v[18:21]
	ds_read_b128 v[236:239], v248 offset:0x1400
	global_load_lds_dwordx4 v187, s[100:101]
	s_add_u32 m0, m0, 0x1000
	s_waitcnt lgkmcnt(3)
	v_mfma_f32_16x16x32_bf16 v[126:129], v[240:243], v[216:219], v[126:129]
	v_mfma_f32_16x16x32_bf16 v[94:97], v[240:243], v[220:223], v[94:97]
	v_mfma_f32_16x16x32_bf16 v[62:65], v[240:243], v[224:227], v[62:65]
	v_mfma_f32_16x16x32_bf16 v[30:33], v[240:243], v[228:231], v[30:33]
	ds_read_b128 v[240:243], v248 offset:0x1800
	global_load_lds_dwordx4 v184, vcc
	s_add_u32 m0, m0, 0x1000
	s_waitcnt lgkmcnt(3)
	v_mfma_f32_16x16x32_bf16 v[118:121], v[244:247], v[216:219], v[118:121]
	v_mfma_f32_16x16x32_bf16 v[86:89], v[244:247], v[220:223], v[86:89]
	v_mfma_f32_16x16x32_bf16 v[54:57], v[244:247], v[224:227], v[54:57]
	v_mfma_f32_16x16x32_bf16 v[22:25], v[244:247], v[228:231], v[22:25]
	ds_read_b128 v[244:247], v248 offset:0x1c00
	global_load_lds_dwordx4 v185, vcc
	s_add_u32 m0, m0, 0x1000
	s_waitcnt lgkmcnt(3)
	v_mfma_f32_16x16x32_bf16 v[106:109], v[232:235], v[216:219], v[106:109]
	v_mfma_f32_16x16x32_bf16 v[74:77], v[232:235], v[220:223], v[74:77]
	v_mfma_f32_16x16x32_bf16 v[42:45], v[232:235], v[224:227], v[42:45]
	v_mfma_f32_16x16x32_bf16 v[10:13], v[232:235], v[228:231], v[10:13]
	global_load_lds_dwordx4 v253, vcc
	s_add_u32 m0, m0, 0x1000
	s_waitcnt lgkmcnt(2)
	v_mfma_f32_16x16x32_bf16 v[98:101], v[236:239], v[216:219], v[98:101]
	v_mfma_f32_16x16x32_bf16 v[66:69], v[236:239], v[220:223], v[66:69]
	v_mfma_f32_16x16x32_bf16 v[34:37], v[236:239], v[224:227], v[34:37]
	v_mfma_f32_16x16x32_bf16 v[2:5], v[236:239], v[228:231], v[2:5]
	global_load_lds_dwordx4 v254, vcc
	s_waitcnt lgkmcnt(1)
	v_mfma_f32_16x16x32_bf16 v[110:113], v[240:243], v[216:219], v[110:113]
	v_mfma_f32_16x16x32_bf16 v[78:81], v[240:243], v[220:223], v[78:81]
	v_mfma_f32_16x16x32_bf16 v[46:49], v[240:243], v[224:227], v[46:49]
	v_mfma_f32_16x16x32_bf16 v[14:17], v[240:243], v[228:231], v[14:17]
	s_waitcnt lgkmcnt(0)
	v_mfma_f32_16x16x32_bf16 v[102:105], v[244:247], v[216:219], v[102:105]
	v_mfma_f32_16x16x32_bf16 v[70:73], v[244:247], v[220:223], v[70:73]
	v_mfma_f32_16x16x32_bf16 v[38:41], v[244:247], v[224:227], v[38:41]
	v_mfma_f32_16x16x32_bf16 v[6:9], v[244:247], v[228:231], v[6:9]
	s_add_u32 s100, s100, s94
	s_addc_u32 s101, s101, s95
	s_add_u32 vcc_lo, vcc_lo, s50
	s_addc_u32 vcc_hi, vcc_hi, s51
	s_add_i32 s42, s42, 1
	s_cmp_lg_u32 s42, 3
	s_cselect_b32 s42, s42, 0
	s_add_i32 s43, s43, 1
	s_cmp_lg_u32 s43, 3
	s_cselect_b32 s43, s43, 0
	s_setprio 0
	s_add_i32 s20, s20, 1
	s_branch .LBB0_2665
.Lgk22_tail:
	s_waitcnt lgkmcnt(6)
	v_mfma_f32_16x16x32_bf16 v[122:125], v[232:235], v[216:219], v[122:125]
	s_waitcnt lgkmcnt(5)
	v_mfma_f32_16x16x32_bf16 v[90:93], v[232:235], v[220:223], v[90:93]
	s_waitcnt lgkmcnt(4)
	v_mfma_f32_16x16x32_bf16 v[58:61], v[232:235], v[224:227], v[58:61]
	s_waitcnt lgkmcnt(3)
	v_mfma_f32_16x16x32_bf16 v[26:29], v[232:235], v[228:231], v[26:29]
	ds_read_b128 v[232:235], v248 offset:0x1000
	s_waitcnt lgkmcnt(3)
	v_mfma_f32_16x16x32_bf16 v[114:117], v[236:239], v[216:219], v[114:117]
	v_mfma_f32_16x16x32_bf16 v[82:85], v[236:239], v[220:223], v[82:85]
	v_mfma_f32_16x16x32_bf16 v[50:53], v[236:239], v[224:227], v[50:53]
	v_mfma_f32_16x16x32_bf16 v[18:21], v[236:239], v[228:231], v[18:21]
	ds_read_b128 v[236:239], v248 offset:0x1400
	s_waitcnt lgkmcnt(3)
	v_mfma_f32_16x16x32_bf16 v[126:129], v[240:243], v[216:219], v[126:129]
	v_mfma_f32_16x16x32_bf16 v[94:97], v[240:243], v[220:223], v[94:97]
	v_mfma_f32_16x16x32_bf16 v[62:65], v[240:243], v[224:227], v[62:65]
	v_mfma_f32_16x16x32_bf16 v[30:33], v[240:243], v[228:231], v[30:33]
	ds_read_b128 v[240:243], v248 offset:0x1800
	s_waitcnt lgkmcnt(3)
	v_mfma_f32_16x16x32_bf16 v[118:121], v[244:247], v[216:219], v[118:121]
	v_mfma_f32_16x16x32_bf16 v[86:89], v[244:247], v[220:223], v[86:89]
	v_mfma_f32_16x16x32_bf16 v[54:57], v[244:247], v[224:227], v[54:57]
	v_mfma_f32_16x16x32_bf16 v[22:25], v[244:247], v[228:231], v[22:25]
	ds_read_b128 v[244:247], v248 offset:0x1c00
	s_waitcnt lgkmcnt(3)
	v_mfma_f32_16x16x32_bf16 v[106:109], v[232:235], v[216:219], v[106:109]
	v_mfma_f32_16x16x32_bf16 v[74:77], v[232:235], v[220:223], v[74:77]
	v_mfma_f32_16x16x32_bf16 v[42:45], v[232:235], v[224:227], v[42:45]
	v_mfma_f32_16x16x32_bf16 v[10:13], v[232:235], v[228:231], v[10:13]
	s_waitcnt lgkmcnt(2)
	v_mfma_f32_16x16x32_bf16 v[98:101], v[236:239], v[216:219], v[98:101]
	v_mfma_f32_16x16x32_bf16 v[66:69], v[236:239], v[220:223], v[66:69]
	v_mfma_f32_16x16x32_bf16 v[34:37], v[236:239], v[224:227], v[34:37]
	v_mfma_f32_16x16x32_bf16 v[2:5], v[236:239], v[228:231], v[2:5]
	s_waitcnt lgkmcnt(1)
	v_mfma_f32_16x16x32_bf16 v[110:113], v[240:243], v[216:219], v[110:113]
	v_mfma_f32_16x16x32_bf16 v[78:81], v[240:243], v[220:223], v[78:81]
	v_mfma_f32_16x16x32_bf16 v[46:49], v[240:243], v[224:227], v[46:49]
	v_mfma_f32_16x16x32_bf16 v[14:17], v[240:243], v[228:231], v[14:17]
	s_waitcnt lgkmcnt(0)
	v_mfma_f32_16x16x32_bf16 v[102:105], v[244:247], v[216:219], v[102:105]
	v_mfma_f32_16x16x32_bf16 v[70:73], v[244:247], v[220:223], v[70:73]
	v_mfma_f32_16x16x32_bf16 v[38:41], v[244:247], v[224:227], v[38:41]
	v_mfma_f32_16x16x32_bf16 v[6:9], v[244:247], v[228:231], v[6:9]
	s_add_i32 s42, s42, 1
	s_cmp_lg_u32 s42, 3
	s_cselect_b32 s42, s42, 0
	s_add_i32 s43, s43, 1
	s_cmp_lg_u32 s43, 3
	s_cselect_b32 s43, s43, 0
	s_setprio 0
	s_add_i32 s20, s20, 1
	s_cmp_lg_u32 s20, 32
	s_cbranch_scc1 .LBB0_2665
	s_branch .LBB0_2662

; template <int EPI, int NB>
; DEVI void gemm_tile(const GemmJob& J, int m0, int n0, unsigned char* smem) {
;     ...
;   asm volatile("s_waitcnt vmcnt(0)" ::: "memory");
;   RAW_BARRIER();
; #pragma unroll
;   for (int st = 0; st < S - 1; ++st) GEMM_ISSUE(st, st);
;   const int fsl = (g ^ ((0 - (l16 >> 2)) & 3)) << 4;
;   const int aofs = (wm * 64 + l16) * 64 + fsl;
;   const int bofs = A_BYTES + (wn * NB * 16 + l16) * 64 + fsl;
;   int cs = 0, is = S - 1;
; #pragma clang loop unroll(disable)
;   for (int kt = 0; kt < nk; ++kt) {
;     if (nk - 1 - kt >= S - 2) {
;       if constexpr (NB == 8) asm volatile("s_waitcnt vmcnt(6)" ::: "memory");
;       else                   asm volatile("s_waitcnt vmcnt(8)" ::: "memory");
;     } else {
;       asm volatile("s_waitcnt vmcnt(0)" ::: "memory");
;     }
;     RAW_BARRIER();
;     if (kt + S - 1 < nk) GEMM_ISSUE(kt + S - 1, is);
;     is = (is + 1 == S) ? 0 : is + 1;
;     const unsigned cur = lbase + cs * STG;
;     cs = (cs + 1 == S) ? 0 : cs + 1;
;     bf16x8 af[4], bfr[NB];
;     const unsigned aa = cur + aofs, ba = cur + bofs;
;     af[0] = ldsr<0>(aa); af[1] = ldsr<1024>(aa); af[2] = ldsr<2048>(aa); af[3] = ldsr<3072>(aa);
;     bfr[0] = ldsr<0>(ba); bfr[1] = ldsr<1024>(ba); bfr[2] = ldsr<2048>(ba); bfr[3] = ldsr<3072>(ba);
;     __builtin_amdgcn_s_setprio(1);
; #pragma unroll
;     for (int nb = 0; nb < NB; ++nb) {
;       if (nb == 0) asm volatile("s_waitcnt lgkmcnt(3)" : "+v"(af[0]), "+v"(af[1]), "+v"(af[2]), "+v"(af[3]), "+v"(bfr[0]) :: "memory");
;       else if (nb <= NB - 4) asm volatile("s_waitcnt lgkmcnt(3)" : "+v"(bfr[nb]) :: "memory");
;       else if (nb == NB - 3) asm volatile("s_waitcnt lgkmcnt(2)" : "+v"(bfr[nb]) :: "memory");
;       else if (nb == NB - 2) asm volatile("s_waitcnt lgkmcnt(1)" : "+v"(bfr[nb]) :: "memory");
;       else asm volatile("s_waitcnt lgkmcnt(0)" : "+v"(bfr[nb]) :: "memory");
;       __builtin_amdgcn_sched_barrier(0);
; #pragma unroll
;       for (int mb = 0; mb < 4; ++mb) {
;         if constexpr (SWAP) acc[mb][nb] = __builtin_amdgcn_mfma_f32_16x16x32_bf16(bfr[nb], af[mb], acc[mb][nb], 0, 0, 0);
;         else                acc[mb][nb] = __builtin_amdgcn_mfma_f32_16x16x32_bf16(af[mb], bfr[nb], acc[mb][nb], 0, 0, 0);
;       }
;       if constexpr (NB == 8) {
;         __builtin_amdgcn_sched_barrier(0);
;         if (nb == 0) bfr[4] = ldsr<4096>(ba);
.LBB0_2679:
	s_mul_i32 s1, s43, 0x6000
	v_add_u32_e32 v215, s1, v212
	v_add_u32_e32 v248, s1, v214
	s_mul_i32 m0, s42, 0x6000
	s_add_u32 m0, m0, s0
	s_cmp_gt_u32 s8, 30
	s_cbranch_scc1 .Lgk23_w0
	s_waitcnt vmcnt(6)
.Lgk23_bar:
	s_waitcnt lgkmcnt(0)
	s_barrier
	s_setprio 1
	ds_read_b128 v[216:219], v215 offset:0
	ds_read_b128 v[232:235], v248 offset:0
	ds_read_b128 v[220:223], v215 offset:0x400
	ds_read_b128 v[224:227], v215 offset:0x800
	ds_read_b128 v[228:231], v215 offset:0xc00
	ds_read_b128 v[236:239], v248 offset:0x400
	ds_read_b128 v[240:243], v248 offset:0x800
	ds_read_b128 v[244:247], v248 offset:0xc00
	s_cmp_gt_u32 s8, 29
	s_cbranch_scc1 .Lgk23_tail
	s_waitcnt lgkmcnt(6)
	v_mfma_f32_16x16x32_bf16 v[122:125], v[232:235], v[216:219], v[122:125]
	s_waitcnt lgkmcnt(5)
	v_mfma_f32_16x16x32_bf16 v[90:93], v[232:235], v[220:223], v[90:93]
	s_waitcnt lgkmcnt(4)
	v_mfma_f32_16x16x32_bf16 v[58:61], v[232:235], v[224:227], v[58:61]
	s_waitcnt lgkmcnt(3)
	v_mfma_f32_16x16x32_bf16 v[26:29], v[232:235], v[228:231], v[26:29]
	ds_read_b128 v[232:235], v248 offset:0x1000
	global_load_lds_dwordx4 v186, s[100:101]
	s_add_u32 m0, m0, 0x1000
	s_waitcnt lgkmcnt(3)
	v_mfma_f32_16x16x32_bf16 v[114:117], v[236:239], v[216:219], v[114:117]
	v_mfma_f32_16x16x32_bf16 v[82:85], v[236:239], v[220:223], v[82:85]
	v_mfma_f32_16x16x32_bf16 v[50:53], v[236:239], v[224:227], v[50:53]
	v_mfma_f32_16x16x32_bf16 v[18:21], v[236:239], v[228:231], v[18:21]
	ds_read_b128 v[236:239], v248 offset:0x1400
	global_load_lds_dwordx4 v187, s[100:101]
	s_add_u32 m0, m0, 0x1000
	s_waitcnt lgkmcnt(3)
	v_mfma_f32_16x16x32_bf16 v[126:129], v[240:243], v[216:219], v[126:129]
	v_mfma_f32_16x16x32_bf16 v[94:97], v[240:243], v[220:223], v[94:97]
	v_mfma_f32_16x16x32_bf16 v[62:65], v[240:243], v[224:227], v[62:65]
	v_mfma_f32_16x16x32_bf16 v[30:33], v[240:243], v[228:231], v[30:33]
	ds_read_b128 v[240:243], v248 offset:0x1800
	global_load_lds_dwordx4 v184, vcc
	s_add_u32 m0, m0, 0x1000
	s_waitcnt lgkmcnt(3)
	v_mfma_f32_16x16x32_bf16 v[118:121], v[244:247], v[216:219], v[118:121]
	v_mfma_f32_16x16x32_bf16 v[86:89], v[244:247], v[220:223], v[86:89]
	v_mfma_f32_16x16x32_bf16 v[54:57], v[244:247], v[224:227], v[54:57]
	v_mfma_f32_16x16x32_bf16 v[22:25], v[244:247], v[228:231], v[22:25]
	ds_read_b128 v[244:247], v248 offset:0x1c00
	global_load_lds_dwordx4 v185, vcc
	s_add_u32 m0, m0, 0x1000
	s_waitcnt lgkmcnt(3)
	v_mfma_f32_16x16x32_bf16 v[106:109], v[232:235], v[216:219], v[106:109]
	v_mfma_f32_16x16x32_bf16 v[74:77], v[232:235], v[220:223], v[74:77]
	v_mfma_f32_16x16x32_bf16 v[42:45], v[232:235], v[224:227], v[42:45]
	v_mfma_f32_16x16x32_bf16 v[10:13], v[232:235], v[228:231], v[10:13]
	global_load_lds_dwordx4 v253, vcc
	s_add_u32 m0, m0, 0x1000
	s_waitcnt lgkmcnt(2)
	v_mfma_f32_16x16x32_bf16 v[98:101], v[236:239], v[216:219], v[98:101]
	v_mfma_f32_16x16x32_bf16 v[66:69], v[236:239], v[220:223], v[66:69]
	v_mfma_f32_16x16x32_bf16 v[34:37], v[236:239], v[224:227], v[34:37]
	v_mfma_f32_16x16x32_bf16 v[2:5], v[236:239], v[228:231], v[2:5]
	global_load_lds_dwordx4 v254, vcc
	s_waitcnt lgkmcnt(1)
	v_mfma_f32_16x16x32_bf16 v[110:113], v[240:243], v[216:219], v[110:113]
	v_mfma_f32_16x16x32_bf16 v[78:81], v[240:243], v[220:223], v[78:81]
	v_mfma_f32_16x16x32_bf16 v[46:49], v[240:243], v[224:227], v[46:49]
	v_mfma_f32_16x16x32_bf16 v[14:17], v[240:243], v[228:231], v[14:17]
	s_waitcnt lgkmcnt(0)
	v_mfma_f32_16x16x32_bf16 v[102:105], v[244:247], v[216:219], v[102:105]
	v_mfma_f32_16x16x32_bf16 v[70:73], v[244:247], v[220:223], v[70:73]
	v_mfma_f32_16x16x32_bf16 v[38:41], v[244:247], v[224:227], v[38:41]
	v_mfma_f32_16x16x32_bf16 v[6:9], v[244:247], v[228:231], v[6:9]
	s_add_u32 s100, s100, s94
	s_addc_u32 s101, s101, s95
	s_add_u32 vcc_lo, vcc_lo, s50
	s_addc_u32 vcc_hi, vcc_hi, s51
	s_add_i32 s42, s42, 1
	s_cmp_lg_u32 s42, 3
	s_cselect_b32 s42, s42, 0
	s_add_i32 s43, s43, 1
	s_cmp_lg_u32 s43, 3
	s_cselect_b32 s43, s43, 0
	s_setprio 0
	s_add_i32 s8, s8, 1
	s_branch .LBB0_2679
.Lgk23_tail:
	s_waitcnt lgkmcnt(6)
	v_mfma_f32_16x16x32_bf16 v[122:125], v[232:235], v[216:219], v[122:125]
	s_waitcnt lgkmcnt(5)
	v_mfma_f32_16x16x32_bf16 v[90:93], v[232:235], v[220:223], v[90:93]
	s_waitcnt lgkmcnt(4)
	v_mfma_f32_16x16x32_bf16 v[58:61], v[232:235], v[224:227], v[58:61]
	s_waitcnt lgkmcnt(3)
	v_mfma_f32_16x16x32_bf16 v[26:29], v[232:235], v[228:231], v[26:29]
	ds_read_b128 v[232:235], v248 offset:0x1000
	s_waitcnt lgkmcnt(3)
	v_mfma_f32_16x16x32_bf16 v[114:117], v[236:239], v[216:219], v[114:117]
	v_mfma_f32_16x16x32_bf16 v[82:85], v[236:239], v[220:223], v[82:85]
	v_mfma_f32_16x16x32_bf16 v[50:53], v[236:239], v[224:227], v[50:53]
	v_mfma_f32_16x16x32_bf16 v[18:21], v[236:239], v[228:231], v[18:21]
	ds_read_b128 v[236:239], v248 offset:0x1400
	s_waitcnt lgkmcnt(3)
	v_mfma_f32_16x16x32_bf16 v[126:129], v[240:243], v[216:219], v[126:129]
	v_mfma_f32_16x16x32_bf16 v[94:97], v[240:243], v[220:223], v[94:97]
	v_mfma_f32_16x16x32_bf16 v[62:65], v[240:243], v[224:227], v[62:65]
	v_mfma_f32_16x16x32_bf16 v[30:33], v[240:243], v[228:231], v[30:33]
	ds_read_b128 v[240:243], v248 offset:0x1800
	s_waitcnt lgkmcnt(3)
	v_mfma_f32_16x16x32_bf16 v[118:121], v[244:247], v[216:219], v[118:121]
	v_mfma_f32_16x16x32_bf16 v[86:89], v[244:247], v[220:223], v[86:89]
	v_mfma_f32_16x16x32_bf16 v[54:57], v[244:247], v[224:227], v[54:57]
	v_mfma_f32_16x16x32_bf16 v[22:25], v[244:247], v[228:231], v[22:25]
	ds_read_b128 v[244:247], v248 offset:0x1c00
	s_waitcnt lgkmcnt(3)
	v_mfma_f32_16x16x32_bf16 v[106:109], v[232:235], v[216:219], v[106:109]
	v_mfma_f32_16x16x32_bf16 v[74:77], v[232:235], v[220:223], v[74:77]
	v_mfma_f32_16x16x32_bf16 v[42:45], v[232:235], v[224:227], v[42:45]
	v_mfma_f32_16x16x32_bf16 v[10:13], v[232:235], v[228:231], v[10:13]
	s_waitcnt lgkmcnt(2)
	v_mfma_f32_16x16x32_bf16 v[98:101], v[236:239], v[216:219], v[98:101]
	v_mfma_f32_16x16x32_bf16 v[66:69], v[236:239], v[220:223], v[66:69]
	v_mfma_f32_16x16x32_bf16 v[34:37], v[236:239], v[224:227], v[34:37]
	v_mfma_f32_16x16x32_bf16 v[2:5], v[236:239], v[228:231], v[2:5]
	s_waitcnt lgkmcnt(1)
	v_mfma_f32_16x16x32_bf16 v[110:113], v[240:243], v[216:219], v[110:113]
	v_mfma_f32_16x16x32_bf16 v[78:81], v[240:243], v[220:223], v[78:81]
	v_mfma_f32_16x16x32_bf16 v[46:49], v[240:243], v[224:227], v[46:49]
	v_mfma_f32_16x16x32_bf16 v[14:17], v[240:243], v[228:231], v[14:17]
	s_waitcnt lgkmcnt(0)
	v_mfma_f32_16x16x32_bf16 v[102:105], v[244:247], v[216:219], v[102:105]
	v_mfma_f32_16x16x32_bf16 v[70:73], v[244:247], v[220:223], v[70:73]
	v_mfma_f32_16x16x32_bf16 v[38:41], v[244:247], v[224:227], v[38:41]
	v_mfma_f32_16x16x32_bf16 v[6:9], v[244:247], v[228:231], v[6:9]
	s_add_i32 s42, s42, 1
	s_cmp_lg_u32 s42, 3
	s_cselect_b32 s42, s42, 0
	s_add_i32 s43, s43, 1
	s_cmp_lg_u32 s43, 3
	s_cselect_b32 s43, s43, 0
	s_setprio 0
	s_add_i32 s8, s8, 1
	s_cmp_lg_u32 s8, 32
	s_cbranch_scc1 .LBB0_2679
	s_branch .LBB0_2676

; template <int EPI, int NB>
; DEVI void gemm_tile(const GemmJob& J, int m0, int n0, unsigned char* smem) {
;     ...
;   asm volatile("s_waitcnt vmcnt(0)" ::: "memory");
;   RAW_BARRIER();
; #pragma unroll
;   for (int st = 0; st < S - 1; ++st) GEMM_ISSUE(st, st);
;   const int fsl = (g ^ ((0 - (l16 >> 2)) & 3)) << 4;
;   const int aofs = (wm * 64 + l16) * 64 + fsl;
;   const int bofs = A_BYTES + (wn * NB * 16 + l16) * 64 + fsl;
;   int cs = 0, is = S - 1;
; #pragma clang loop unroll(disable)
;   for (int kt = 0; kt < nk; ++kt) {
;     if (nk - 1 - kt >= S - 2) {
;       if constexpr (NB == 8) asm volatile("s_waitcnt vmcnt(6)" ::: "memory");
;       else                   asm volatile("s_waitcnt vmcnt(8)" ::: "memory");
;     } else {
;       asm volatile("s_waitcnt vmcnt(0)" ::: "memory");
;     }
;     RAW_BARRIER();
;     if (kt + S - 1 < nk) GEMM_ISSUE(kt + S - 1, is);
;     is = (is + 1 == S) ? 0 : is + 1;
;     const unsigned cur = lbase + cs * STG;
;     cs = (cs + 1 == S) ? 0 : cs + 1;
;     bf16x8 af[4], bfr[NB];
;     const unsigned aa = cur + aofs, ba = cur + bofs;
;     af[0] = ldsr<0>(aa); af[1] = ldsr<1024>(aa); af[2] = ldsr<2048>(aa); af[3] = ldsr<3072>(aa);
;     bfr[0] = ldsr<0>(ba); bfr[1] = ldsr<1024>(ba); bfr[2] = ldsr<2048>(ba); bfr[3] = ldsr<3072>(ba);
;     __builtin_amdgcn_s_setprio(1);
; #pragma unroll
;     for (int nb = 0; nb < NB; ++nb) {
;       if (nb == 0) asm volatile("s_waitcnt lgkmcnt(3)" : "+v"(af[0]), "+v"(af[1]), "+v"(af[2]), "+v"(af[3]), "+v"(bfr[0]) :: "memory");
;       else if (nb <= NB - 4) asm volatile("s_waitcnt lgkmcnt(3)" : "+v"(bfr[nb]) :: "memory");
;       else if (nb == NB - 3) asm volatile("s_waitcnt lgkmcnt(2)" : "+v"(bfr[nb]) :: "memory");
;       else if (nb == NB - 2) asm volatile("s_waitcnt lgkmcnt(1)" : "+v"(bfr[nb]) :: "memory");
;       else asm volatile("s_waitcnt lgkmcnt(0)" : "+v"(bfr[nb]) :: "memory");
;       __builtin_amdgcn_sched_barrier(0);
; #pragma unroll
;       for (int mb = 0; mb < 4; ++mb) {
;         if constexpr (SWAP) acc[mb][nb] = __builtin_amdgcn_mfma_f32_16x16x32_bf16(bfr[nb], af[mb], acc[mb][nb], 0, 0, 0);
;         else                acc[mb][nb] = __builtin_amdgcn_mfma_f32_16x16x32_bf16(af[mb], bfr[nb], acc[mb][nb], 0, 0, 0);
;       }
;       if constexpr (NB == 8) {
;         __builtin_amdgcn_sched_barrier(0);
;         if (nb == 0) bfr[4] = ldsr<4096>(ba);
.LBB0_2744:
	s_mul_i32 s1, s41, 0x6000
	v_add_u32_e32 v213, s1, v211
	v_add_u32_e32 v246, s1, v212
	s_mul_i32 m0, s40, 0x6000
	s_add_u32 m0, m0, s0
	s_cmp_gt_u32 s20, 86
	s_cbranch_scc1 .Lgk24_w0
	s_waitcnt vmcnt(6)
.Lgk24_bar:
	s_waitcnt lgkmcnt(0)
	s_barrier
	s_setprio 1
	ds_read_b128 v[214:217], v213 offset:0
	ds_read_b128 v[230:233], v246 offset:0
	ds_read_b128 v[218:221], v213 offset:0x400
	ds_read_b128 v[222:225], v213 offset:0x800
	ds_read_b128 v[226:229], v213 offset:0xc00
	ds_read_b128 v[234:237], v246 offset:0x400
	ds_read_b128 v[238:241], v246 offset:0x800
	ds_read_b128 v[242:245], v246 offset:0xc00
	s_cmp_gt_u32 s20, 85
	s_cbranch_scc1 .Lgk24_tail
	s_waitcnt lgkmcnt(6)
	v_mfma_f32_16x16x32_bf16 v[126:129], v[230:233], v[214:217], v[126:129]
	s_waitcnt lgkmcnt(5)
	v_mfma_f32_16x16x32_bf16 v[94:97], v[230:233], v[218:221], v[94:97]
	s_waitcnt lgkmcnt(4)
	v_mfma_f32_16x16x32_bf16 v[62:65], v[230:233], v[222:225], v[62:65]
	s_waitcnt lgkmcnt(3)
	v_mfma_f32_16x16x32_bf16 v[30:33], v[230:233], v[226:229], v[30:33]
	ds_read_b128 v[230:233], v246 offset:0x1000
	global_load_lds_dwordx4 v184, s[100:101]
	s_add_u32 m0, m0, 0x1000
	s_waitcnt lgkmcnt(3)
	v_mfma_f32_16x16x32_bf16 v[122:125], v[234:237], v[214:217], v[122:125]
	v_mfma_f32_16x16x32_bf16 v[90:93], v[234:237], v[218:221], v[90:93]
	v_mfma_f32_16x16x32_bf16 v[58:61], v[234:237], v[222:225], v[58:61]
	v_mfma_f32_16x16x32_bf16 v[26:29], v[234:237], v[226:229], v[26:29]
	ds_read_b128 v[234:237], v246 offset:0x1400
	global_load_lds_dwordx4 v185, s[100:101]
	s_add_u32 m0, m0, 0x1000
	s_waitcnt lgkmcnt(3)
	v_mfma_f32_16x16x32_bf16 v[118:121], v[238:241], v[214:217], v[118:121]
	v_mfma_f32_16x16x32_bf16 v[86:89], v[238:241], v[218:221], v[86:89]
	v_mfma_f32_16x16x32_bf16 v[54:57], v[238:241], v[222:225], v[54:57]
	v_mfma_f32_16x16x32_bf16 v[22:25], v[238:241], v[226:229], v[22:25]
	ds_read_b128 v[238:241], v246 offset:0x1800
	global_load_lds_dwordx4 v182, vcc
	s_add_u32 m0, m0, 0x1000
	s_waitcnt lgkmcnt(3)
	v_mfma_f32_16x16x32_bf16 v[114:117], v[242:245], v[214:217], v[114:117]
	v_mfma_f32_16x16x32_bf16 v[82:85], v[242:245], v[218:221], v[82:85]
	v_mfma_f32_16x16x32_bf16 v[50:53], v[242:245], v[222:225], v[50:53]
	v_mfma_f32_16x16x32_bf16 v[18:21], v[242:245], v[226:229], v[18:21]
	ds_read_b128 v[242:245], v246 offset:0x1c00
	global_load_lds_dwordx4 v183, vcc
	s_add_u32 m0, m0, 0x1000
	s_waitcnt lgkmcnt(3)
	v_mfma_f32_16x16x32_bf16 v[110:113], v[230:233], v[214:217], v[110:113]
	v_mfma_f32_16x16x32_bf16 v[78:81], v[230:233], v[218:221], v[78:81]
	v_mfma_f32_16x16x32_bf16 v[46:49], v[230:233], v[222:225], v[46:49]
	v_mfma_f32_16x16x32_bf16 v[14:17], v[230:233], v[226:229], v[14:17]
	global_load_lds_dwordx4 v253, vcc
	s_add_u32 m0, m0, 0x1000
	s_waitcnt lgkmcnt(2)
	v_mfma_f32_16x16x32_bf16 v[106:109], v[234:237], v[214:217], v[106:109]
	v_mfma_f32_16x16x32_bf16 v[74:77], v[234:237], v[218:221], v[74:77]
	v_mfma_f32_16x16x32_bf16 v[42:45], v[234:237], v[222:225], v[42:45]
	v_mfma_f32_16x16x32_bf16 v[10:13], v[234:237], v[226:229], v[10:13]
	global_load_lds_dwordx4 v254, vcc
	s_waitcnt lgkmcnt(1)
	v_mfma_f32_16x16x32_bf16 v[102:105], v[238:241], v[214:217], v[102:105]
	v_mfma_f32_16x16x32_bf16 v[70:73], v[238:241], v[218:221], v[70:73]
	v_mfma_f32_16x16x32_bf16 v[38:41], v[238:241], v[222:225], v[38:41]
	v_mfma_f32_16x16x32_bf16 v[6:9], v[238:241], v[226:229], v[6:9]
	s_waitcnt lgkmcnt(0)
	v_mfma_f32_16x16x32_bf16 v[98:101], v[242:245], v[214:217], v[98:101]
	v_mfma_f32_16x16x32_bf16 v[66:69], v[242:245], v[218:221], v[66:69]
	v_mfma_f32_16x16x32_bf16 v[34:37], v[242:245], v[222:225], v[34:37]
	v_mfma_f32_16x16x32_bf16 v[2:5], v[242:245], v[226:229], v[2:5]
	s_add_u32 s100, s100, s94
	s_addc_u32 s101, s101, s95
	s_add_u32 vcc_lo, vcc_lo, s22
	s_addc_u32 vcc_hi, vcc_hi, s23
	s_add_i32 s40, s40, 1
	s_cmp_lg_u32 s40, 3
	s_cselect_b32 s40, s40, 0
	s_add_i32 s41, s41, 1
	s_cmp_lg_u32 s41, 3
	s_cselect_b32 s41, s41, 0
	s_setprio 0
	s_add_i32 s20, s20, 1
	s_branch .LBB0_2744
.Lgk24_tail:
	s_waitcnt lgkmcnt(6)
	v_mfma_f32_16x16x32_bf16 v[126:129], v[230:233], v[214:217], v[126:129]
	s_waitcnt lgkmcnt(5)
	v_mfma_f32_16x16x32_bf16 v[94:97], v[230:233], v[218:221], v[94:97]
	s_waitcnt lgkmcnt(4)
	v_mfma_f32_16x16x32_bf16 v[62:65], v[230:233], v[222:225], v[62:65]
	s_waitcnt lgkmcnt(3)
	v_mfma_f32_16x16x32_bf16 v[30:33], v[230:233], v[226:229], v[30:33]
	ds_read_b128 v[230:233], v246 offset:0x1000
	s_waitcnt lgkmcnt(3)
	v_mfma_f32_16x16x32_bf16 v[122:125], v[234:237], v[214:217], v[122:125]
	v_mfma_f32_16x16x32_bf16 v[90:93], v[234:237], v[218:221], v[90:93]
	v_mfma_f32_16x16x32_bf16 v[58:61], v[234:237], v[222:225], v[58:61]
	v_mfma_f32_16x16x32_bf16 v[26:29], v[234:237], v[226:229], v[26:29]
	ds_read_b128 v[234:237], v246 offset:0x1400
	s_waitcnt lgkmcnt(3)
	v_mfma_f32_16x16x32_bf16 v[118:121], v[238:241], v[214:217], v[118:121]
	v_mfma_f32_16x16x32_bf16 v[86:89], v[238:241], v[218:221], v[86:89]
	v_mfma_f32_16x16x32_bf16 v[54:57], v[238:241], v[222:225], v[54:57]
	v_mfma_f32_16x16x32_bf16 v[22:25], v[238:241], v[226:229], v[22:25]
	ds_read_b128 v[238:241], v246 offset:0x1800
	s_waitcnt lgkmcnt(3)
	v_mfma_f32_16x16x32_bf16 v[114:117], v[242:245], v[214:217], v[114:117]
	v_mfma_f32_16x16x32_bf16 v[82:85], v[242:245], v[218:221], v[82:85]
	v_mfma_f32_16x16x32_bf16 v[50:53], v[242:245], v[222:225], v[50:53]
	v_mfma_f32_16x16x32_bf16 v[18:21], v[242:245], v[226:229], v[18:21]
	ds_read_b128 v[242:245], v246 offset:0x1c00
	s_waitcnt lgkmcnt(3)
	v_mfma_f32_16x16x32_bf16 v[110:113], v[230:233], v[214:217], v[110:113]
	v_mfma_f32_16x16x32_bf16 v[78:81], v[230:233], v[218:221], v[78:81]
	v_mfma_f32_16x16x32_bf16 v[46:49], v[230:233], v[222:225], v[46:49]
	v_mfma_f32_16x16x32_bf16 v[14:17], v[230:233], v[226:229], v[14:17]
	s_waitcnt lgkmcnt(2)
	v_mfma_f32_16x16x32_bf16 v[106:109], v[234:237], v[214:217], v[106:109]
	v_mfma_f32_16x16x32_bf16 v[74:77], v[234:237], v[218:221], v[74:77]
	v_mfma_f32_16x16x32_bf16 v[42:45], v[234:237], v[222:225], v[42:45]
	v_mfma_f32_16x16x32_bf16 v[10:13], v[234:237], v[226:229], v[10:13]
	s_waitcnt lgkmcnt(1)
	v_mfma_f32_16x16x32_bf16 v[102:105], v[238:241], v[214:217], v[102:105]
	v_mfma_f32_16x16x32_bf16 v[70:73], v[238:241], v[218:221], v[70:73]
	v_mfma_f32_16x16x32_bf16 v[38:41], v[238:241], v[222:225], v[38:41]
	v_mfma_f32_16x16x32_bf16 v[6:9], v[238:241], v[226:229], v[6:9]
	s_waitcnt lgkmcnt(0)
	v_mfma_f32_16x16x32_bf16 v[98:101], v[242:245], v[214:217], v[98:101]
	v_mfma_f32_16x16x32_bf16 v[66:69], v[242:245], v[218:221], v[66:69]
	v_mfma_f32_16x16x32_bf16 v[34:37], v[242:245], v[222:225], v[34:37]
	v_mfma_f32_16x16x32_bf16 v[2:5], v[242:245], v[226:229], v[2:5]
	s_add_i32 s40, s40, 1
	s_cmp_lg_u32 s40, 3
	s_cselect_b32 s40, s40, 0
	s_add_i32 s41, s41, 1
	s_cmp_lg_u32 s41, 3
	s_cselect_b32 s41, s41, 0
	s_setprio 0
	s_add_i32 s20, s20, 1
	s_cmp_lg_u32 s20, 88
	s_cbranch_scc1 .LBB0_2744
	s_branch .LBB0_2750

; template <int EPI, int NB>
; DEVI void gemm_tile(const GemmJob& J, int m0, int n0, unsigned char* smem) {
;     ...
;   asm volatile("s_waitcnt vmcnt(0)" ::: "memory");
;   RAW_BARRIER();
; #pragma unroll
;   for (int st = 0; st < S - 1; ++st) GEMM_ISSUE(st, st);
;   const int fsl = (g ^ ((0 - (l16 >> 2)) & 3)) << 4;
;   const int aofs = (wm * 64 + l16) * 64 + fsl;
;   const int bofs = A_BYTES + (wn * NB * 16 + l16) * 64 + fsl;
;   int cs = 0, is = S - 1;
; #pragma clang loop unroll(disable)
;   for (int kt = 0; kt < nk; ++kt) {
;     if (nk - 1 - kt >= S - 2) {
;       if constexpr (NB == 8) asm volatile("s_waitcnt vmcnt(6)" ::: "memory");
;       else                   asm volatile("s_waitcnt vmcnt(8)" ::: "memory");
;     } else {
;       asm volatile("s_waitcnt vmcnt(0)" ::: "memory");
;     }
;     RAW_BARRIER();
;     if (kt + S - 1 < nk) GEMM_ISSUE(kt + S - 1, is);
;     is = (is + 1 == S) ? 0 : is + 1;
;     const unsigned cur = lbase + cs * STG;
;     cs = (cs + 1 == S) ? 0 : cs + 1;
;     bf16x8 af[4], bfr[NB];
;     const unsigned aa = cur + aofs, ba = cur + bofs;
;     af[0] = ldsr<0>(aa); af[1] = ldsr<1024>(aa); af[2] = ldsr<2048>(aa); af[3] = ldsr<3072>(aa);
;     bfr[0] = ldsr<0>(ba); bfr[1] = ldsr<1024>(ba); bfr[2] = ldsr<2048>(ba); bfr[3] = ldsr<3072>(ba);
;     __builtin_amdgcn_s_setprio(1);
; #pragma unroll
;     for (int nb = 0; nb < NB; ++nb) {
;       if (nb == 0) asm volatile("s_waitcnt lgkmcnt(3)" : "+v"(af[0]), "+v"(af[1]), "+v"(af[2]), "+v"(af[3]), "+v"(bfr[0]) :: "memory");
;       else if (nb <= NB - 4) asm volatile("s_waitcnt lgkmcnt(3)" : "+v"(bfr[nb]) :: "memory");
;       else if (nb == NB - 3) asm volatile("s_waitcnt lgkmcnt(2)" : "+v"(bfr[nb]) :: "memory");
;       else if (nb == NB - 2) asm volatile("s_waitcnt lgkmcnt(1)" : "+v"(bfr[nb]) :: "memory");
;       else asm volatile("s_waitcnt lgkmcnt(0)" : "+v"(bfr[nb]) :: "memory");
;       __builtin_amdgcn_sched_barrier(0);
; #pragma unroll
;       for (int mb = 0; mb < 4; ++mb) {
;         if constexpr (SWAP) acc[mb][nb] = __builtin_amdgcn_mfma_f32_16x16x32_bf16(bfr[nb], af[mb], acc[mb][nb], 0, 0, 0);
;         else                acc[mb][nb] = __builtin_amdgcn_mfma_f32_16x16x32_bf16(af[mb], bfr[nb], acc[mb][nb], 0, 0, 0);
;       }
;       if constexpr (NB == 8) {
;         __builtin_amdgcn_sched_barrier(0);
;         if (nb == 0) bfr[4] = ldsr<4096>(ba);
.LBB0_2821:
	s_mul_i32 s1, s41, 0x6000
	v_add_u32_e32 v213, s1, v211
	v_add_u32_e32 v246, s1, v212
	s_mul_i32 m0, s40, 0x6000
	s_add_u32 m0, m0, s0
	s_cmp_gt_u32 s2, 86
	s_cbranch_scc1 .Lgk25_w0
	s_waitcnt vmcnt(6)
.Lgk25_bar:
	s_waitcnt lgkmcnt(0)
	s_barrier
	s_setprio 1
	ds_read_b128 v[214:217], v213 offset:0
	ds_read_b128 v[230:233], v246 offset:0
	ds_read_b128 v[218:221], v213 offset:0x400
	ds_read_b128 v[222:225], v213 offset:0x800
	ds_read_b128 v[226:229], v213 offset:0xc00
	ds_read_b128 v[234:237], v246 offset:0x400
	ds_read_b128 v[238:241], v246 offset:0x800
	ds_read_b128 v[242:245], v246 offset:0xc00
	s_cmp_gt_u32 s2, 85
	s_cbranch_scc1 .Lgk25_tail
	s_waitcnt lgkmcnt(6)
	v_mfma_f32_16x16x32_bf16 v[126:129], v[230:233], v[214:217], v[126:129]
	s_waitcnt lgkmcnt(5)
	v_mfma_f32_16x16x32_bf16 v[94:97], v[230:233], v[218:221], v[94:97]
	s_waitcnt lgkmcnt(4)
	v_mfma_f32_16x16x32_bf16 v[62:65], v[230:233], v[222:225], v[62:65]
	s_waitcnt lgkmcnt(3)
	v_mfma_f32_16x16x32_bf16 v[30:33], v[230:233], v[226:229], v[30:33]
	ds_read_b128 v[230:233], v246 offset:0x1000
	global_load_lds_dwordx4 v184, s[100:101]
	s_add_u32 m0, m0, 0x1000
	s_waitcnt lgkmcnt(3)
	v_mfma_f32_16x16x32_bf16 v[122:125], v[234:237], v[214:217], v[122:125]
	v_mfma_f32_16x16x32_bf16 v[90:93], v[234:237], v[218:221], v[90:93]
	v_mfma_f32_16x16x32_bf16 v[58:61], v[234:237], v[222:225], v[58:61]
	v_mfma_f32_16x16x32_bf16 v[26:29], v[234:237], v[226:229], v[26:29]
	ds_read_b128 v[234:237], v246 offset:0x1400
	global_load_lds_dwordx4 v185, s[100:101]
	s_add_u32 m0, m0, 0x1000
	s_waitcnt lgkmcnt(3)
	v_mfma_f32_16x16x32_bf16 v[118:121], v[238:241], v[214:217], v[118:121]
	v_mfma_f32_16x16x32_bf16 v[86:89], v[238:241], v[218:221], v[86:89]
	v_mfma_f32_16x16x32_bf16 v[54:57], v[238:241], v[222:225], v[54:57]
	v_mfma_f32_16x16x32_bf16 v[22:25], v[238:241], v[226:229], v[22:25]
	ds_read_b128 v[238:241], v246 offset:0x1800
	global_load_lds_dwordx4 v182, vcc
	s_add_u32 m0, m0, 0x1000
	s_waitcnt lgkmcnt(3)
	v_mfma_f32_16x16x32_bf16 v[114:117], v[242:245], v[214:217], v[114:117]
	v_mfma_f32_16x16x32_bf16 v[82:85], v[242:245], v[218:221], v[82:85]
	v_mfma_f32_16x16x32_bf16 v[50:53], v[242:245], v[222:225], v[50:53]
	v_mfma_f32_16x16x32_bf16 v[18:21], v[242:245], v[226:229], v[18:21]
	ds_read_b128 v[242:245], v246 offset:0x1c00
	global_load_lds_dwordx4 v183, vcc
	s_add_u32 m0, m0, 0x1000
	s_waitcnt lgkmcnt(3)
	v_mfma_f32_16x16x32_bf16 v[110:113], v[230:233], v[214:217], v[110:113]
	v_mfma_f32_16x16x32_bf16 v[78:81], v[230:233], v[218:221], v[78:81]
	v_mfma_f32_16x16x32_bf16 v[46:49], v[230:233], v[222:225], v[46:49]
	v_mfma_f32_16x16x32_bf16 v[14:17], v[230:233], v[226:229], v[14:17]
	global_load_lds_dwordx4 v253, vcc
	s_add_u32 m0, m0, 0x1000
	s_waitcnt lgkmcnt(2)
	v_mfma_f32_16x16x32_bf16 v[106:109], v[234:237], v[214:217], v[106:109]
	v_mfma_f32_16x16x32_bf16 v[74:77], v[234:237], v[218:221], v[74:77]
	v_mfma_f32_16x16x32_bf16 v[42:45], v[234:237], v[222:225], v[42:45]
	v_mfma_f32_16x16x32_bf16 v[10:13], v[234:237], v[226:229], v[10:13]
	global_load_lds_dwordx4 v254, vcc
	s_waitcnt lgkmcnt(1)
	v_mfma_f32_16x16x32_bf16 v[102:105], v[238:241], v[214:217], v[102:105]
	v_mfma_f32_16x16x32_bf16 v[70:73], v[238:241], v[218:221], v[70:73]
	v_mfma_f32_16x16x32_bf16 v[38:41], v[238:241], v[222:225], v[38:41]
	v_mfma_f32_16x16x32_bf16 v[6:9], v[238:241], v[226:229], v[6:9]
	s_waitcnt lgkmcnt(0)
	v_mfma_f32_16x16x32_bf16 v[98:101], v[242:245], v[214:217], v[98:101]
	v_mfma_f32_16x16x32_bf16 v[66:69], v[242:245], v[218:221], v[66:69]
	v_mfma_f32_16x16x32_bf16 v[34:37], v[242:245], v[222:225], v[34:37]
	v_mfma_f32_16x16x32_bf16 v[2:5], v[242:245], v[226:229], v[2:5]
	s_add_u32 s100, s100, s94
	s_addc_u32 s101, s101, s95
	s_add_u32 vcc_lo, vcc_lo, s22
	s_addc_u32 vcc_hi, vcc_hi, s23
	s_add_i32 s40, s40, 1
	s_cmp_lg_u32 s40, 3
	s_cselect_b32 s40, s40, 0
	s_add_i32 s41, s41, 1
	s_cmp_lg_u32 s41, 3
	s_cselect_b32 s41, s41, 0
	s_setprio 0
	s_add_i32 s2, s2, 1
	s_branch .LBB0_2821
.Lgk25_tail:
	s_waitcnt lgkmcnt(6)
	v_mfma_f32_16x16x32_bf16 v[126:129], v[230:233], v[214:217], v[126:129]
	s_waitcnt lgkmcnt(5)
	v_mfma_f32_16x16x32_bf16 v[94:97], v[230:233], v[218:221], v[94:97]
	s_waitcnt lgkmcnt(4)
	v_mfma_f32_16x16x32_bf16 v[62:65], v[230:233], v[222:225], v[62:65]
	s_waitcnt lgkmcnt(3)
	v_mfma_f32_16x16x32_bf16 v[30:33], v[230:233], v[226:229], v[30:33]
	ds_read_b128 v[230:233], v246 offset:0x1000
	s_waitcnt lgkmcnt(3)
	v_mfma_f32_16x16x32_bf16 v[122:125], v[234:237], v[214:217], v[122:125]
	v_mfma_f32_16x16x32_bf16 v[90:93], v[234:237], v[218:221], v[90:93]
	v_mfma_f32_16x16x32_bf16 v[58:61], v[234:237], v[222:225], v[58:61]
	v_mfma_f32_16x16x32_bf16 v[26:29], v[234:237], v[226:229], v[26:29]
	ds_read_b128 v[234:237], v246 offset:0x1400
	s_waitcnt lgkmcnt(3)
	v_mfma_f32_16x16x32_bf16 v[118:121], v[238:241], v[214:217], v[118:121]
	v_mfma_f32_16x16x32_bf16 v[86:89], v[238:241], v[218:221], v[86:89]
	v_mfma_f32_16x16x32_bf16 v[54:57], v[238:241], v[222:225], v[54:57]
	v_mfma_f32_16x16x32_bf16 v[22:25], v[238:241], v[226:229], v[22:25]
	ds_read_b128 v[238:241], v246 offset:0x1800
	s_waitcnt lgkmcnt(3)
	v_mfma_f32_16x16x32_bf16 v[114:117], v[242:245], v[214:217], v[114:117]
	v_mfma_f32_16x16x32_bf16 v[82:85], v[242:245], v[218:221], v[82:85]
	v_mfma_f32_16x16x32_bf16 v[50:53], v[242:245], v[222:225], v[50:53]
	v_mfma_f32_16x16x32_bf16 v[18:21], v[242:245], v[226:229], v[18:21]
	ds_read_b128 v[242:245], v246 offset:0x1c00
	s_waitcnt lgkmcnt(3)
	v_mfma_f32_16x16x32_bf16 v[110:113], v[230:233], v[214:217], v[110:113]
	v_mfma_f32_16x16x32_bf16 v[78:81], v[230:233], v[218:221], v[78:81]
	v_mfma_f32_16x16x32_bf16 v[46:49], v[230:233], v[222:225], v[46:49]
	v_mfma_f32_16x16x32_bf16 v[14:17], v[230:233], v[226:229], v[14:17]
	s_waitcnt lgkmcnt(2)
	v_mfma_f32_16x16x32_bf16 v[106:109], v[234:237], v[214:217], v[106:109]
	v_mfma_f32_16x16x32_bf16 v[74:77], v[234:237], v[218:221], v[74:77]
	v_mfma_f32_16x16x32_bf16 v[42:45], v[234:237], v[222:225], v[42:45]
	v_mfma_f32_16x16x32_bf16 v[10:13], v[234:237], v[226:229], v[10:13]
	s_waitcnt lgkmcnt(1)
	v_mfma_f32_16x16x32_bf16 v[102:105], v[238:241], v[214:217], v[102:105]
	v_mfma_f32_16x16x32_bf16 v[70:73], v[238:241], v[218:221], v[70:73]
	v_mfma_f32_16x16x32_bf16 v[38:41], v[238:241], v[222:225], v[38:41]
	v_mfma_f32_16x16x32_bf16 v[6:9], v[238:241], v[226:229], v[6:9]
	s_waitcnt lgkmcnt(0)
	v_mfma_f32_16x16x32_bf16 v[98:101], v[242:245], v[214:217], v[98:101]
	v_mfma_f32_16x16x32_bf16 v[66:69], v[242:245], v[218:221], v[66:69]
	v_mfma_f32_16x16x32_bf16 v[34:37], v[242:245], v[222:225], v[34:37]
	v_mfma_f32_16x16x32_bf16 v[2:5], v[242:245], v[226:229], v[2:5]
	s_add_i32 s40, s40, 1
	s_cmp_lg_u32 s40, 3
	s_cselect_b32 s40, s40, 0
	s_add_i32 s41, s41, 1
	s_cmp_lg_u32 s41, 3
	s_cselect_b32 s41, s41, 0
	s_setprio 0
	s_add_i32 s2, s2, 1
	s_cmp_lg_u32 s2, 88
	s_cbranch_scc1 .LBB0_2821
	s_branch .LBB0_2827
